# v55 plus NA bias via fma on a pre-scaled table, and NA P.V pass V-image addresses derived by one v_xor from the per-step base (was v_or+v_bitop3+v_lshl_add)
# speedup vs baseline: 1.0124x; 1.0039x over previous
; #define LAS __attribute__((address_space(3)))
; __device__ __forceinline__ unsigned pk2(float lo, float hi) { return f2bf(lo) | (f2bf(hi) << 16); }
; template <int L>
; __device__ __forceinline__ void layer_body(const Args& args, LAS unsigned char* lds, const int wave, const int G, const int gw, const int NGW, const int lo, const int hi,
;                                            unsigned char* const ws_kernel, const XcdBarrier& bar, int& pid) {
;     ...
;                     for (int s = 0; s < 8; ++s) { const f32x4 p0 = sc[2 * s], p1 = sc[2 * s + 1]; v4u w; w.x = pk2(p0[0], p0[1]); w.y = pk2(p0[2], p0[3]); w.z = pk2(p1[0], p1[1]); w.w = pk2(p1[2], p1[3]); pbf[s] = __builtin_bit_cast(bf16x8, w); }
;                     __syncthreads();
; #pragma unroll
;                     for (int i = 0; i < 14; ++i) { const int kid = skey + 32 * i; *(LAS v4u*)(size_t)(IMG + vimg_off(kid, sch)) = rst[i]; }
;                     __syncthreads();
;                     if (unit + GH < UEND) { NA_LOADROWS(unit + GH, rst, D); NA_LOADQ(unit + GH); }
;                     f32x4 acc[8];
; #pragma unroll
;                     for (int mt = 0; mt < 8; ++mt) acc[mt] = (f32x4){0.f, 0.f, 0.f, 0.f};
;                     const int trq = (lane & 15) >> 2, trp = lane & 3;
; #pragma unroll
;                     for (int s = 0; s < 8; ++s) {
;                         const int ir0 = (r0w - krlo + s) * 40 + coloff;
; #pragma unroll
;                         for (int mh = 0; mh < 2; ++mh) {
;                             s16x4 lo[4], hi[4];
; #pragma unroll
;                             for (int m4 = 0; m4 < 4; ++m4) { const int mt = mh * 4 + m4, r0_ = ir0 + 4 * kg + trq, r1_ = ir0 + 16 + 4 * kg + trq, ch_ = 2 * mt + (trp >> 1);
;                                 lo[m4] = tr_read_b64(IMG + vimg_off(r0_, ch_) + 8u * (trp & 1)); hi[m4] = tr_read_b64(IMG + vimg_off(r1_, ch_) + 8u * (trp & 1)); }
;                             asm volatile("s_waitcnt lgkmcnt(0)" ::: "memory"); __builtin_amdgcn_sched_barrier(0);
; #pragma unroll
;                             for (int m4 = 0; m4 < 4; ++m4) { const int mt = mh * 4 + m4; const bf16x8 va = (bf16x8){lo[m4][0], lo[m4][1], lo[m4][2], lo[m4][3], hi[m4][0], hi[m4][1], hi[m4][2], hi[m4][3]};
;                                 acc[mt] = __builtin_amdgcn_mfma_f32_16x16x32_bf16(va, pbf[s], acc[mt], 0, 0, 0); }
.LBB0_843:
	v_cvt_pk_bf16_f32 v101, v196, v202
	v_cvt_pk_bf16_f32 v100, v192, v200
	v_cvt_pk_bf16_f32 v103, v201, v204
	v_cvt_pk_bf16_f32 v102, v198, v203
	v_cvt_pk_bf16_f32 v97, v186, v195
	v_cvt_pk_bf16_f32 v96, v182, v193
	v_cvt_pk_bf16_f32 v99, v194, v199
	v_cvt_pk_bf16_f32 v98, v189, v197
	v_cvt_pk_bf16_f32 v93, v180, v185
	v_cvt_pk_bf16_f32 v92, v179, v183
	v_cvt_pk_bf16_f32 v95, v184, v190
	v_cvt_pk_bf16_f32 v94, v181, v187
	v_cvt_pk_bf16_f32 v89, v142, v148
	v_cvt_pk_bf16_f32 v88, v138, v146
	v_cvt_pk_bf16_f32 v91, v147, v152
	v_cvt_pk_bf16_f32 v90, v144, v150
	v_cvt_pk_bf16_f32 v85, v134, v141
	v_cvt_pk_bf16_f32 v84, v130, v139
	v_cvt_pk_bf16_f32 v87, v140, v145
	v_cvt_pk_bf16_f32 v86, v136, v143
	v_cvt_pk_bf16_f32 v81, v126, v133
	v_cvt_pk_bf16_f32 v80, v122, v131
	v_bfe_u32 v78, v125, 16, 1
	v_add3_u32 v113, v125, v78, s23
	v_bfe_u32 v79, v118, 16, 1
	v_cvt_pk_bf16_f32 v83, v132, v137
	v_add3_u32 v79, v118, v79, s23
	v_cvt_pk_bf16_f32 v82, v128, v135
	v_lshrrev_b32_e32 v118, 16, v79
	v_cvt_pk_bf16_f32 v79, v124, v129
	v_cvt_pk_bf16_f32 v76, v75, v123
	v_cvt_pk_bf16_f32 v78, v120, v127
	v_and_or_b32 v77, v113, s89, v118
	v_bfe_u32 v114, v115, 16, 1
	v_add3_u32 v114, v115, v114, s23
	v_bfe_u32 v115, v72, 16, 1
	v_add3_u32 v72, v72, v115, s23
	v_lshrrev_b32_e32 v112, 2, v112
	v_lshrrev_b32_e32 v72, 16, v72
	v_cvt_pk_bf16_f32 v75, v116, v121
	v_or_b32_e32 v115, v110, v112
	s_add_i32 s6, s6, s15
	v_cvt_pk_bf16_f32 v73, v73, v117
	v_and_or_b32 v72, v114, s89, v72
	v_or_b32_e32 v113, 16, v115
	v_bfe_u32 v112, v111, 1, 1
	v_lshlrev_b32_e32 v111, 3, v111
	v_add_u32_e32 v114, s6, v115
	v_and_or_b32 v111, v111, 8, 0
	v_add_u32_e32 v116, s6, v113
	v_lshlrev_b32_e32 v117, 2, v114
	v_and_b32_e32 v152, 12, v117
	v_bfe_u32 v153, v114, 2, 2
	v_lshl_add_u32 v154, v114, 8, v111
	v_lshlrev_b32_e32 v114, 2, v116
	v_and_b32_e32 v155, 12, v114
	v_bitop3_b32 v114, v152, v112, v153 bitop3:0x36
	v_bfe_u32 v156, v116, 2, 2
	v_lshl_add_u32 v253, v114, 4, v154
	v_lshl_add_u32 v157, v116, 8, v111
	ds_read_b64_tr_b16 v[120:121], v253
	v_bitop3_b32 v114, v155, v112, v156 bitop3:0x36
	v_lshl_add_u32 v252, v114, 4, v157
	ds_read_b64_tr_b16 v[122:123], v252
	v_xor_b32_e32 v116, 0x20, v253
	ds_read_b64_tr_b16 v[124:125], v116
	v_xor_b32_e32 v116, 0x20, v252
	ds_read_b64_tr_b16 v[126:127], v116
	v_or_b32_e32 v116, 4, v112
	v_xor_b32_e32 v117, 0x40, v253
	ds_read_b64_tr_b16 v[128:129], v117
	v_xor_b32_e32 v117, 0x40, v252
	ds_read_b64_tr_b16 v[130:131], v117
	v_xor_b32_e32 v118, 0x60, v253
	ds_read_b64_tr_b16 v[132:133], v118
	v_xor_b32_e32 v118, 0x60, v252
	ds_read_b64_tr_b16 v[134:135], v118
	s_waitcnt lgkmcnt(0)
	v_cvt_pk_bf16_f32 v74, v74, v119
	v_add_f32_e32 v104, v149, v151
	v_xor_b32_e32 v119, 0x80, v253
	v_mfma_f32_16x16x32_bf16 v[136:139], v[120:123], v[100:103], 0
	ds_read_b64_tr_b16 v[122:123], v119
	v_xor_b32_e32 v119, 0x80, v252
	v_mfma_f32_16x16x32_bf16 v[140:143], v[124:127], v[100:103], 0
	ds_read_b64_tr_b16 v[124:125], v119
	v_xor_b32_e32 v120, 0xa0, v253
	v_mfma_f32_16x16x32_bf16 v[126:129], v[128:131], v[100:103], 0
	ds_read_b64_tr_b16 v[130:131], v120
	v_xor_b32_e32 v120, 0xa0, v252
	v_mfma_f32_16x16x32_bf16 v[144:147], v[132:135], v[100:103], 0
	ds_read_b64_tr_b16 v[132:133], v120
	v_xor_b32_e32 v121, 0xc0, v253
	ds_read_b64_tr_b16 v[148:149], v121
	v_xor_b32_e32 v121, 0xc0, v252
	ds_read_b64_tr_b16 v[150:151], v121
	v_or_b32_e32 v121, 14, v112
	v_xor_b32_e32 v134, 0xe0, v253
	ds_read_b64_tr_b16 v[152:153], v134
	v_xor_b32_e32 v134, 0xe0, v252
	ds_read_b64_tr_b16 v[154:155], v134
	s_waitcnt lgkmcnt(0)
	s_add_i32 s7, s7, s15
	v_add_u32_e32 v134, s7, v115
	v_add_u32_e32 v135, s7, v113
	v_lshlrev_b32_e32 v156, 2, v134
	v_and_b32_e32 v168, 12, v156
	v_bfe_u32 v169, v134, 2, 2
	v_lshl_add_u32 v170, v134, 8, v111
	v_lshlrev_b32_e32 v134, 2, v135
	v_and_b32_e32 v171, 12, v134
	v_bitop3_b32 v134, v168, v112, v169 bitop3:0x36
	v_bfe_u32 v172, v135, 2, 2
	v_lshl_add_u32 v253, v134, 4, v170
	v_mfma_f32_16x16x32_bf16 v[122:125], v[122:125], v[100:103], 0
	v_lshl_add_u32 v173, v135, 8, v111
	v_mfma_f32_16x16x32_bf16 v[130:133], v[130:133], v[100:103], 0
	v_mfma_f32_16x16x32_bf16 v[148:151], v[148:151], v[100:103], 0
	v_mfma_f32_16x16x32_bf16 v[100:103], v[152:155], v[100:103], 0
	ds_read_b64_tr_b16 v[152:153], v253
	v_bitop3_b32 v134, v171, v112, v172 bitop3:0x36
	v_lshl_add_u32 v252, v134, 4, v173
	ds_read_b64_tr_b16 v[154:155], v252
	v_xor_b32_e32 v134, 0x20, v253
	ds_read_b64_tr_b16 v[156:157], v134
	v_xor_b32_e32 v134, 0x20, v252
	ds_read_b64_tr_b16 v[158:159], v134
	v_xor_b32_e32 v134, 0x40, v253
	ds_read_b64_tr_b16 v[160:161], v134
	v_xor_b32_e32 v134, 0x40, v252
	ds_read_b64_tr_b16 v[162:163], v134
	v_xor_b32_e32 v134, 0x60, v253
	ds_read_b64_tr_b16 v[164:165], v134
	v_xor_b32_e32 v134, 0x60, v252
	ds_read_b64_tr_b16 v[166:167], v134
	s_waitcnt lgkmcnt(0)
	v_mfma_f32_16x16x32_bf16 v[134:137], v[152:155], v[96:99], v[136:139]
	v_mfma_f32_16x16x32_bf16 v[138:141], v[156:159], v[96:99], v[140:143]
	v_mfma_f32_16x16x32_bf16 v[142:145], v[164:167], v[96:99], v[144:147]
	s_nop 2
	v_xor_b32_e32 v146, 0x80, v253
	ds_read_b64_tr_b16 v[152:153], v146
	v_xor_b32_e32 v146, 0x80, v252
	ds_read_b64_tr_b16 v[154:155], v146
	v_xor_b32_e32 v146, 0xa0, v253
	ds_read_b64_tr_b16 v[156:157], v146
	v_xor_b32_e32 v146, 0xa0, v252
	ds_read_b64_tr_b16 v[158:159], v146
	v_xor_b32_e32 v146, 0xc0, v253
	v_mfma_f32_16x16x32_bf16 v[126:129], v[160:163], v[96:99], v[126:129]
	ds_read_b64_tr_b16 v[160:161], v146
	v_xor_b32_e32 v146, 0xc0, v252
	ds_read_b64_tr_b16 v[162:163], v146
	v_xor_b32_e32 v146, 0xe0, v253
	ds_read_b64_tr_b16 v[164:165], v146
	v_xor_b32_e32 v146, 0xe0, v252
	ds_read_b64_tr_b16 v[166:167], v146
	s_waitcnt lgkmcnt(0)
; __device__ __forceinline__ s16x4 tr_read_b64(unsigned addr) { s16x4 r; asm volatile("ds_read_b64_tr_b16 %0, %1" : "=v"(r) : "v"(addr) : "memory"); return r; }
; template <int L>
; __device__ __forceinline__ void layer_body(const Args& args, LAS unsigned char* lds, const int wave, const int G, const int gw, const int NGW, const int lo, const int hi,
;                                            unsigned char* const ws_kernel, const XcdBarrier& bar, int& pid) {
;     ...
;                     for (int s = 0; s < 8; ++s) {
;                         const int ir0 = (r0w - krlo + s) * 40 + coloff;
; #pragma unroll
;                         for (int mh = 0; mh < 2; ++mh) {
;                             s16x4 lo[4], hi[4];
; #pragma unroll
;                             for (int m4 = 0; m4 < 4; ++m4) { const int mt = mh * 4 + m4, r0_ = ir0 + 4 * kg + trq, r1_ = ir0 + 16 + 4 * kg + trq, ch_ = 2 * mt + (trp >> 1);
;                                 lo[m4] = tr_read_b64(IMG + vimg_off(r0_, ch_) + 8u * (trp & 1)); hi[m4] = tr_read_b64(IMG + vimg_off(r1_, ch_) + 8u * (trp & 1)); }
;                             asm volatile("s_waitcnt lgkmcnt(0)" ::: "memory"); __builtin_amdgcn_sched_barrier(0);
; #pragma unroll
;                             for (int m4 = 0; m4 < 4; ++m4) { const int mt = mh * 4 + m4; const bf16x8 va = (bf16x8){lo[m4][0], lo[m4][1], lo[m4][2], lo[m4][3], hi[m4][0], hi[m4][1], hi[m4][2], hi[m4][3]};
;                                 acc[mt] = __builtin_amdgcn_mfma_f32_16x16x32_bf16(va, pbf[s], acc[mt], 0, 0, 0); }
;                         }
	s_add_i32 s8, s8, s15
	v_mfma_f32_16x16x32_bf16 v[122:125], v[152:155], v[96:99], v[122:125]
	v_mfma_f32_16x16x32_bf16 v[130:133], v[156:159], v[96:99], v[130:133]
	v_mfma_f32_16x16x32_bf16 v[146:149], v[160:163], v[96:99], v[148:151]
	v_mfma_f32_16x16x32_bf16 v[96:99], v[164:167], v[96:99], v[100:103]
	s_nop 2
	v_add_u32_e32 v100, s8, v115
	v_add_u32_e32 v101, s8, v113
	v_lshlrev_b32_e32 v102, 2, v100
	v_and_b32_e32 v162, 12, v102
	v_bfe_u32 v163, v100, 2, 2
	v_lshl_add_u32 v164, v100, 8, v111
	v_lshlrev_b32_e32 v100, 2, v101
	v_and_b32_e32 v165, 12, v100
	v_bfe_u32 v166, v101, 2, 2
	v_bitop3_b32 v100, v162, v112, v163 bitop3:0x36
	v_lshl_add_u32 v167, v101, 8, v111
	v_lshl_add_u32 v253, v100, 4, v164
	v_bitop3_b32 v102, v165, v112, v166 bitop3:0x36
	ds_read_b64_tr_b16 v[100:101], v253
	v_lshl_add_u32 v252, v102, 4, v167
	ds_read_b64_tr_b16 v[102:103], v252
	v_xor_b32_e32 v150, 0x20, v253
	ds_read_b64_tr_b16 v[150:151], v150
	v_xor_b32_e32 v152, 0x20, v252
	ds_read_b64_tr_b16 v[152:153], v152
	v_xor_b32_e32 v154, 0x40, v253
	ds_read_b64_tr_b16 v[154:155], v154
	v_xor_b32_e32 v156, 0x40, v252
	ds_read_b64_tr_b16 v[156:157], v156
	v_xor_b32_e32 v158, 0x60, v253
	ds_read_b64_tr_b16 v[158:159], v158
	v_xor_b32_e32 v160, 0x60, v252
	ds_read_b64_tr_b16 v[160:161], v160
	s_waitcnt lgkmcnt(0)
	v_mfma_f32_16x16x32_bf16 v[100:103], v[100:103], v[92:95], v[134:137]
	v_mfma_f32_16x16x32_bf16 v[134:137], v[150:153], v[92:95], v[138:141]
	v_xor_b32_e32 v150, 0xa0, v253
	v_mfma_f32_16x16x32_bf16 v[138:141], v[158:161], v[92:95], v[142:145]
	v_xor_b32_e32 v152, 0xa0, v252
	v_xor_b32_e32 v158, 0xe0, v253
	v_xor_b32_e32 v142, 0x80, v253
	ds_read_b64_tr_b16 v[142:143], v142
	v_xor_b32_e32 v144, 0x80, v252
	ds_read_b64_tr_b16 v[144:145], v144
	v_mfma_f32_16x16x32_bf16 v[126:129], v[154:157], v[92:95], v[126:129]
	ds_read_b64_tr_b16 v[150:151], v150
	ds_read_b64_tr_b16 v[152:153], v152
	v_xor_b32_e32 v154, 0xc0, v253
	ds_read_b64_tr_b16 v[154:155], v154
	v_xor_b32_e32 v156, 0xc0, v252
	ds_read_b64_tr_b16 v[156:157], v156
	ds_read_b64_tr_b16 v[158:159], v158
	v_xor_b32_e32 v160, 0xe0, v252
	ds_read_b64_tr_b16 v[160:161], v160
	s_waitcnt lgkmcnt(0)
	s_add_i32 s37, s37, s15
	v_mfma_f32_16x16x32_bf16 v[122:125], v[142:145], v[92:95], v[122:125]
	v_mfma_f32_16x16x32_bf16 v[130:133], v[150:153], v[92:95], v[130:133]
	v_mfma_f32_16x16x32_bf16 v[142:145], v[154:157], v[92:95], v[146:149]
	v_mfma_f32_16x16x32_bf16 v[92:95], v[158:161], v[92:95], v[96:99]
	s_nop 2
	v_add_u32_e32 v96, s37, v115
	v_add_u32_e32 v97, s37, v113
	v_lshlrev_b32_e32 v98, 2, v96
	v_and_b32_e32 v158, 12, v98
	v_bfe_u32 v159, v96, 2, 2
	v_lshl_add_u32 v160, v96, 8, v111
	v_lshlrev_b32_e32 v96, 2, v97
	v_and_b32_e32 v161, 12, v96
	v_bfe_u32 v162, v97, 2, 2
	v_bitop3_b32 v96, v158, v112, v159 bitop3:0x36
	v_lshl_add_u32 v163, v97, 8, v111
	v_lshl_add_u32 v253, v96, 4, v160
	v_bitop3_b32 v98, v161, v112, v162 bitop3:0x36
	ds_read_b64_tr_b16 v[96:97], v253
	v_lshl_add_u32 v252, v98, 4, v163
	ds_read_b64_tr_b16 v[98:99], v252
	v_xor_b32_e32 v146, 0x20, v253
	ds_read_b64_tr_b16 v[146:147], v146
	v_xor_b32_e32 v148, 0x20, v252
	ds_read_b64_tr_b16 v[148:149], v148
	v_xor_b32_e32 v150, 0x40, v253
	ds_read_b64_tr_b16 v[150:151], v150
	v_xor_b32_e32 v152, 0x40, v252
	ds_read_b64_tr_b16 v[152:153], v152
	v_xor_b32_e32 v154, 0x60, v253
	ds_read_b64_tr_b16 v[154:155], v154
	v_xor_b32_e32 v156, 0x60, v252
	ds_read_b64_tr_b16 v[156:157], v156
	s_waitcnt lgkmcnt(0)
	v_mfma_f32_16x16x32_bf16 v[96:99], v[96:99], v[88:91], v[100:103]
	v_mfma_f32_16x16x32_bf16 v[100:103], v[146:149], v[88:91], v[134:137]
	v_xor_b32_e32 v146, 0xa0, v253
	v_mfma_f32_16x16x32_bf16 v[134:137], v[154:157], v[88:91], v[138:141]
	v_xor_b32_e32 v148, 0xa0, v252
	v_xor_b32_e32 v154, 0xe0, v253
	v_xor_b32_e32 v138, 0x80, v253
	ds_read_b64_tr_b16 v[138:139], v138
	v_xor_b32_e32 v140, 0x80, v252
	ds_read_b64_tr_b16 v[140:141], v140
	v_mfma_f32_16x16x32_bf16 v[126:129], v[150:153], v[88:91], v[126:129]
	ds_read_b64_tr_b16 v[146:147], v146
	ds_read_b64_tr_b16 v[148:149], v148
	v_xor_b32_e32 v150, 0xc0, v253
	ds_read_b64_tr_b16 v[150:151], v150
	v_xor_b32_e32 v152, 0xc0, v252
	ds_read_b64_tr_b16 v[152:153], v152
	ds_read_b64_tr_b16 v[154:155], v154
	v_xor_b32_e32 v156, 0xe0, v252
	ds_read_b64_tr_b16 v[156:157], v156
	s_waitcnt lgkmcnt(0)
	s_add_i32 s38, s38, s15
	v_mfma_f32_16x16x32_bf16 v[122:125], v[138:141], v[88:91], v[122:125]
	v_mfma_f32_16x16x32_bf16 v[130:133], v[146:149], v[88:91], v[130:133]
	v_mfma_f32_16x16x32_bf16 v[138:141], v[150:153], v[88:91], v[142:145]
	v_mfma_f32_16x16x32_bf16 v[88:91], v[154:157], v[88:91], v[92:95]
	s_nop 2
	v_add_u32_e32 v92, s38, v115
	v_add_u32_e32 v93, s38, v113
	v_lshlrev_b32_e32 v94, 2, v92
	v_and_b32_e32 v154, 12, v94
	v_bfe_u32 v155, v92, 2, 2
	v_lshl_add_u32 v156, v92, 8, v111
	v_lshlrev_b32_e32 v92, 2, v93
	v_and_b32_e32 v157, 12, v92
	v_bfe_u32 v158, v93, 2, 2
	v_bitop3_b32 v92, v154, v112, v155 bitop3:0x36
	v_lshl_add_u32 v159, v93, 8, v111
	v_lshl_add_u32 v253, v92, 4, v156
	v_bitop3_b32 v94, v157, v112, v158 bitop3:0x36
	ds_read_b64_tr_b16 v[92:93], v253
	v_lshl_add_u32 v252, v94, 4, v159
	ds_read_b64_tr_b16 v[94:95], v252
	v_xor_b32_e32 v142, 0x20, v253
	ds_read_b64_tr_b16 v[142:143], v142
	v_xor_b32_e32 v144, 0x20, v252
	ds_read_b64_tr_b16 v[144:145], v144
	v_xor_b32_e32 v146, 0x40, v253
	ds_read_b64_tr_b16 v[146:147], v146
	v_xor_b32_e32 v148, 0x40, v252
	ds_read_b64_tr_b16 v[148:149], v148
	v_xor_b32_e32 v150, 0x60, v253
	ds_read_b64_tr_b16 v[150:151], v150
	v_xor_b32_e32 v152, 0x60, v252
	ds_read_b64_tr_b16 v[152:153], v152
	s_waitcnt lgkmcnt(0)
; __device__ __forceinline__ s16x4 tr_read_b64(unsigned addr) { s16x4 r; asm volatile("ds_read_b64_tr_b16 %0, %1" : "=v"(r) : "v"(addr) : "memory"); return r; }
; template <int L>
; __device__ __forceinline__ void layer_body(const Args& args, LAS unsigned char* lds, const int wave, const int G, const int gw, const int NGW, const int lo, const int hi,
;                                            unsigned char* const ws_kernel, const XcdBarrier& bar, int& pid) {
;     ...
;                     for (int s = 0; s < 8; ++s) {
;                         const int ir0 = (r0w - krlo + s) * 40 + coloff;
; #pragma unroll
;                         for (int mh = 0; mh < 2; ++mh) {
;                             s16x4 lo[4], hi[4];
; #pragma unroll
;                             for (int m4 = 0; m4 < 4; ++m4) { const int mt = mh * 4 + m4, r0_ = ir0 + 4 * kg + trq, r1_ = ir0 + 16 + 4 * kg + trq, ch_ = 2 * mt + (trp >> 1);
;                                 lo[m4] = tr_read_b64(IMG + vimg_off(r0_, ch_) + 8u * (trp & 1)); hi[m4] = tr_read_b64(IMG + vimg_off(r1_, ch_) + 8u * (trp & 1)); }
;                             asm volatile("s_waitcnt lgkmcnt(0)" ::: "memory"); __builtin_amdgcn_sched_barrier(0);
; #pragma unroll
;                             for (int m4 = 0; m4 < 4; ++m4) { const int mt = mh * 4 + m4; const bf16x8 va = (bf16x8){lo[m4][0], lo[m4][1], lo[m4][2], lo[m4][3], hi[m4][0], hi[m4][1], hi[m4][2], hi[m4][3]};
;                                 acc[mt] = __builtin_amdgcn_mfma_f32_16x16x32_bf16(va, pbf[s], acc[mt], 0, 0, 0); }
;                         }
	v_mfma_f32_16x16x32_bf16 v[92:95], v[92:95], v[84:87], v[96:99]
	v_mfma_f32_16x16x32_bf16 v[96:99], v[142:145], v[84:87], v[100:103]
	v_xor_b32_e32 v142, 0xa0, v253
	v_mfma_f32_16x16x32_bf16 v[100:103], v[146:149], v[84:87], v[126:129]
	v_xor_b32_e32 v144, 0xa0, v252
	v_xor_b32_e32 v146, 0xc0, v253
	v_mfma_f32_16x16x32_bf16 v[126:129], v[150:153], v[84:87], v[134:137]
	v_xor_b32_e32 v148, 0xc0, v252
	v_xor_b32_e32 v134, 0x80, v253
	ds_read_b64_tr_b16 v[134:135], v134
	v_xor_b32_e32 v136, 0x80, v252
	ds_read_b64_tr_b16 v[136:137], v136
	ds_read_b64_tr_b16 v[142:143], v142
	ds_read_b64_tr_b16 v[144:145], v144
	ds_read_b64_tr_b16 v[146:147], v146
	ds_read_b64_tr_b16 v[148:149], v148
	v_xor_b32_e32 v150, 0xe0, v253
	ds_read_b64_tr_b16 v[150:151], v150
	v_xor_b32_e32 v152, 0xe0, v252
	ds_read_b64_tr_b16 v[152:153], v152
	s_waitcnt lgkmcnt(0)
	s_add_i32 s39, s39, s15
	v_mfma_f32_16x16x32_bf16 v[122:125], v[134:137], v[84:87], v[122:125]
	v_mfma_f32_16x16x32_bf16 v[130:133], v[142:145], v[84:87], v[130:133]
	v_mfma_f32_16x16x32_bf16 v[134:137], v[146:149], v[84:87], v[138:141]
	v_mfma_f32_16x16x32_bf16 v[84:87], v[150:153], v[84:87], v[88:91]
	s_nop 2
	v_add_u32_e32 v88, s39, v115
	v_add_u32_e32 v89, s39, v113
	v_lshlrev_b32_e32 v90, 2, v88
	v_and_b32_e32 v150, 12, v90
	v_bfe_u32 v151, v88, 2, 2
	v_lshl_add_u32 v152, v88, 8, v111
	v_lshlrev_b32_e32 v88, 2, v89
	v_and_b32_e32 v153, 12, v88
	v_bfe_u32 v154, v89, 2, 2
	v_bitop3_b32 v88, v150, v112, v151 bitop3:0x36
	v_lshl_add_u32 v155, v89, 8, v111
	v_lshl_add_u32 v253, v88, 4, v152
	v_bitop3_b32 v90, v153, v112, v154 bitop3:0x36
	ds_read_b64_tr_b16 v[88:89], v253
	v_lshl_add_u32 v252, v90, 4, v155
	ds_read_b64_tr_b16 v[90:91], v252
	v_xor_b32_e32 v138, 0x20, v253
	ds_read_b64_tr_b16 v[138:139], v138
	v_xor_b32_e32 v140, 0x20, v252
	ds_read_b64_tr_b16 v[140:141], v140
	v_xor_b32_e32 v142, 0x40, v253
	ds_read_b64_tr_b16 v[142:143], v142
	v_xor_b32_e32 v144, 0x40, v252
	ds_read_b64_tr_b16 v[144:145], v144
	v_xor_b32_e32 v146, 0x60, v253
	ds_read_b64_tr_b16 v[146:147], v146
	v_xor_b32_e32 v148, 0x60, v252
	ds_read_b64_tr_b16 v[148:149], v148
	s_waitcnt lgkmcnt(0)
	v_mfma_f32_16x16x32_bf16 v[88:91], v[88:91], v[80:83], v[92:95]
	v_xor_b32_e32 v156, 0x80, v253
	ds_read_b64_tr_b16 v[92:93], v156
	v_mfma_f32_16x16x32_bf16 v[96:99], v[138:141], v[80:83], v[96:99]
	s_nop 0
	v_xor_b32_e32 v94, 0x80, v252
	ds_read_b64_tr_b16 v[94:95], v94
	v_xor_b32_e32 v138, 0xa0, v253
	v_mfma_f32_16x16x32_bf16 v[100:103], v[142:145], v[80:83], v[100:103]
	ds_read_b64_tr_b16 v[138:139], v138
	v_xor_b32_e32 v140, 0xa0, v252
	ds_read_b64_tr_b16 v[140:141], v140
	v_xor_b32_e32 v142, 0xc0, v253
	v_mfma_f32_16x16x32_bf16 v[126:129], v[146:149], v[80:83], v[126:129]
	ds_read_b64_tr_b16 v[142:143], v142
	v_xor_b32_e32 v144, 0xc0, v252
	ds_read_b64_tr_b16 v[144:145], v144
	v_xor_b32_e32 v146, 0xe0, v253
	ds_read_b64_tr_b16 v[146:147], v146
	v_xor_b32_e32 v148, 0xe0, v252
	ds_read_b64_tr_b16 v[148:149], v148
	s_waitcnt lgkmcnt(0)
	s_add_i32 s40, s40, s15
	v_mfma_f32_16x16x32_bf16 v[92:95], v[92:95], v[80:83], v[122:125]
	v_mfma_f32_16x16x32_bf16 v[122:125], v[138:141], v[80:83], v[130:133]
	v_mfma_f32_16x16x32_bf16 v[130:133], v[142:145], v[80:83], v[134:137]
	v_mfma_f32_16x16x32_bf16 v[80:83], v[146:149], v[80:83], v[84:87]
	s_nop 2
	v_add_u32_e32 v84, s40, v115
	v_add_u32_e32 v85, s40, v113
	v_lshlrev_b32_e32 v86, 2, v84
	v_and_b32_e32 v146, 12, v86
	v_bfe_u32 v147, v84, 2, 2
	v_lshl_add_u32 v148, v84, 8, v111
	v_lshlrev_b32_e32 v84, 2, v85
	v_and_b32_e32 v149, 12, v84
	v_bfe_u32 v150, v85, 2, 2
	v_bitop3_b32 v84, v146, v112, v147 bitop3:0x36
	v_lshl_add_u32 v151, v85, 8, v111
	v_lshl_add_u32 v253, v84, 4, v148
	v_bitop3_b32 v86, v149, v112, v150 bitop3:0x36
	ds_read_b64_tr_b16 v[84:85], v253
	v_lshl_add_u32 v252, v86, 4, v151
	ds_read_b64_tr_b16 v[86:87], v252
	v_xor_b32_e32 v134, 0x20, v253
	ds_read_b64_tr_b16 v[134:135], v134
	v_xor_b32_e32 v136, 0x20, v252
	ds_read_b64_tr_b16 v[136:137], v136
	v_xor_b32_e32 v138, 0x40, v253
	ds_read_b64_tr_b16 v[138:139], v138
	v_xor_b32_e32 v140, 0x40, v252
	ds_read_b64_tr_b16 v[140:141], v140
	v_xor_b32_e32 v142, 0x60, v253
	ds_read_b64_tr_b16 v[142:143], v142
	v_xor_b32_e32 v144, 0x60, v252
	ds_read_b64_tr_b16 v[144:145], v144
	s_waitcnt lgkmcnt(0)
	v_mfma_f32_16x16x32_bf16 v[84:87], v[84:87], v[76:79], v[88:91]
	v_xor_b32_e32 v152, 0x80, v253
	ds_read_b64_tr_b16 v[88:89], v152
	v_mfma_f32_16x16x32_bf16 v[96:99], v[134:137], v[76:79], v[96:99]
	s_nop 0
	v_xor_b32_e32 v90, 0x80, v252
	ds_read_b64_tr_b16 v[90:91], v90
	v_xor_b32_e32 v134, 0xa0, v253
	v_mfma_f32_16x16x32_bf16 v[100:103], v[138:141], v[76:79], v[100:103]
	ds_read_b64_tr_b16 v[134:135], v134
	v_xor_b32_e32 v136, 0xa0, v252
	ds_read_b64_tr_b16 v[136:137], v136
	v_xor_b32_e32 v138, 0xc0, v253
	v_mfma_f32_16x16x32_bf16 v[126:129], v[142:145], v[76:79], v[126:129]
	ds_read_b64_tr_b16 v[138:139], v138
	v_xor_b32_e32 v140, 0xc0, v252
	ds_read_b64_tr_b16 v[140:141], v140
	v_xor_b32_e32 v142, 0xe0, v253
	ds_read_b64_tr_b16 v[142:143], v142
	v_xor_b32_e32 v144, 0xe0, v252
	ds_read_b64_tr_b16 v[144:145], v144
	s_waitcnt lgkmcnt(0)
; #define GAS __attribute__((address_space(1)))
; __device__ __forceinline__ unsigned pk2(float lo, float hi) { return f2bf(lo) | (f2bf(hi) << 16); }
; __device__ __forceinline__ s16x4 tr_read_b64(unsigned addr) { s16x4 r; asm volatile("ds_read_b64_tr_b16 %0, %1" : "=v"(r) : "v"(addr) : "memory"); return r; }
; template <int L>
; __device__ __forceinline__ void layer_body(const Args& args, LAS unsigned char* lds, const int wave, const int G, const int gw, const int NGW, const int lo, const int hi,
;                                            unsigned char* const ws_kernel, const XcdBarrier& bar, int& pid) {
;     ...
;                     for (int s = 0; s < 8; ++s) {
;                         const int ir0 = (r0w - krlo + s) * 40 + coloff;
; #pragma unroll
;                         for (int mh = 0; mh < 2; ++mh) {
;                             s16x4 lo[4], hi[4];
; #pragma unroll
;                             for (int m4 = 0; m4 < 4; ++m4) { const int mt = mh * 4 + m4, r0_ = ir0 + 4 * kg + trq, r1_ = ir0 + 16 + 4 * kg + trq, ch_ = 2 * mt + (trp >> 1);
;                                 lo[m4] = tr_read_b64(IMG + vimg_off(r0_, ch_) + 8u * (trp & 1)); hi[m4] = tr_read_b64(IMG + vimg_off(r1_, ch_) + 8u * (trp & 1)); }
;                             asm volatile("s_waitcnt lgkmcnt(0)" ::: "memory"); __builtin_amdgcn_sched_barrier(0);
; #pragma unroll
;                             for (int m4 = 0; m4 < 4; ++m4) { const int mt = mh * 4 + m4; const bf16x8 va = (bf16x8){lo[m4][0], lo[m4][1], lo[m4][2], lo[m4][3], hi[m4][0], hi[m4][1], hi[m4][2], hi[m4][3]};
;                                 acc[mt] = __builtin_amdgcn_mfma_f32_16x16x32_bf16(va, pbf[s], acc[mt], 0, 0, 0); }
;                         }
;                     }
;                     const float inv = 1.0f / sum;
;                     GAS bf16* op = (GAS bf16*)(obuf + (size_t)(b * SEQ + r * 64 + c) * D + h * HD + 4 * kg);
; #pragma unroll
;                     for (int mt = 0; mt < 8; ++mt) { v2u w; w.x = pk2(acc[mt][0] * inv, acc[mt][1] * inv); w.y = pk2(acc[mt][2] * inv, acc[mt][3] * inv); *(GAS v2u*)(op + 16 * mt) = w; }
	s_add_i32 s41, s41, s15
	v_add_u32_e32 v115, s41, v115
	v_mfma_f32_16x16x32_bf16 v[88:91], v[88:91], v[76:79], v[92:95]
	v_add_u32_e32 v113, s41, v113
	v_bfe_u32 v147, v115, 2, 2
	v_lshl_add_u32 v148, v115, 8, v111
	v_lshlrev_b32_e32 v92, 2, v115
	v_and_b32_e32 v146, 12, v92
	v_lshlrev_b32_e32 v115, 2, v113
	v_mfma_f32_16x16x32_bf16 v[92:95], v[134:137], v[76:79], v[122:125]
	v_lshl_add_u32 v111, v113, 8, v111
	v_mfma_f32_16x16x32_bf16 v[122:125], v[138:141], v[76:79], v[130:133]
	v_and_b32_e32 v138, 12, v115
	v_bfe_u32 v139, v113, 2, 2
	v_mfma_f32_16x16x32_bf16 v[76:79], v[142:145], v[76:79], v[80:83]
	v_bitop3_b32 v130, v146, v116, v147 bitop3:0x36
	v_lshl_add_u32 v130, v130, 4, v148
	v_bitop3_b32 v116, v138, v116, v139 bitop3:0x36
	v_bitop3_b32 v80, v146, v112, v147 bitop3:0x36
	v_lshl_add_u32 v253, v80, 4, v148
	v_bitop3_b32 v82, v138, v112, v139 bitop3:0x36
	ds_read_b64_tr_b16 v[80:81], v253
	v_lshl_add_u32 v252, v82, 4, v111
	ds_read_b64_tr_b16 v[82:83], v252
	v_xor_b32_e32 v112, 0x20, v253
	ds_read_b64_tr_b16 v[112:113], v112
	v_xor_b32_e32 v114, 0x20, v252
	ds_read_b64_tr_b16 v[114:115], v114
	ds_read_b64_tr_b16 v[130:131], v130
	v_lshl_add_u32 v116, v116, 4, v111
	ds_read_b64_tr_b16 v[132:133], v116
	v_xor_b32_e32 v116, 0x60, v253
	ds_read_b64_tr_b16 v[134:135], v116
	v_xor_b32_e32 v116, 0x60, v252
	ds_read_b64_tr_b16 v[136:137], v116
	s_waitcnt lgkmcnt(0)
	v_mfma_f32_16x16x32_bf16 v[80:83], v[80:83], v[72:75], v[84:87]
	v_xor_b32_e32 v116, 0x80, v253
	ds_read_b64_tr_b16 v[84:85], v116
	v_mfma_f32_16x16x32_bf16 v[96:99], v[112:115], v[72:75], v[96:99]
	s_nop 0
	v_xor_b32_e32 v86, 0x80, v252
	ds_read_b64_tr_b16 v[86:87], v86
	v_xor_b32_e32 v112, 0xa0, v253
	ds_read_b64_tr_b16 v[112:113], v112
	v_xor_b32_e32 v114, 0xa0, v252
	v_mfma_f32_16x16x32_bf16 v[116:119], v[134:137], v[72:75], v[126:129]
	ds_read_b64_tr_b16 v[114:115], v114
	v_mfma_f32_16x16x32_bf16 v[100:103], v[130:133], v[72:75], v[100:103]
	s_nop 1
	v_xor_b32_e32 v126, 0xc0, v253
	ds_read_b64_tr_b16 v[126:127], v126
	v_xor_b32_e32 v120, 0xc0, v252
	ds_read_b64_tr_b16 v[128:129], v120
	v_xor_b32_e32 v120, 0xe0, v253
	ds_read_b64_tr_b16 v[130:131], v120
	v_xor_b32_e32 v111, 0xe0, v252
	ds_read_b64_tr_b16 v[132:133], v111
	s_waitcnt lgkmcnt(0)
	v_div_scale_f32 v111, s[6:7], v104, v104, 1.0
	v_rcp_f32_e32 v120, v111
	v_mfma_f32_16x16x32_bf16 v[84:87], v[84:87], v[72:75], v[88:91]
	s_lshl_b32 s6, s14, 6
	s_add_i32 s6, s6, s60
	s_lshl_b32 s60, s36, 1
	v_fma_f32 v88, -v111, v120, 1.0
	v_fmac_f32_e32 v120, v88, v120
	v_mfma_f32_16x16x32_bf16 v[88:91], v[112:115], v[72:75], v[92:95]
	v_div_scale_f32 v112, vcc, 1.0, v104, 1.0
	v_mul_f32_e32 v113, v112, v120
	v_fma_f32 v114, -v111, v113, v112
	v_mfma_f32_16x16x32_bf16 v[92:95], v[126:129], v[72:75], v[122:125]
	v_fmac_f32_e32 v113, v114, v120
	v_fma_f32 v111, -v111, v113, v112
	s_add_i32 s84, s84, s82
	v_mfma_f32_16x16x32_bf16 v[72:75], v[130:133], v[72:75], v[76:79]
	s_add_i32 s96, s96, s92
	s_nop 1
	v_or_b32_e32 v78, s6, v109
	v_ashrrev_i32_e32 v79, 31, v78
	v_div_fmas_f32 v76, v111, v120, v113
	v_lshlrev_b64 v[78:79], 12, v[78:79]
	v_div_fixup_f32 v76, v76, v104, 1.0
	v_lshl_add_u64 v[78:79], s[4:5], 0, v[78:79]
	v_mov_b32_e32 v111, v82
	v_mov_b32_e32 v82, v81
	v_lshl_add_u64 v[78:79], v[78:79], 0, s[60:61]
	v_lshlrev_b32_e32 v104, 1, v110
	v_mov_b32_e32 v110, v80
	v_pk_mul_f32 v[80:81], v[76:77], v[82:83] op_sel_hi:[0,1]
	v_lshl_add_u64 v[78:79], v[78:79], 0, v[104:105]
	v_pk_mul_f32 v[110:111], v[76:77], v[110:111] op_sel_hi:[0,1]
	v_and_b32_sdwa v83, v81, v108 dst_sel:DWORD dst_unused:UNUSED_PAD src0_sel:WORD_1 src1_sel:DWORD
	v_and_b32_sdwa v77, v111, v108 dst_sel:DWORD dst_unused:UNUSED_PAD src0_sel:WORD_1 src1_sel:DWORD
	v_add3_u32 v81, v81, v83, s23
	v_add3_u32 v77, v111, v77, s23
	v_and_b32_e32 v81, 0xffff0000, v81
	v_or_b32_sdwa v81, v81, v77 dst_sel:DWORD dst_unused:UNUSED_PAD src0_sel:DWORD src1_sel:WORD_1
	v_cvt_pk_bf16_f32 v80, v110, v80
	global_store_dwordx2 v[78:79], v[80:81], off
	v_mov_b32_e32 v80, v96
	v_mov_b32_e32 v81, v98
	v_pk_mul_f32 v[80:81], v[76:77], v[80:81] op_sel_hi:[0,1]
	v_mov_b32_e32 v98, v97
	v_pk_mul_f32 v[82:83], v[76:77], v[98:99] op_sel_hi:[0,1]
	v_and_b32_sdwa v77, v81, v108 dst_sel:DWORD dst_unused:UNUSED_PAD src0_sel:WORD_1 src1_sel:DWORD
	v_add3_u32 v77, v81, v77, s23
	v_and_b32_sdwa v81, v83, v108 dst_sel:DWORD dst_unused:UNUSED_PAD src0_sel:WORD_1 src1_sel:DWORD
	v_add3_u32 v81, v83, v81, s23
	v_and_b32_e32 v81, 0xffff0000, v81
	v_or_b32_sdwa v81, v81, v77 dst_sel:DWORD dst_unused:UNUSED_PAD src0_sel:DWORD src1_sel:WORD_1
	v_cvt_pk_bf16_f32 v80, v80, v82
	global_store_dwordx2 v[78:79], v[80:81], off offset:32
	v_mov_b32_e32 v80, v100
	v_mov_b32_e32 v81, v102
	v_pk_mul_f32 v[80:81], v[76:77], v[80:81] op_sel_hi:[0,1]
	v_mov_b32_e32 v102, v101
	v_pk_mul_f32 v[82:83], v[76:77], v[102:103] op_sel_hi:[0,1]
	v_and_b32_sdwa v77, v81, v108 dst_sel:DWORD dst_unused:UNUSED_PAD src0_sel:WORD_1 src1_sel:DWORD
	v_add3_u32 v77, v81, v77, s23
	v_and_b32_sdwa v81, v83, v108 dst_sel:DWORD dst_unused:UNUSED_PAD src0_sel:WORD_1 src1_sel:DWORD
	v_add3_u32 v81, v83, v81, s23
	v_and_b32_e32 v81, 0xffff0000, v81
	v_or_b32_sdwa v81, v81, v77 dst_sel:DWORD dst_unused:UNUSED_PAD src0_sel:DWORD src1_sel:WORD_1
	v_cvt_pk_bf16_f32 v80, v80, v82
	global_store_dwordx2 v[78:79], v[80:81], off offset:64
	v_mov_b32_e32 v80, v116
	v_mov_b32_e32 v81, v118
	v_pk_mul_f32 v[80:81], v[76:77], v[80:81] op_sel_hi:[0,1]
	v_mov_b32_e32 v118, v117
	v_pk_mul_f32 v[82:83], v[76:77], v[118:119] op_sel_hi:[0,1]
	v_and_b32_sdwa v77, v81, v108 dst_sel:DWORD dst_unused:UNUSED_PAD src0_sel:WORD_1 src1_sel:DWORD
	v_add3_u32 v77, v81, v77, s23
; #define GAS __attribute__((address_space(1)))
; #define LAS __attribute__((address_space(3)))
; __device__ __forceinline__ unsigned pk2(float lo, float hi) { return f2bf(lo) | (f2bf(hi) << 16); }
; #define NA_DECODE(u_, b, h, rbase, hc, krlo, nkr) do { hc = (u_) & 1; const int rg_ = ((u_) >> 1) & 7; h = ((u_) >> 4) & 15; b = (u_) >> 8; rbase = 4 * rg_; \
;                     krlo = min(max(rbase - 4, 0), 24); nkr = min(max(rbase - 1, 0), 24) + 8 - krlo; } while (0)
; template <int L>
; __device__ __forceinline__ void layer_body(const Args& args, LAS unsigned char* lds, const int wave, const int G, const int gw, const int NGW, const int lo, const int hi,
;                                            unsigned char* const ws_kernel, const XcdBarrier& bar, int& pid) {
;     ...
;                 for (; unit < UEND; unit += GH) {
;                     int b, h, rbase, hc, krlo, nkr; NA_DECODE(unit, b, h, rbase, hc, krlo, nkr);
;                     int tl_ = tid; asm volatile("" : "+v"(tl_));
;                     const int lane = tl_ & 63, qi = lane & 15, kg = lane >> 4, sch = tl_ & 15, skey = tl_ >> 4;
; #pragma unroll
;                     for (int i = 0; i < 14; ++i) { const int kid = skey + 32 * i; *(LAS v4u*)(size_t)(IMG + kid * KPITCH + 16 * sch) = rst[i]; }
;                     if (tl_ < 15 * 31) rl[tl_] = rpb[h * 15 * 31 + tl_];
;     ...
;                     const float inv = 1.0f / sum;
;                     GAS bf16* op = (GAS bf16*)(obuf + (size_t)(b * SEQ + r * 64 + c) * D + h * HD + 4 * kg);
; #pragma unroll
;                     for (int mt = 0; mt < 8; ++mt) { v2u w; w.x = pk2(acc[mt][0] * inv, acc[mt][1] * inv); w.y = pk2(acc[mt][2] * inv, acc[mt][3] * inv); *(GAS v2u*)(op + 16 * mt) = w; }
;                     __syncthreads();
	v_and_b32_sdwa v81, v83, v108 dst_sel:DWORD dst_unused:UNUSED_PAD src0_sel:WORD_1 src1_sel:DWORD
	v_add3_u32 v81, v83, v81, s23
	v_and_b32_e32 v81, 0xffff0000, v81
	v_or_b32_sdwa v81, v81, v77 dst_sel:DWORD dst_unused:UNUSED_PAD src0_sel:DWORD src1_sel:WORD_1
	v_cvt_pk_bf16_f32 v80, v80, v82
	global_store_dwordx2 v[78:79], v[80:81], off offset:96
	v_mov_b32_e32 v80, v84
	v_mov_b32_e32 v81, v86
	v_pk_mul_f32 v[80:81], v[76:77], v[80:81] op_sel_hi:[0,1]
	v_mov_b32_e32 v86, v85
	v_pk_mul_f32 v[82:83], v[76:77], v[86:87] op_sel_hi:[0,1]
	v_and_b32_sdwa v77, v81, v108 dst_sel:DWORD dst_unused:UNUSED_PAD src0_sel:WORD_1 src1_sel:DWORD
	v_add3_u32 v77, v81, v77, s23
	v_and_b32_sdwa v81, v83, v108 dst_sel:DWORD dst_unused:UNUSED_PAD src0_sel:WORD_1 src1_sel:DWORD
	v_add3_u32 v81, v83, v81, s23
	v_and_b32_e32 v81, 0xffff0000, v81
	v_or_b32_sdwa v81, v81, v77 dst_sel:DWORD dst_unused:UNUSED_PAD src0_sel:DWORD src1_sel:WORD_1
	v_cvt_pk_bf16_f32 v80, v80, v82
	global_store_dwordx2 v[78:79], v[80:81], off offset:128
	v_mov_b32_e32 v80, v88
	v_mov_b32_e32 v81, v90
	v_pk_mul_f32 v[80:81], v[76:77], v[80:81] op_sel_hi:[0,1]
	v_mov_b32_e32 v90, v89
	v_pk_mul_f32 v[82:83], v[76:77], v[90:91] op_sel_hi:[0,1]
	v_and_b32_sdwa v77, v81, v108 dst_sel:DWORD dst_unused:UNUSED_PAD src0_sel:WORD_1 src1_sel:DWORD
	v_add3_u32 v77, v81, v77, s23
	v_and_b32_sdwa v81, v83, v108 dst_sel:DWORD dst_unused:UNUSED_PAD src0_sel:WORD_1 src1_sel:DWORD
	v_add3_u32 v81, v83, v81, s23
	v_and_b32_e32 v81, 0xffff0000, v81
	v_or_b32_sdwa v81, v81, v77 dst_sel:DWORD dst_unused:UNUSED_PAD src0_sel:DWORD src1_sel:WORD_1
	v_cvt_pk_bf16_f32 v80, v80, v82
	global_store_dwordx2 v[78:79], v[80:81], off offset:160
	v_mov_b32_e32 v80, v92
	v_mov_b32_e32 v81, v94
	v_pk_mul_f32 v[80:81], v[76:77], v[80:81] op_sel_hi:[0,1]
	v_mov_b32_e32 v94, v93
	v_pk_mul_f32 v[82:83], v[76:77], v[94:95] op_sel_hi:[0,1]
	v_and_b32_sdwa v77, v81, v108 dst_sel:DWORD dst_unused:UNUSED_PAD src0_sel:WORD_1 src1_sel:DWORD
	v_add3_u32 v77, v81, v77, s23
	v_and_b32_sdwa v81, v83, v108 dst_sel:DWORD dst_unused:UNUSED_PAD src0_sel:WORD_1 src1_sel:DWORD
	v_add3_u32 v81, v83, v81, s23
	v_and_b32_e32 v81, 0xffff0000, v81
	v_or_b32_sdwa v81, v81, v77 dst_sel:DWORD dst_unused:UNUSED_PAD src0_sel:DWORD src1_sel:WORD_1
	v_cvt_pk_bf16_f32 v80, v80, v82
	global_store_dwordx2 v[78:79], v[80:81], off offset:192
	v_mov_b32_e32 v81, v74
	v_mov_b32_e32 v74, v73
	v_mov_b32_e32 v80, v72
	v_pk_mul_f32 v[72:73], v[76:77], v[74:75] op_sel_hi:[0,1]
	v_pk_mul_f32 v[80:81], v[76:77], v[80:81] op_sel_hi:[0,1]
	v_cvt_pk_bf16_f32 v73, v81, v73
	v_cvt_pk_bf16_f32 v72, v80, v72
	s_andn2_b64 vcc, exec, s[0:1]
	global_store_dwordx2 v[78:79], v[72:73], off offset:224
	s_barrier
	s_cbranch_vccz .LBB0_976
.LBB0_844:
	v_mov_b32_e32 v111, v106
	s_movk_i32 s0, 0x1d1
	v_and_b32_e32 v112, 15, v111
	v_ashrrev_i32_e32 v77, 4, v111
	v_lshlrev_b32_e32 v104, 4, v112
	v_mul_lo_u32 v72, v77, s90
	s_bfe_u32 s36, s21, 0x40004
	v_add3_u32 v72, v104, 0, v72
	v_cmp_gt_i32_e32 vcc, s0, v111
	s_waitcnt vmcnt(0)
	ds_write_b128 v72, v[0:3]
	v_add_u32_e32 v0, 0x2200, v72
	ds_write_b128 v72, v[4:7] offset:8704
	v_add_u32_e32 v1, 0x4400, v72
	ds_write_b128 v72, v[8:11] offset:17408
	v_add_u32_e32 v2, 0x6600, v72
	ds_write_b128 v72, v[12:15] offset:26112
	v_add_u32_e32 v3, 0x8800, v72
	ds_write_b128 v72, v[16:19] offset:34816
	v_add_u32_e32 v4, 0xaa00, v72
	ds_write_b128 v72, v[20:23] offset:43520
	v_add_u32_e32 v5, 0xcc00, v72
	ds_write_b128 v72, v[40:43] offset:52224
	ds_write_b128 v72, v[44:47] offset:60928
	ds_write_b128 v0, v[48:51] offset:60928
	ds_write_b128 v1, v[52:55] offset:60928
	ds_write_b128 v2, v[56:59] offset:60928
	ds_write_b128 v3, v[60:63] offset:60928
	ds_write_b128 v4, v[64:67] offset:60928
	ds_write_b128 v5, v[68:71] offset:60928
	s_and_saveexec_b64 s[0:1], vcc
	s_cbranch_execz .LBB0_846
	s_mul_i32 s6, s36, 0x1d1
	v_add_u32_e32 v0, s6, v111
	v_readlane_b32 s64, v254, 27
	v_ashrrev_i32_e32 v1, 31, v0
	v_readlane_b32 s65, v254, 28
	v_readlane_b32 s66, v254, 29
	v_readlane_b32 s67, v254, 30
	v_lshl_add_u64 v[0:1], v[0:1], 2, s[64:65]
	global_load_dword v0, v[0:1], off
	v_lshl_add_u32 v1, v111, 2, 0
	v_add_u32_e32 v1, 0x1dc00, v1
	v_readlane_b32 s68, v254, 31
	v_readlane_b32 s69, v254, 32
	v_readlane_b32 s70, v254, 33
	v_readlane_b32 s71, v254, 34
	v_readlane_b32 s72, v254, 35
	v_readlane_b32 s73, v254, 36
	v_readlane_b32 s74, v254, 37
	v_readlane_b32 s75, v254, 38
	v_readlane_b32 s76, v254, 39
	v_readlane_b32 s77, v254, 40
	v_readlane_b32 s78, v254, 41
	v_readlane_b32 s79, v254, 42
	s_waitcnt vmcnt(0)
	v_mul_f32_e32 v0, s63, v0
	ds_write_b32 v1, v0
; #define LAS __attribute__((address_space(3)))
; #define NA_DECODE(u_, b, h, rbase, hc, krlo, nkr) do { hc = (u_) & 1; const int rg_ = ((u_) >> 1) & 7; h = ((u_) >> 4) & 15; b = (u_) >> 8; rbase = 4 * rg_; \
;                     krlo = min(max(rbase - 4, 0), 24); nkr = min(max(rbase - 1, 0), 24) + 8 - krlo; } while (0)
; template <int L>
; __device__ __forceinline__ void layer_body(const Args& args, LAS unsigned char* lds, const int wave, const int G, const int gw, const int NGW, const int lo, const int hi,
;                                            unsigned char* const ws_kernel, const XcdBarrier& bar, int& pid) {
;     ...
;                 int unit = vcu;
;                 { const int qi = lane & 15, kg = lane >> 4, sch = tid & 15, skey = tid >> 4; if (unit < UEND) { NA_LOADROWS(unit, rst, D); NA_LOADQ(unit); } }
;                 for (; unit < UEND; unit += GH) {
;                     int b, h, rbase, hc, krlo, nkr; NA_DECODE(unit, b, h, rbase, hc, krlo, nkr);
;                     int tl_ = tid; asm volatile("" : "+v"(tl_));
;                     const int lane = tl_ & 63, qi = lane & 15, kg = lane >> 4, sch = tl_ & 15, skey = tl_ >> 4;
; #pragma unroll
;                     for (int i = 0; i < 14; ++i) { const int kid = skey + 32 * i; *(LAS v4u*)(size_t)(IMG + kid * KPITCH + 16 * sch) = rst[i]; }
;                     if (tl_ < 15 * 31) rl[tl_] = rpb[h * 15 * 31 + tl_];
;                     __syncthreads();
;                     NA_LOADROWS(unit, rst, 2 * D);
;                     const int rr = wave >> 1, cb = 2 * hc + (wave & 1), r = rbase + rr, r0w = min(max(r - 4, 0), 24), cs = min(max(16 * cb - 8, 0), 32), coloff = cs - 24 * hc;
.LBB0_846:
	s_or_b64 exec, exec, s[0:1]
	s_add_i32 s0, s81, s84
	s_and_b32 s14, s0, 28
	s_max_u32 s0, s14, 4
	v_med3_u32 v0, s14, 1, 25
	v_add_u32_e32 v4, 32, v77
	v_add_u32_e32 v8, 64, v77
	v_add_u32_e32 v12, 0x60, v77
	v_add_u32_e32 v16, 0x80, v77
	v_add_u32_e32 v20, 0xa0, v77
	v_add_u32_e32 v40, 0xc0, v77
	v_add_u32_e32 v44, 0xe0, v77
	v_add_u32_e32 v48, 0x100, v77
	v_add_u32_e32 v52, 0x120, v77
	v_add_u32_e32 v56, 0x140, v77
	v_add_u32_e32 v60, 0x160, v77
	v_add_u32_e32 v64, 0x180, v77
	v_add_u32_e32 v70, 0x1a0, v77
	s_and_b32 s1, s21, 1
	s_lshl_b32 s6, s36, 8
	v_subrev_u32_e32 v0, s0, v0
	s_add_u32 s6, s57, s6
	v_add_u32_e32 v72, 10, v0
	v_mul_hi_i32 v0, v77, s9
	v_mul_hi_i32 v5, v4, s9
	v_mul_hi_i32 v9, v8, s9
	v_mul_hi_i32 v13, v12, s9
	v_mul_hi_i32 v17, v16, s9
	v_mul_hi_i32 v21, v20, s9
	v_mul_hi_i32 v41, v40, s9
	v_mul_hi_i32 v45, v44, s9
	v_mul_hi_i32 v49, v48, s9
	v_mul_hi_i32 v53, v52, s9
	v_mul_hi_i32 v57, v56, s9
	v_mul_hi_i32 v61, v60, s9
	v_mul_hi_i32 v65, v64, s9
	v_mul_hi_i32 v73, v70, s9
	s_addc_u32 s7, s58, 0
	v_lshrrev_b32_e32 v1, 31, v0
	v_ashrrev_i32_e32 v0, 4, v0
	v_lshrrev_b32_e32 v6, 31, v5
	v_ashrrev_i32_e32 v5, 4, v5
	v_lshrrev_b32_e32 v10, 31, v9
	v_ashrrev_i32_e32 v9, 4, v9
	v_lshrrev_b32_e32 v14, 31, v13
	v_ashrrev_i32_e32 v13, 4, v13
	v_lshrrev_b32_e32 v18, 31, v17
	v_ashrrev_i32_e32 v17, 4, v17
	v_lshrrev_b32_e32 v22, 31, v21
	v_ashrrev_i32_e32 v21, 4, v21
	v_lshrrev_b32_e32 v42, 31, v41
	v_ashrrev_i32_e32 v41, 4, v41
	v_lshrrev_b32_e32 v46, 31, v45
	v_ashrrev_i32_e32 v45, 4, v45
	v_lshrrev_b32_e32 v50, 31, v49
	v_ashrrev_i32_e32 v49, 4, v49
	v_lshrrev_b32_e32 v54, 31, v53
	v_ashrrev_i32_e32 v53, 4, v53
	v_lshrrev_b32_e32 v58, 31, v57
	v_ashrrev_i32_e32 v57, 4, v57
	v_lshrrev_b32_e32 v62, 31, v61
	v_ashrrev_i32_e32 v61, 4, v61
	v_lshrrev_b32_e32 v66, 31, v65
	v_ashrrev_i32_e32 v65, 4, v65
	v_lshrrev_b32_e32 v74, 31, v73
	v_ashrrev_i32_e32 v73, 4, v73
	v_lshl_add_u64 v[68:69], s[6:7], 0, v[104:105]
	s_add_i32 s6, s85, s96
	v_add_u32_e32 v78, v0, v1
	v_add_u32_e32 v80, v5, v6
	v_add_u32_e32 v82, v9, v10
	v_add_u32_e32 v84, v13, v14
	v_add_u32_e32 v86, v17, v18
	v_add_u32_e32 v88, v21, v22
	v_add_u32_e32 v90, v41, v42
	v_add_u32_e32 v92, v45, v46
	v_add_u32_e32 v94, v49, v50
	v_add_u32_e32 v96, v53, v54
	v_add_u32_e32 v98, v57, v58
	v_add_u32_e32 v100, v61, v62
	v_add_u32_e32 v102, v65, v66
	v_add_u32_e32 v113, v73, v74
	v_sub_u32_e64 v71, s14, 4 clamp
	s_and_b32 s60, s6, 0xfffff800
	s_mul_i32 s6, s1, 24
	v_min_i32_e32 v0, v78, v72
	v_min_i32_e32 v5, v80, v72
	v_min_i32_e32 v9, v82, v72
	v_min_i32_e32 v13, v84, v72
	v_min_i32_e32 v17, v86, v72
	v_min_i32_e32 v21, v88, v72
	v_min_i32_e32 v41, v90, v72
	v_min_i32_e32 v45, v92, v72
	v_min_i32_e32 v49, v94, v72
	v_min_i32_e32 v53, v96, v72
	v_min_i32_e32 v57, v98, v72
	v_min_i32_e32 v61, v100, v72
	v_min_i32_e32 v65, v102, v72
	v_min_i32_e32 v72, v113, v72
	s_or_b32 s8, s60, s6
	v_add_lshl_u32 v0, v0, v71, 6
	v_mad_i32_i24 v79, v78, s88, v77
	v_add_lshl_u32 v5, v5, v71, 6
	v_mad_i32_i24 v81, v80, s88, v4
	v_add_lshl_u32 v9, v9, v71, 6
	v_mad_i32_i24 v83, v82, s88, v8
	v_add_lshl_u32 v13, v13, v71, 6
	v_mad_i32_i24 v85, v84, s88, v12
	v_add_lshl_u32 v17, v17, v71, 6
	v_mad_i32_i24 v87, v86, s88, v16
	v_add_lshl_u32 v21, v21, v71, 6
	v_mad_i32_i24 v89, v88, s88, v20
	v_add_lshl_u32 v41, v41, v71, 6
	v_mad_i32_i24 v91, v90, s88, v40
	v_add_lshl_u32 v45, v45, v71, 6
	v_mad_i32_i24 v93, v92, s88, v44
	v_add_lshl_u32 v49, v49, v71, 6
	v_mad_i32_i24 v95, v94, s88, v48
	v_add_lshl_u32 v53, v53, v71, 6
	v_mad_i32_i24 v97, v96, s88, v52
	v_add_lshl_u32 v57, v57, v71, 6
	v_mad_i32_i24 v99, v98, s88, v56
	v_add_lshl_u32 v61, v61, v71, 6
	v_mad_i32_i24 v101, v100, s88, v60
	v_add_lshl_u32 v65, v65, v71, 6
	v_mad_i32_i24 v103, v102, s88, v64
	v_add_lshl_u32 v71, v72, v71, 6
	v_mad_i32_i24 v114, v113, s88, v70
	v_add3_u32 v0, v79, s8, v0
	v_add3_u32 v4, v81, s8, v5
	v_add3_u32 v8, v83, s8, v9
	v_add3_u32 v12, v85, s8, v13
	v_add3_u32 v16, v87, s8, v17
	v_add3_u32 v20, v89, s8, v21
	v_add3_u32 v40, v91, s8, v41
	v_add3_u32 v44, v93, s8, v45
	v_add3_u32 v48, v95, s8, v49
	v_add3_u32 v52, v97, s8, v53
	v_add3_u32 v56, v99, s8, v57
	v_add3_u32 v60, v101, s8, v61
	v_add3_u32 v64, v103, s8, v65
	v_add3_u32 v70, v114, s8, v71
	v_mad_i64_i32 v[0:1], s[6:7], v0, s22, v[68:69]
	v_mad_i64_i32 v[4:5], s[6:7], v4, s22, v[68:69]
	v_mad_i64_i32 v[8:9], s[6:7], v8, s22, v[68:69]
	v_mad_i64_i32 v[12:13], s[6:7], v12, s22, v[68:69]
	v_mad_i64_i32 v[16:17], s[6:7], v16, s22, v[68:69]
	v_mad_i64_i32 v[20:21], s[6:7], v20, s22, v[68:69]
	v_mad_i64_i32 v[40:41], s[6:7], v40, s22, v[68:69]
	v_mad_i64_i32 v[44:45], s[6:7], v44, s22, v[68:69]
	v_mad_i64_i32 v[48:49], s[6:7], v48, s22, v[68:69]
	v_mad_i64_i32 v[52:53], s[6:7], v52, s22, v[68:69]
	v_mad_i64_i32 v[56:57], s[6:7], v56, s22, v[68:69]
	v_mad_i64_i32 v[60:61], s[6:7], v60, s22, v[68:69]
	v_mad_i64_i32 v[64:65], s[6:7], v64, s22, v[68:69]
	v_mad_i64_i32 v[68:69], s[6:7], v70, s22, v[68:69]
	s_waitcnt lgkmcnt(0)
	s_barrier
; #define LAS __attribute__((address_space(3)))
; template <int L>
; __device__ __forceinline__ void layer_body(const Args& args, LAS unsigned char* lds, const int wave, const int G, const int gw, const int NGW, const int lo, const int hi,
;                                            unsigned char* const ws_kernel, const XcdBarrier& bar, int& pid) {
;     ...
;                     NA_LOADROWS(unit, rst, 2 * D);
;                     const int rr = wave >> 1, cb = 2 * hc + (wave & 1), r = rbase + rr, r0w = min(max(r - 4, 0), 24), cs = min(max(16 * cb - 8, 0), 32), coloff = cs - 24 * hc;
;                     const int c = 16 * cb + qi, wsq = min(max(c - 8, 0), 48);
;                     f32x4 sc[16];
; #pragma unroll
;                     for (int t = 0; t < 16; ++t) {
;                         const int irow = (r0w - krlo + (t >> 1)) * 40 + coloff + 16 * (t & 1);
;                         const unsigned ka = IMG + (unsigned)((irow + qi) * KPITCH + 16 * kg);
;                         f32x4 a = (f32x4){0.f, 0.f, 0.f, 0.f};
; #pragma unroll
;                         for (int ks = 0; ks < 4; ++ks) a = __builtin_amdgcn_mfma_f32_16x16x32_bf16(*(const LAS bf16x8*)(size_t)(ka + 64 * ks), qfn[ks], a, 0, 0, 0);
;                         const int dr = r0w + (t >> 1) - r + 7;
; #pragma unroll
;                         for (int j = 0; j < 4; ++j) { const int kc = cs + 16 * (t & 1) + 4 * kg + j; const bool valid = (kc >= wsq) && (kc < wsq + 16); const int dc = min(max(kc - c + 15, 0), 30);
;                             sc[t][j] = valid ? a[j] * scale_log2 + rl[dr * 31 + dc] * LOG2E : -1e30f; }
	global_load_dwordx4 v[0:3], v[0:1], off
	s_add_i32 s14, s14, s53
	global_load_dwordx4 v[4:7], v[4:5], off
	s_lshl_b32 s7, s1, 5
	global_load_dwordx4 v[8:11], v[8:9], off
	s_max_i32 s6, s14, 4
	global_load_dwordx4 v[12:15], v[12:13], off
	s_or_b32 s7, s7, s54
	global_load_dwordx4 v[16:19], v[16:17], off
	s_add_i32 s6, s6, -4
	global_load_dwordx4 v[20:23], v[20:21], off
	s_max_i32 s8, s7, 8
	global_load_dwordx4 v[40:43], v[40:41], off
	s_min_u32 s6, s6, 24
	global_load_dwordx4 v[44:47], v[44:45], off
	s_add_i32 s8, s8, -8
	global_load_dwordx4 v[48:51], v[48:49], off
	s_min_u32 s8, s8, 32
	global_load_dwordx4 v[52:55], v[52:53], off
	s_mulk_i32 s1, 0xffe8
	global_load_dwordx4 v[56:59], v[56:57], off
	v_or_b32_e32 v109, s7, v112
	global_load_dwordx4 v[60:63], v[60:61], off
	s_sub_i32 s41, s6, s0
	global_load_dwordx4 v[64:67], v[64:65], off
	s_add_i32 s15, s8, s1
	global_load_dwordx4 v[68:71], v[68:69], off
	v_max_i32_e32 v72, 8, v109
	s_mul_i32 s41, s41, 40
	v_bfe_u32 v76, v111, 4, 2
	v_add_u32_e32 v72, -8, v72
	v_add_u32_e32 v121, s15, v112
	s_sub_i32 s0, s6, s14
	s_add_i32 s6, s41, 0xa0
	v_min_u32_e32 v129, 48, v72
	v_lshl_add_u32 v118, v76, 4, 0
	v_add_u32_e32 v72, s6, v121
	v_mad_i32_i24 v104, v72, s90, v118
	ds_read_b128 v[72:75], v104
	ds_read_b128 v[122:125], v104 offset:64
	s_waitcnt lgkmcnt(1)
	v_mfma_f32_16x16x32_bf16 v[72:75], v[72:75], v[24:27], 0
	v_lshlrev_b32_e32 v110, 2, v76
	v_add_u32_e32 v134, s8, v110
	v_add_u32_e32 v131, 16, v129
	s_waitcnt lgkmcnt(0)
	v_mfma_f32_16x16x32_bf16 v[72:75], v[122:125], v[28:31], v[72:75]
	ds_read_b128 v[122:125], v104 offset:128
	s_mulk_i32 s0, 0x7c
	s_add_i32 s42, s0, 0
	s_waitcnt lgkmcnt(0)
	v_mfma_f32_16x16x32_bf16 v[72:75], v[122:125], v[32:35], v[72:75]
	ds_read_b128 v[122:125], v104 offset:192
	v_cmp_ge_u32_e32 vcc, v134, v129
	v_cmp_lt_u32_e64 s[0:1], v134, v131
	s_waitcnt lgkmcnt(0)
	v_mfma_f32_16x16x32_bf16 v[72:75], v[122:125], v[36:39], v[72:75]
	v_sub_u32_e32 v115, v134, v109
	s_add_i32 s42, s42, 0x1dc00
	s_and_b64 s[64:65], vcc, s[0:1]
	v_mov_b32_e32 v104, 0xf149f2ca
	v_max_i32_e32 v124, -15, v115
	v_mov_b32_e32 v115, 0xf149f2ca
	v_mov_b32_e32 v204, 0xf149f2ca
	s_nop 1
	v_add_u32_e32 v201, 15, v124
	v_min_u32_e32 v201, 30, v201
	v_lshl_add_u32 v216, v201, 2, s42
	ds_read_b32 v201, v216 offset:868
	s_nop 0
	s_waitcnt lgkmcnt(0)
	v_fma_f32 v200, v72, s62, v201
	v_cndmask_b32_e64 v115, v204, v200, s[64:65]
	v_or_b32_e32 v72, 1, v134
	v_cmp_ge_u32_e32 vcc, v72, v129
	v_cmp_lt_u32_e64 s[0:1], v72, v131
	v_sub_u32_e32 v72, v72, v109
	s_and_b64 s[66:67], vcc, s[0:1]
	v_max_i32_e32 v125, -15, v72
	s_nop 1
	v_add_u32_e32 v203, 15, v125
	v_min_u32_e32 v203, 30, v203
	v_lshl_add_u32 v217, v203, 2, s42
	ds_read_b32 v203, v217 offset:868
	s_nop 0
	s_waitcnt lgkmcnt(0)
	v_fma_f32 v202, v73, s62, v203
	v_cndmask_b32_e64 v104, v204, v202, s[66:67]
	v_or_b32_e32 v72, 2, v134
	v_cmp_ge_u32_e32 vcc, v72, v129
	v_cmp_lt_u32_e64 s[0:1], v72, v131
	v_sub_u32_e32 v72, v72, v109
	s_and_b64 s[68:69], vcc, s[0:1]
	v_mov_b32_e32 v116, 0xf149f2ca
	v_max_i32_e32 v126, -15, v72
	v_mov_b32_e32 v117, 0xf149f2ca
	s_nop 1
	v_add_u32_e32 v213, 15, v126
	v_min_u32_e32 v213, 30, v213
	v_lshl_add_u32 v218, v213, 2, s42
	ds_read_b32 v213, v218 offset:868
	s_nop 0
	s_waitcnt lgkmcnt(0)
	v_fma_f32 v212, v74, s62, v213
	v_cndmask_b32_e64 v117, v204, v212, s[68:69]
	v_or_b32_e32 v72, 3, v134
	v_cmp_ge_u32_e32 vcc, v72, v129
	v_cmp_lt_u32_e64 s[0:1], v72, v131
	v_sub_u32_e32 v72, v72, v109
	s_and_b64 s[70:71], vcc, s[0:1]
	v_max_i32_e32 v127, -15, v72
	s_nop 1
	v_add_u32_e32 v215, 15, v127
	v_min_u32_e32 v215, 30, v215
	v_lshl_add_u32 v219, v215, 2, s42
	ds_read_b32 v215, v219 offset:868
	s_nop 0
	s_waitcnt lgkmcnt(0)
	v_fma_f32 v214, v75, s62, v215
	v_cndmask_b32_e64 v116, v204, v214, s[70:71]
	v_add_u32_e32 v128, 16, v121
	v_add_u32_e32 v72, s6, v128
	v_mad_i32_i24 v119, v72, s90, v118
	ds_read_b128 v[72:75], v119
	ds_read_b128 v[136:139], v119 offset:64
	v_add_u32_e32 v120, 16, v134
	v_cmp_ge_u32_e32 vcc, v120, v129
	v_cmp_lt_u32_e64 s[0:1], v134, v129
	v_sub_u32_e32 v120, v120, v109
	s_and_b64 s[72:73], vcc, s[0:1]
	v_max_i32_e32 v130, -15, v120
	v_mov_b32_e32 v120, 0xf149f2ca
	s_waitcnt lgkmcnt(1)
	v_mfma_f32_16x16x32_bf16 v[72:75], v[72:75], v[24:27], 0
	s_waitcnt lgkmcnt(0)
	v_mfma_f32_16x16x32_bf16 v[72:75], v[136:139], v[28:31], v[72:75]
	ds_read_b128 v[136:139], v119 offset:128
	s_waitcnt lgkmcnt(0)
	v_mfma_f32_16x16x32_bf16 v[72:75], v[136:139], v[32:35], v[72:75]
	ds_read_b128 v[136:139], v119 offset:192
	v_mov_b32_e32 v119, 0xf149f2ca
	s_waitcnt lgkmcnt(0)
	v_mfma_f32_16x16x32_bf16 v[72:75], v[136:139], v[36:39], v[72:75]
	s_nop 1
	v_add_u32_e32 v201, 15, v130
	v_min_u32_e32 v201, 30, v201
	v_lshl_add_u32 v220, v201, 2, s42
	ds_read_b32 v201, v220 offset:868
	s_nop 1
	s_nop 0
	s_waitcnt lgkmcnt(0)
	v_fma_f32 v200, v72, s62, v201
	v_cndmask_b32_e64 v120, v204, v200, s[72:73]
	s_nop 4
	v_add_u32_e32 v72, 17, v134
	v_cmp_ge_u32_e32 vcc, v72, v129
	v_cmp_lt_u32_e64 s[0:1], v72, v131
	v_sub_u32_e32 v72, v72, v109
	s_and_b64 s[74:75], vcc, s[0:1]
	v_max_i32_e32 v132, -15, v72
	s_nop 1
	v_add_u32_e32 v203, 15, v132
	v_min_u32_e32 v203, 30, v203
	v_lshl_add_u32 v221, v203, 2, s42
	ds_read_b32 v203, v221 offset:868
	s_nop 0
	s_waitcnt lgkmcnt(0)
	v_fma_f32 v202, v73, s62, v203
	v_cndmask_b32_e64 v119, v204, v202, s[74:75]
	v_add_u32_e32 v72, 18, v134
	v_cmp_ge_u32_e32 vcc, v72, v129
	v_cmp_lt_u32_e64 s[0:1], v72, v131
	v_sub_u32_e32 v72, v72, v109
	s_and_b64 s[76:77], vcc, s[0:1]
	v_mov_b32_e32 v122, 0xf149f2ca
	v_max_i32_e32 v133, -15, v72
	v_mov_b32_e32 v123, 0xf149f2ca
	s_nop 1
	v_add_u32_e32 v213, 15, v133
	v_min_u32_e32 v213, 30, v213
	v_lshl_add_u32 v222, v213, 2, s42
	ds_read_b32 v213, v222 offset:868
	s_nop 0
	s_waitcnt lgkmcnt(0)
; #define LAS __attribute__((address_space(3)))
; template <int L>
; __device__ __forceinline__ void layer_body(const Args& args, LAS unsigned char* lds, const int wave, const int G, const int gw, const int NGW, const int lo, const int hi,
;                                            unsigned char* const ws_kernel, const XcdBarrier& bar, int& pid) {
;     ...
; #pragma unroll
;                     for (int t = 0; t < 16; ++t) {
;                         const int irow = (r0w - krlo + (t >> 1)) * 40 + coloff + 16 * (t & 1);
;                         const unsigned ka = IMG + (unsigned)((irow + qi) * KPITCH + 16 * kg);
;                         f32x4 a = (f32x4){0.f, 0.f, 0.f, 0.f};
; #pragma unroll
;                         for (int ks = 0; ks < 4; ++ks) a = __builtin_amdgcn_mfma_f32_16x16x32_bf16(*(const LAS bf16x8*)(size_t)(ka + 64 * ks), qfn[ks], a, 0, 0, 0);
;                         const int dr = r0w + (t >> 1) - r + 7;
; #pragma unroll
;                         for (int j = 0; j < 4; ++j) { const int kc = cs + 16 * (t & 1) + 4 * kg + j; const bool valid = (kc >= wsq) && (kc < wsq + 16); const int dc = min(max(kc - c + 15, 0), 30);
;                             sc[t][j] = valid ? a[j] * scale_log2 + rl[dr * 31 + dc] * LOG2E : -1e30f; }
;                         __builtin_amdgcn_sched_barrier(0);
;                     }
	v_fma_f32 v212, v74, s62, v213
	v_cndmask_b32_e64 v123, v204, v212, s[76:77]
	v_add_u32_e32 v72, 19, v134
	v_cmp_ge_u32_e32 vcc, v72, v129
	v_cmp_lt_u32_e64 s[0:1], v72, v131
	v_sub_u32_e32 v72, v72, v109
	s_and_b64 s[0:1], vcc, s[0:1]
	v_max_i32_e32 v134, -15, v72
	s_nop 1
	v_add_u32_e32 v215, 15, v134
	v_min_u32_e32 v215, 30, v215
	v_lshl_add_u32 v223, v215, 2, s42
	ds_read_b32 v215, v223 offset:868
	s_nop 0
	s_waitcnt lgkmcnt(0)
	v_fma_f32 v214, v75, s62, v215
	v_cndmask_b32_e64 v122, v204, v214, s[0:1]
	s_add_i32 s7, s41, 0xc8
	v_add_u32_e32 v72, s7, v121
	v_mad_i32_i24 v129, v72, s90, v118
	ds_read_b128 v[72:75], v129
	ds_read_b128 v[136:139], v129 offset:64
	v_mov_b32_e32 v131, 0xf149f2ca
	s_waitcnt lgkmcnt(1)
	v_mfma_f32_16x16x32_bf16 v[72:75], v[72:75], v[24:27], 0
	s_waitcnt lgkmcnt(0)
	v_mfma_f32_16x16x32_bf16 v[72:75], v[136:139], v[28:31], v[72:75]
	ds_read_b128 v[136:139], v129 offset:128
	s_waitcnt lgkmcnt(0)
	v_mfma_f32_16x16x32_bf16 v[72:75], v[136:139], v[32:35], v[72:75]
	ds_read_b128 v[136:139], v129 offset:192
	v_mov_b32_e32 v129, 0xf149f2ca
	s_waitcnt lgkmcnt(0)
	v_mfma_f32_16x16x32_bf16 v[72:75], v[136:139], v[36:39], v[72:75]
	ds_read_b32 v201, v216 offset:992
	ds_read_b32 v203, v217 offset:992
	ds_read_b32 v213, v218 offset:992
	ds_read_b32 v215, v219 offset:992
	s_nop 4
	s_waitcnt lgkmcnt(0)
	v_fma_f32 v200, v72, s62, v201
	v_fma_f32 v202, v73, s62, v203
	v_fma_f32 v212, v74, s62, v213
	v_fma_f32 v214, v75, s62, v215
	v_cndmask_b32_e64 v131, v204, v200, s[64:65]
	v_cndmask_b32_e64 v129, v204, v202, s[66:67]
	v_cndmask_b32_e64 v136, v204, v212, s[68:69]
	v_cndmask_b32_e64 v135, v204, v214, s[70:71]
	v_add_u32_e32 v72, s7, v128
	v_mad_i32_i24 v137, v72, s90, v118
	ds_read_b128 v[72:75], v137
	ds_read_b128 v[138:141], v137 offset:64
	s_waitcnt lgkmcnt(1)
	v_mfma_f32_16x16x32_bf16 v[72:75], v[72:75], v[24:27], 0
	s_waitcnt lgkmcnt(0)
	v_mfma_f32_16x16x32_bf16 v[72:75], v[138:141], v[28:31], v[72:75]
	ds_read_b128 v[138:141], v137 offset:128
	s_waitcnt lgkmcnt(0)
	v_mfma_f32_16x16x32_bf16 v[72:75], v[138:141], v[32:35], v[72:75]
	ds_read_b128 v[138:141], v137 offset:192
	v_mov_b32_e32 v137, 0xf149f2ca
	s_waitcnt lgkmcnt(0)
	v_mfma_f32_16x16x32_bf16 v[72:75], v[138:141], v[36:39], v[72:75]
	v_mov_b32_e32 v138, 0xf149f2ca
	ds_read_b32 v201, v220 offset:992
	ds_read_b32 v203, v221 offset:992
	ds_read_b32 v213, v222 offset:992
	ds_read_b32 v215, v223 offset:992
	s_nop 4
	s_waitcnt lgkmcnt(0)
	v_fma_f32 v200, v72, s62, v201
	v_fma_f32 v202, v73, s62, v203
	v_fma_f32 v212, v74, s62, v213
	v_fma_f32 v214, v75, s62, v215
	v_cndmask_b32_e64 v138, v204, v200, s[72:73]
	v_cndmask_b32_e64 v137, v204, v202, s[74:75]
	v_cndmask_b32_e64 v140, v204, v212, s[76:77]
	v_cndmask_b32_e64 v139, v204, v214, s[0:1]
	s_add_i32 s8, s41, 0xf0
	v_add_u32_e32 v72, s8, v121
	v_mad_i32_i24 v141, v72, s90, v118
	ds_read_b128 v[72:75], v141
	ds_read_b128 v[142:145], v141 offset:64
	s_waitcnt lgkmcnt(1)
	v_mfma_f32_16x16x32_bf16 v[72:75], v[72:75], v[24:27], 0
	s_waitcnt lgkmcnt(0)
	v_mfma_f32_16x16x32_bf16 v[72:75], v[142:145], v[28:31], v[72:75]
	ds_read_b128 v[142:145], v141 offset:128
	s_waitcnt lgkmcnt(0)
	v_mfma_f32_16x16x32_bf16 v[72:75], v[142:145], v[32:35], v[72:75]
	ds_read_b128 v[142:145], v141 offset:192
	v_mov_b32_e32 v141, 0xf149f2ca
	s_waitcnt lgkmcnt(0)
	v_mfma_f32_16x16x32_bf16 v[72:75], v[142:145], v[36:39], v[72:75]
	v_mov_b32_e32 v142, 0xf149f2ca
	ds_read_b32 v201, v216 offset:1116
	ds_read_b32 v203, v217 offset:1116
	ds_read_b32 v213, v218 offset:1116
	ds_read_b32 v215, v219 offset:1116
	s_nop 4
	s_waitcnt lgkmcnt(0)
	v_fma_f32 v200, v72, s62, v201
	v_fma_f32 v202, v73, s62, v203
	v_fma_f32 v212, v74, s62, v213
	v_fma_f32 v214, v75, s62, v215
	v_cndmask_b32_e64 v142, v204, v200, s[64:65]
	v_cndmask_b32_e64 v141, v204, v202, s[66:67]
	v_cndmask_b32_e64 v144, v204, v212, s[68:69]
	v_cndmask_b32_e64 v143, v204, v214, s[70:71]
	v_add_u32_e32 v72, s8, v128
	v_mad_i32_i24 v145, v72, s90, v118
	ds_read_b128 v[72:75], v145
	ds_read_b128 v[146:149], v145 offset:64
	s_waitcnt lgkmcnt(1)
	v_mfma_f32_16x16x32_bf16 v[72:75], v[72:75], v[24:27], 0
	s_waitcnt lgkmcnt(0)
	v_mfma_f32_16x16x32_bf16 v[72:75], v[146:149], v[28:31], v[72:75]
	ds_read_b128 v[146:149], v145 offset:128
	s_waitcnt lgkmcnt(0)
	v_mfma_f32_16x16x32_bf16 v[72:75], v[146:149], v[32:35], v[72:75]
	ds_read_b128 v[146:149], v145 offset:192
	v_mov_b32_e32 v145, 0xf149f2ca
	s_waitcnt lgkmcnt(0)
	v_mfma_f32_16x16x32_bf16 v[72:75], v[146:149], v[36:39], v[72:75]
	v_mov_b32_e32 v146, 0xf149f2ca
	ds_read_b32 v201, v220 offset:1116
	ds_read_b32 v203, v221 offset:1116
	ds_read_b32 v213, v222 offset:1116
	ds_read_b32 v215, v223 offset:1116
	s_nop 4
	s_waitcnt lgkmcnt(0)
	v_fma_f32 v200, v72, s62, v201
	v_fma_f32 v202, v73, s62, v203
	v_fma_f32 v212, v74, s62, v213
	v_fma_f32 v214, v75, s62, v215
	v_cndmask_b32_e64 v146, v204, v200, s[72:73]
	v_cndmask_b32_e64 v145, v204, v202, s[74:75]
	v_cndmask_b32_e64 v148, v204, v212, s[76:77]
	v_cndmask_b32_e64 v147, v204, v214, s[0:1]
	s_add_i32 s37, s41, 0x118
	v_add_u32_e32 v72, s37, v121
	v_mad_i32_i24 v149, v72, s90, v118
	ds_read_b128 v[72:75], v149
	ds_read_b128 v[150:153], v149 offset:64
	s_waitcnt lgkmcnt(1)
	v_mfma_f32_16x16x32_bf16 v[72:75], v[72:75], v[24:27], 0
	s_waitcnt lgkmcnt(0)
	v_mfma_f32_16x16x32_bf16 v[72:75], v[150:153], v[28:31], v[72:75]
	ds_read_b128 v[150:153], v149 offset:128
	s_waitcnt lgkmcnt(0)
	v_mfma_f32_16x16x32_bf16 v[72:75], v[150:153], v[32:35], v[72:75]
	ds_read_b128 v[150:153], v149 offset:192
	v_mov_b32_e32 v149, 0xf149f2ca
	s_waitcnt lgkmcnt(0)
; #define LAS __attribute__((address_space(3)))
; template <int L>
; __device__ __forceinline__ void layer_body(const Args& args, LAS unsigned char* lds, const int wave, const int G, const int gw, const int NGW, const int lo, const int hi,
;                                            unsigned char* const ws_kernel, const XcdBarrier& bar, int& pid) {
;     ...
; #pragma unroll
;                     for (int t = 0; t < 16; ++t) {
;                         const int irow = (r0w - krlo + (t >> 1)) * 40 + coloff + 16 * (t & 1);
;                         const unsigned ka = IMG + (unsigned)((irow + qi) * KPITCH + 16 * kg);
;                         f32x4 a = (f32x4){0.f, 0.f, 0.f, 0.f};
; #pragma unroll
;                         for (int ks = 0; ks < 4; ++ks) a = __builtin_amdgcn_mfma_f32_16x16x32_bf16(*(const LAS bf16x8*)(size_t)(ka + 64 * ks), qfn[ks], a, 0, 0, 0);
;                         const int dr = r0w + (t >> 1) - r + 7;
; #pragma unroll
;                         for (int j = 0; j < 4; ++j) { const int kc = cs + 16 * (t & 1) + 4 * kg + j; const bool valid = (kc >= wsq) && (kc < wsq + 16); const int dc = min(max(kc - c + 15, 0), 30);
;                             sc[t][j] = valid ? a[j] * scale_log2 + rl[dr * 31 + dc] * LOG2E : -1e30f; }
;                         __builtin_amdgcn_sched_barrier(0);
;                     }
	v_mfma_f32_16x16x32_bf16 v[72:75], v[150:153], v[36:39], v[72:75]
	v_mov_b32_e32 v150, 0xf149f2ca
	ds_read_b32 v201, v216 offset:1240
	ds_read_b32 v203, v217 offset:1240
	ds_read_b32 v213, v218 offset:1240
	ds_read_b32 v215, v219 offset:1240
	s_nop 4
	s_waitcnt lgkmcnt(0)
	v_fma_f32 v200, v72, s62, v201
	v_fma_f32 v202, v73, s62, v203
	v_fma_f32 v212, v74, s62, v213
	v_fma_f32 v214, v75, s62, v215
	v_cndmask_b32_e64 v150, v204, v200, s[64:65]
	v_cndmask_b32_e64 v149, v204, v202, s[66:67]
	v_cndmask_b32_e64 v152, v204, v212, s[68:69]
	v_cndmask_b32_e64 v151, v204, v214, s[70:71]
	v_add_u32_e32 v72, s37, v128
	v_mad_i32_i24 v153, v72, s90, v118
	ds_read_b128 v[72:75], v153
	ds_read_b128 v[154:157], v153 offset:64
	s_waitcnt lgkmcnt(1)
	v_mfma_f32_16x16x32_bf16 v[72:75], v[72:75], v[24:27], 0
	s_waitcnt lgkmcnt(0)
	v_mfma_f32_16x16x32_bf16 v[72:75], v[154:157], v[28:31], v[72:75]
	ds_read_b128 v[154:157], v153 offset:128
	s_waitcnt lgkmcnt(0)
	v_mfma_f32_16x16x32_bf16 v[72:75], v[154:157], v[32:35], v[72:75]
	ds_read_b128 v[154:157], v153 offset:192
	v_mov_b32_e32 v153, 0xf149f2ca
	s_waitcnt lgkmcnt(0)
	v_mfma_f32_16x16x32_bf16 v[72:75], v[154:157], v[36:39], v[72:75]
	v_mov_b32_e32 v154, 0xf149f2ca
	ds_read_b32 v201, v220 offset:1240
	ds_read_b32 v203, v221 offset:1240
	ds_read_b32 v213, v222 offset:1240
	ds_read_b32 v215, v223 offset:1240
	s_nop 4
	s_waitcnt lgkmcnt(0)
	v_fma_f32 v200, v72, s62, v201
	v_fma_f32 v202, v73, s62, v203
	v_fma_f32 v212, v74, s62, v213
	v_fma_f32 v214, v75, s62, v215
	v_cndmask_b32_e64 v154, v204, v200, s[72:73]
	v_cndmask_b32_e64 v153, v204, v202, s[74:75]
	v_cndmask_b32_e64 v156, v204, v212, s[76:77]
	v_cndmask_b32_e64 v155, v204, v214, s[0:1]
	s_add_i32 s38, s41, 0x140
	v_add_u32_e32 v72, s38, v121
	v_mad_i32_i24 v157, v72, s90, v118
	ds_read_b128 v[72:75], v157
	ds_read_b128 v[158:161], v157 offset:64
	s_waitcnt lgkmcnt(1)
	v_mfma_f32_16x16x32_bf16 v[72:75], v[72:75], v[24:27], 0
	s_waitcnt lgkmcnt(0)
	v_mfma_f32_16x16x32_bf16 v[72:75], v[158:161], v[28:31], v[72:75]
	ds_read_b128 v[158:161], v157 offset:128
	s_waitcnt lgkmcnt(0)
	v_mfma_f32_16x16x32_bf16 v[72:75], v[158:161], v[32:35], v[72:75]
	ds_read_b128 v[158:161], v157 offset:192
	v_mov_b32_e32 v157, 0xf149f2ca
	s_waitcnt lgkmcnt(0)
	v_mfma_f32_16x16x32_bf16 v[72:75], v[158:161], v[36:39], v[72:75]
	v_mov_b32_e32 v158, 0xf149f2ca
	ds_read_b32 v201, v216 offset:1364
	ds_read_b32 v203, v217 offset:1364
	ds_read_b32 v213, v218 offset:1364
	ds_read_b32 v215, v219 offset:1364
	s_nop 4
	s_waitcnt lgkmcnt(0)
	v_fma_f32 v200, v72, s62, v201
	v_fma_f32 v202, v73, s62, v203
	v_fma_f32 v212, v74, s62, v213
	v_fma_f32 v214, v75, s62, v215
	v_cndmask_b32_e64 v158, v204, v200, s[64:65]
	v_cndmask_b32_e64 v157, v204, v202, s[66:67]
	v_cndmask_b32_e64 v160, v204, v212, s[68:69]
	v_cndmask_b32_e64 v159, v204, v214, s[70:71]
	v_add_u32_e32 v72, s38, v128
	v_mad_i32_i24 v161, v72, s90, v118
	ds_read_b128 v[72:75], v161
	ds_read_b128 v[162:165], v161 offset:64
	s_waitcnt lgkmcnt(1)
	v_mfma_f32_16x16x32_bf16 v[72:75], v[72:75], v[24:27], 0
	s_waitcnt lgkmcnt(0)
	v_mfma_f32_16x16x32_bf16 v[72:75], v[162:165], v[28:31], v[72:75]
	ds_read_b128 v[162:165], v161 offset:128
	s_waitcnt lgkmcnt(0)
	v_mfma_f32_16x16x32_bf16 v[72:75], v[162:165], v[32:35], v[72:75]
	ds_read_b128 v[162:165], v161 offset:192
	v_mov_b32_e32 v161, 0xf149f2ca
	s_waitcnt lgkmcnt(0)
	v_mfma_f32_16x16x32_bf16 v[72:75], v[162:165], v[36:39], v[72:75]
	v_mov_b32_e32 v162, 0xf149f2ca
	ds_read_b32 v201, v220 offset:1364
	ds_read_b32 v203, v221 offset:1364
	ds_read_b32 v213, v222 offset:1364
	ds_read_b32 v215, v223 offset:1364
	s_nop 4
	s_waitcnt lgkmcnt(0)
	v_fma_f32 v200, v72, s62, v201
	v_fma_f32 v202, v73, s62, v203
	v_fma_f32 v212, v74, s62, v213
	v_fma_f32 v214, v75, s62, v215
	v_cndmask_b32_e64 v162, v204, v200, s[72:73]
	v_cndmask_b32_e64 v161, v204, v202, s[74:75]
	v_cndmask_b32_e64 v164, v204, v212, s[76:77]
	v_cndmask_b32_e64 v163, v204, v214, s[0:1]
	s_add_i32 s39, s41, 0x168
	v_add_u32_e32 v72, s39, v121
	v_mad_i32_i24 v165, v72, s90, v118
	ds_read_b128 v[72:75], v165
	ds_read_b128 v[166:169], v165 offset:64
	s_waitcnt lgkmcnt(1)
	v_mfma_f32_16x16x32_bf16 v[72:75], v[72:75], v[24:27], 0
	s_waitcnt lgkmcnt(0)
	v_mfma_f32_16x16x32_bf16 v[72:75], v[166:169], v[28:31], v[72:75]
	ds_read_b128 v[166:169], v165 offset:128
	s_waitcnt lgkmcnt(0)
	v_mfma_f32_16x16x32_bf16 v[72:75], v[166:169], v[32:35], v[72:75]
	ds_read_b128 v[166:169], v165 offset:192
	v_mov_b32_e32 v165, 0xf149f2ca
	s_waitcnt lgkmcnt(0)
	v_mfma_f32_16x16x32_bf16 v[72:75], v[166:169], v[36:39], v[72:75]
	v_mov_b32_e32 v166, 0xf149f2ca
	ds_read_b32 v201, v216 offset:1488
	ds_read_b32 v203, v217 offset:1488
	ds_read_b32 v213, v218 offset:1488
	ds_read_b32 v215, v219 offset:1488
	s_nop 4
	s_waitcnt lgkmcnt(0)
	v_fma_f32 v200, v72, s62, v201
	v_fma_f32 v202, v73, s62, v203
	v_fma_f32 v212, v74, s62, v213
	v_fma_f32 v214, v75, s62, v215
	v_cndmask_b32_e64 v166, v204, v200, s[64:65]
	v_cndmask_b32_e64 v165, v204, v202, s[66:67]
	v_cndmask_b32_e64 v168, v204, v212, s[68:69]
	v_cndmask_b32_e64 v167, v204, v214, s[70:71]
	v_add_u32_e32 v72, s39, v128
	v_mad_i32_i24 v169, v72, s90, v118
	ds_read_b128 v[72:75], v169
	ds_read_b128 v[170:173], v169 offset:64
	s_waitcnt lgkmcnt(1)
	v_mfma_f32_16x16x32_bf16 v[72:75], v[72:75], v[24:27], 0
	s_waitcnt lgkmcnt(0)
	v_mfma_f32_16x16x32_bf16 v[72:75], v[170:173], v[28:31], v[72:75]
	ds_read_b128 v[170:173], v169 offset:128
	s_waitcnt lgkmcnt(0)
	v_mfma_f32_16x16x32_bf16 v[72:75], v[170:173], v[32:35], v[72:75]
	ds_read_b128 v[170:173], v169 offset:192
	v_mov_b32_e32 v169, 0xf149f2ca
	s_waitcnt lgkmcnt(0)
; #define LAS __attribute__((address_space(3)))
; template <int L>
; __device__ __forceinline__ void layer_body(const Args& args, LAS unsigned char* lds, const int wave, const int G, const int gw, const int NGW, const int lo, const int hi,
;                                            unsigned char* const ws_kernel, const XcdBarrier& bar, int& pid) {
;     ...
; #pragma unroll
;                     for (int t = 0; t < 16; ++t) {
;                         const int irow = (r0w - krlo + (t >> 1)) * 40 + coloff + 16 * (t & 1);
;                         const unsigned ka = IMG + (unsigned)((irow + qi) * KPITCH + 16 * kg);
;                         f32x4 a = (f32x4){0.f, 0.f, 0.f, 0.f};
; #pragma unroll
;                         for (int ks = 0; ks < 4; ++ks) a = __builtin_amdgcn_mfma_f32_16x16x32_bf16(*(const LAS bf16x8*)(size_t)(ka + 64 * ks), qfn[ks], a, 0, 0, 0);
;                         const int dr = r0w + (t >> 1) - r + 7;
; #pragma unroll
;                         for (int j = 0; j < 4; ++j) { const int kc = cs + 16 * (t & 1) + 4 * kg + j; const bool valid = (kc >= wsq) && (kc < wsq + 16); const int dc = min(max(kc - c + 15, 0), 30);
;                             sc[t][j] = valid ? a[j] * scale_log2 + rl[dr * 31 + dc] * LOG2E : -1e30f; }
;                         __builtin_amdgcn_sched_barrier(0);
;                     }
;                     float mx = -1e30f;
; #pragma unroll
;                     for (int t = 0; t < 16; ++t)
; #pragma unroll
;                         for (int j = 0; j < 4; ++j) mx = fmaxf(mx, sc[t][j]);
;                     mx = fmaxf(mx, __shfl_xor(mx, 16)); mx = fmaxf(mx, __shfl_xor(mx, 32));
	v_mfma_f32_16x16x32_bf16 v[72:75], v[170:173], v[36:39], v[72:75]
	v_mov_b32_e32 v170, 0xf149f2ca
	ds_read_b32 v201, v220 offset:1488
	ds_read_b32 v203, v221 offset:1488
	ds_read_b32 v213, v222 offset:1488
	ds_read_b32 v215, v223 offset:1488
	s_nop 4
	s_waitcnt lgkmcnt(0)
	v_fma_f32 v200, v72, s62, v201
	v_fma_f32 v202, v73, s62, v203
	v_fma_f32 v212, v74, s62, v213
	v_fma_f32 v214, v75, s62, v215
	v_cndmask_b32_e64 v170, v204, v200, s[72:73]
	v_cndmask_b32_e64 v169, v204, v202, s[74:75]
	v_cndmask_b32_e64 v172, v204, v212, s[76:77]
	v_cndmask_b32_e64 v171, v204, v214, s[0:1]
	s_add_i32 s40, s41, 0x190
	v_add_u32_e32 v72, s40, v121
	v_mad_i32_i24 v173, v72, s90, v118
	ds_read_b128 v[72:75], v173
	ds_read_b128 v[174:177], v173 offset:64
	s_waitcnt lgkmcnt(1)
	v_mfma_f32_16x16x32_bf16 v[72:75], v[72:75], v[24:27], 0
	s_waitcnt lgkmcnt(0)
	v_mfma_f32_16x16x32_bf16 v[72:75], v[174:177], v[28:31], v[72:75]
	ds_read_b128 v[174:177], v173 offset:128
	s_waitcnt lgkmcnt(0)
	v_mfma_f32_16x16x32_bf16 v[72:75], v[174:177], v[32:35], v[72:75]
	ds_read_b128 v[174:177], v173 offset:192
	v_mov_b32_e32 v173, 0xf149f2ca
	s_waitcnt lgkmcnt(0)
	v_mfma_f32_16x16x32_bf16 v[72:75], v[174:177], v[36:39], v[72:75]
	v_mov_b32_e32 v174, 0xf149f2ca
	ds_read_b32 v201, v216 offset:1612
	ds_read_b32 v203, v217 offset:1612
	ds_read_b32 v213, v218 offset:1612
	ds_read_b32 v215, v219 offset:1612
	s_nop 4
	s_waitcnt lgkmcnt(0)
	v_fma_f32 v200, v72, s62, v201
	v_fma_f32 v202, v73, s62, v203
	v_fma_f32 v212, v74, s62, v213
	v_fma_f32 v214, v75, s62, v215
	v_cndmask_b32_e64 v174, v204, v200, s[64:65]
	v_cndmask_b32_e64 v173, v204, v202, s[66:67]
	v_cndmask_b32_e64 v176, v204, v212, s[68:69]
	v_cndmask_b32_e64 v175, v204, v214, s[70:71]
	v_add_u32_e32 v72, s40, v128
	v_mad_i32_i24 v177, v72, s90, v118
	ds_read_b128 v[72:75], v177
	ds_read_b128 v[178:181], v177 offset:64
	s_waitcnt lgkmcnt(1)
	v_mfma_f32_16x16x32_bf16 v[72:75], v[72:75], v[24:27], 0
	s_waitcnt lgkmcnt(0)
	v_mfma_f32_16x16x32_bf16 v[72:75], v[178:181], v[28:31], v[72:75]
	ds_read_b128 v[178:181], v177 offset:128
	s_waitcnt lgkmcnt(0)
	v_mfma_f32_16x16x32_bf16 v[72:75], v[178:181], v[32:35], v[72:75]
	ds_read_b128 v[178:181], v177 offset:192
	v_mov_b32_e32 v177, 0xf149f2ca
	s_waitcnt lgkmcnt(0)
	v_mfma_f32_16x16x32_bf16 v[72:75], v[178:181], v[36:39], v[72:75]
	v_mov_b32_e32 v178, 0xf149f2ca
	ds_read_b32 v201, v220 offset:1612
	ds_read_b32 v203, v221 offset:1612
	ds_read_b32 v213, v222 offset:1612
	ds_read_b32 v215, v223 offset:1612
	s_nop 4
	s_waitcnt lgkmcnt(0)
	v_fma_f32 v200, v72, s62, v201
	v_fma_f32 v202, v73, s62, v203
	v_fma_f32 v212, v74, s62, v213
	v_fma_f32 v214, v75, s62, v215
	v_cndmask_b32_e64 v178, v204, v200, s[72:73]
	v_cndmask_b32_e64 v177, v204, v202, s[74:75]
	v_cndmask_b32_e64 v191, v204, v212, s[76:77]
	v_cndmask_b32_e64 v188, v204, v214, s[0:1]
	s_addk_i32 s41, 0x1b8
	v_add_u32_e32 v72, s41, v121
	v_mad_i32_i24 v121, v72, s90, v118
	ds_read_b128 v[72:75], v121
	ds_read_b128 v[180:183], v121 offset:64
	v_mov_b32_e32 v205, 0xf149f2ca
	s_waitcnt lgkmcnt(1)
	v_mfma_f32_16x16x32_bf16 v[72:75], v[72:75], v[24:27], 0
	s_waitcnt lgkmcnt(0)
	v_mfma_f32_16x16x32_bf16 v[72:75], v[180:183], v[28:31], v[72:75]
	ds_read_b128 v[180:183], v121 offset:128
	s_waitcnt lgkmcnt(0)
	v_mfma_f32_16x16x32_bf16 v[72:75], v[180:183], v[32:35], v[72:75]
	ds_read_b128 v[180:183], v121 offset:192
	v_mov_b32_e32 v121, 0xf149f2ca
	s_waitcnt lgkmcnt(0)
	v_mfma_f32_16x16x32_bf16 v[72:75], v[180:183], v[36:39], v[72:75]
	ds_read_b32 v201, v216 offset:1736
	ds_read_b32 v203, v217 offset:1736
	ds_read_b32 v213, v218 offset:1736
	ds_read_b32 v215, v219 offset:1736
	s_nop 4
	s_waitcnt lgkmcnt(0)
	v_fma_f32 v200, v72, s62, v201
	v_fma_f32 v202, v73, s62, v203
	v_fma_f32 v212, v74, s62, v213
	v_fma_f32 v214, v75, s62, v215
	v_cndmask_b32_e64 v205, v204, v200, s[64:65]
	v_cndmask_b32_e64 v121, v204, v202, s[66:67]
	v_cndmask_b32_e64 v207, v204, v212, s[68:69]
	v_cndmask_b32_e64 v206, v204, v214, s[70:71]
	v_add_u32_e32 v72, s41, v128
	v_mad_i32_i24 v118, v72, s90, v118
	ds_read_b128 v[72:75], v118
	ds_read_b128 v[124:127], v118 offset:64
	v_mov_b32_e32 v208, 0xf149f2ca
	v_mov_b32_e32 v209, 0xf149f2ca
	s_waitcnt lgkmcnt(1)
	v_mfma_f32_16x16x32_bf16 v[72:75], v[72:75], v[24:27], 0
	s_waitcnt lgkmcnt(0)
	v_mfma_f32_16x16x32_bf16 v[72:75], v[124:127], v[28:31], v[72:75]
	ds_read_b128 v[124:127], v118 offset:128
	s_waitcnt lgkmcnt(0)
	v_mfma_f32_16x16x32_bf16 v[72:75], v[124:127], v[32:35], v[72:75]
	ds_read_b128 v[124:127], v118 offset:192
	s_waitcnt lgkmcnt(0)
	v_mfma_f32_16x16x32_bf16 v[72:75], v[124:127], v[36:39], v[72:75]
	ds_read_b32 v201, v220 offset:1736
	ds_read_b32 v203, v221 offset:1736
	ds_read_b32 v213, v222 offset:1736
	ds_read_b32 v215, v223 offset:1736
	s_nop 4
	s_waitcnt lgkmcnt(0)
	v_fma_f32 v200, v72, s62, v201
	v_fma_f32 v202, v73, s62, v203
	v_fma_f32 v212, v74, s62, v213
	v_fma_f32 v214, v75, s62, v215
	v_cndmask_b32_e64 v209, v204, v200, s[72:73]
	v_cndmask_b32_e64 v208, v204, v202, s[74:75]
	v_cndmask_b32_e64 v211, v204, v212, s[76:77]
	v_cndmask_b32_e64 v210, v204, v214, s[0:1]
	s_lshl_b32 s36, s36, 7
	s_mov_b32 s0, 0xf149f2ca
	v_max3_f32 v72, v115, s0, v104
	v_max3_f32 v72, v72, v117, v116
	v_max3_f32 v72, v72, v120, v119
	v_max3_f32 v72, v72, v123, v122
	v_max3_f32 v72, v72, v131, v129
	v_max3_f32 v72, v72, v136, v135
	v_max3_f32 v72, v72, v138, v137
	v_max3_f32 v72, v72, v140, v139
	v_max3_f32 v72, v72, v142, v141
	v_max3_f32 v72, v72, v144, v143
	v_max3_f32 v72, v72, v146, v145
	v_max3_f32 v72, v72, v148, v147
	v_max3_f32 v72, v72, v150, v149
	v_max3_f32 v72, v72, v152, v151
	v_max3_f32 v72, v72, v154, v153
	v_max3_f32 v72, v72, v156, v155
	v_max3_f32 v72, v72, v158, v157
	v_max3_f32 v72, v72, v160, v159
	v_max3_f32 v72, v72, v162, v161
	v_max3_f32 v72, v72, v164, v163
	v_max3_f32 v72, v72, v166, v165
	v_max3_f32 v72, v72, v168, v167
	v_max3_f32 v72, v72, v170, v169
	v_max3_f32 v72, v72, v172, v171
	v_max3_f32 v72, v72, v174, v173
	v_max3_f32 v72, v72, v176, v175
	v_max3_f32 v72, v72, v178, v177
	v_max3_f32 v72, v72, v191, v188
	v_and_b32_e32 v74, 64, v107
	v_max3_f32 v72, v72, v205, v121
	v_xor_b32_e32 v73, 16, v107
	v_add_u32_e32 v74, 64, v74
	v_max3_f32 v72, v72, v207, v206
	v_cmp_lt_i32_e32 vcc, v73, v74
	v_max3_f32 v72, v72, v209, v208
	v_max3_f32 v72, v72, v211, v210
	v_cndmask_b32_e32 v73, v107, v73, vcc
	v_lshlrev_b32_e32 v212, 2, v73
	ds_bpermute_b32 v73, v212, v72
	s_waitcnt lgkmcnt(0)
	s_barrier
; template <int L>
; __device__ __forceinline__ void layer_body(const Args& args, LAS unsigned char* lds, const int wave, const int G, const int gw, const int NGW, const int lo, const int hi,
;                                            unsigned char* const ws_kernel, const XcdBarrier& bar, int& pid) {
;     ...
;                     float mx = -1e30f;
; #pragma unroll
;                     for (int t = 0; t < 16; ++t)
; #pragma unroll
;                         for (int j = 0; j < 4; ++j) mx = fmaxf(mx, sc[t][j]);
;                     mx = fmaxf(mx, __shfl_xor(mx, 16)); mx = fmaxf(mx, __shfl_xor(mx, 32));
;                     float sum = 0.f;
; #pragma unroll
;                     for (int t = 0; t < 16; ++t)
; #pragma unroll
;                         for (int j = 0; j < 4; ++j) { sc[t][j] = __builtin_amdgcn_exp2f(sc[t][j] - mx); sum += sc[t][j]; }
;                     sum += __shfl_xor(sum, 16); sum += __shfl_xor(sum, 32);
	s_add_i32 s21, s21, s86
	v_max_f32_e32 v73, v73, v73
	v_max_f32_e32 v72, v72, v73
	v_xor_b32_e32 v73, 32, v107
	v_cmp_lt_i32_e32 vcc, v73, v74
	s_cmp_ge_i32 s21, s52
	s_cselect_b64 s[0:1], -1, 0
	v_cndmask_b32_e32 v73, v107, v73, vcc
	v_lshlrev_b32_e32 v213, 2, v73
	ds_bpermute_b32 v73, v213, v72
	s_and_b64 vcc, exec, s[0:1]
	s_waitcnt lgkmcnt(0)
	v_max_f32_e32 v73, v73, v73
	v_max_f32_e32 v214, v72, v73
	v_sub_f32_e32 v72, v115, v214
	v_exp_f32_e32 v192, v72
	v_sub_f32_e32 v72, v104, v214
	v_exp_f32_e32 v200, v72
	v_sub_f32_e32 v72, v117, v214
	v_exp_f32_e32 v196, v72
	v_sub_f32_e32 v72, v116, v214
	v_exp_f32_e32 v202, v72
	v_sub_f32_e32 v72, v120, v214
	v_sub_f32_e32 v104, v208, v214
	v_exp_f32_e32 v198, v72
	v_sub_f32_e32 v72, v119, v214
	v_exp_f32_e32 v119, v104
	v_sub_f32_e32 v104, v211, v214
	v_exp_f32_e32 v116, v104
	v_sub_f32_e32 v104, v210, v214
	v_sub_f32_e32 v73, v121, v214
	v_exp_f32_e32 v121, v104
	v_add_f32_e32 v104, 0, v192
	v_exp_f32_e32 v203, v72
	v_sub_f32_e32 v72, v123, v214
	v_add_f32_e32 v104, v200, v104
	v_exp_f32_e32 v201, v72
	v_sub_f32_e32 v72, v122, v214
	v_add_f32_e32 v104, v196, v104
	v_exp_f32_e32 v204, v72
	v_sub_f32_e32 v72, v131, v214
	v_add_f32_e32 v104, v202, v104
	v_exp_f32_e32 v182, v72
	v_sub_f32_e32 v72, v129, v214
	v_add_f32_e32 v104, v198, v104
	v_exp_f32_e32 v193, v72
	v_sub_f32_e32 v72, v136, v214
	v_add_f32_e32 v104, v203, v104
	v_exp_f32_e32 v186, v72
	v_sub_f32_e32 v72, v135, v214
	v_add_f32_e32 v104, v201, v104
	v_exp_f32_e32 v195, v72
	v_sub_f32_e32 v72, v138, v214
	v_add_f32_e32 v104, v204, v104
	v_exp_f32_e32 v189, v72
	v_sub_f32_e32 v72, v137, v214
	v_add_f32_e32 v104, v182, v104
	v_exp_f32_e32 v197, v72
	v_sub_f32_e32 v72, v140, v214
	v_add_f32_e32 v104, v193, v104
	v_exp_f32_e32 v194, v72
	v_sub_f32_e32 v72, v139, v214
	v_add_f32_e32 v104, v186, v104
	v_exp_f32_e32 v199, v72
	v_sub_f32_e32 v72, v142, v214
	v_add_f32_e32 v104, v195, v104
	v_exp_f32_e32 v179, v72
	v_sub_f32_e32 v72, v141, v214
	v_add_f32_e32 v104, v189, v104
	v_exp_f32_e32 v183, v72
	v_sub_f32_e32 v72, v144, v214
	v_add_f32_e32 v104, v197, v104
	v_exp_f32_e32 v180, v72
	v_sub_f32_e32 v72, v143, v214
	v_add_f32_e32 v104, v194, v104
	v_exp_f32_e32 v185, v72
	v_sub_f32_e32 v72, v146, v214
	v_add_f32_e32 v104, v199, v104
	v_exp_f32_e32 v181, v72
	v_sub_f32_e32 v72, v145, v214
	v_add_f32_e32 v104, v179, v104
	v_exp_f32_e32 v187, v72
	v_sub_f32_e32 v72, v148, v214
	v_add_f32_e32 v104, v183, v104
	v_exp_f32_e32 v184, v72
	v_sub_f32_e32 v72, v147, v214
	v_add_f32_e32 v104, v180, v104
	v_exp_f32_e32 v190, v72
	v_sub_f32_e32 v72, v150, v214
	v_add_f32_e32 v104, v185, v104
	v_exp_f32_e32 v138, v72
	v_sub_f32_e32 v72, v149, v214
	v_add_f32_e32 v104, v181, v104
	v_exp_f32_e32 v146, v72
	v_sub_f32_e32 v72, v152, v214
	v_add_f32_e32 v104, v187, v104
	v_exp_f32_e32 v142, v72
	v_sub_f32_e32 v72, v151, v214
	v_add_f32_e32 v104, v184, v104
	v_exp_f32_e32 v148, v72
	v_sub_f32_e32 v72, v154, v214
	v_add_f32_e32 v104, v190, v104
	v_exp_f32_e32 v144, v72
	v_sub_f32_e32 v72, v153, v214
	v_add_f32_e32 v104, v138, v104
	v_exp_f32_e32 v150, v72
	v_sub_f32_e32 v72, v156, v214
	v_add_f32_e32 v104, v146, v104
	v_exp_f32_e32 v147, v72
	v_sub_f32_e32 v72, v155, v214
	v_add_f32_e32 v104, v142, v104
	v_exp_f32_e32 v152, v72
	v_sub_f32_e32 v72, v158, v214
	v_add_f32_e32 v104, v148, v104
	v_exp_f32_e32 v130, v72
	v_sub_f32_e32 v72, v157, v214
	v_add_f32_e32 v104, v144, v104
	v_exp_f32_e32 v139, v72
	v_sub_f32_e32 v72, v160, v214
	v_add_f32_e32 v104, v150, v104
	v_exp_f32_e32 v134, v72
	v_sub_f32_e32 v72, v159, v214
	v_add_f32_e32 v104, v147, v104
	v_exp_f32_e32 v141, v72
	v_sub_f32_e32 v72, v162, v214
	v_add_f32_e32 v104, v152, v104
	v_exp_f32_e32 v136, v72
	v_sub_f32_e32 v72, v161, v214
	v_add_f32_e32 v104, v130, v104
	v_exp_f32_e32 v143, v72
	v_sub_f32_e32 v72, v164, v214
	v_add_f32_e32 v104, v139, v104
	v_exp_f32_e32 v140, v72
	v_sub_f32_e32 v72, v163, v214
	v_add_f32_e32 v104, v134, v104
	v_exp_f32_e32 v145, v72
	v_sub_f32_e32 v72, v166, v214
	v_add_f32_e32 v104, v141, v104
	v_exp_f32_e32 v122, v72
	v_sub_f32_e32 v72, v165, v214
	v_add_f32_e32 v104, v136, v104
	v_exp_f32_e32 v131, v72
	v_sub_f32_e32 v72, v168, v214
	v_add_f32_e32 v104, v143, v104
	v_exp_f32_e32 v126, v72
	v_sub_f32_e32 v72, v167, v214
	v_add_f32_e32 v104, v140, v104
	v_exp_f32_e32 v133, v72
	v_sub_f32_e32 v72, v170, v214
	v_add_f32_e32 v104, v145, v104
	v_exp_f32_e32 v128, v72
	v_sub_f32_e32 v72, v169, v214
	v_add_f32_e32 v104, v122, v104
	v_exp_f32_e32 v135, v72
	v_sub_f32_e32 v72, v172, v214
	v_add_f32_e32 v104, v131, v104
	v_exp_f32_e32 v132, v72
	v_sub_f32_e32 v72, v171, v214
	v_add_f32_e32 v104, v126, v104
	v_exp_f32_e32 v137, v72
	v_sub_f32_e32 v72, v174, v214
	v_add_f32_e32 v104, v133, v104
	v_exp_f32_e32 v75, v72
	v_sub_f32_e32 v72, v173, v214
	v_add_f32_e32 v104, v128, v104
	v_exp_f32_e32 v123, v72
	v_sub_f32_e32 v72, v176, v214
	v_add_f32_e32 v104, v135, v104
	v_exp_f32_e32 v118, v72
	v_sub_f32_e32 v72, v175, v214
	v_add_f32_e32 v104, v132, v104
	v_exp_f32_e32 v125, v72
	v_sub_f32_e32 v72, v178, v214
	v_add_f32_e32 v104, v137, v104
	v_exp_f32_e32 v120, v72
	v_sub_f32_e32 v72, v177, v214
	v_add_f32_e32 v104, v75, v104
	v_exp_f32_e32 v127, v72
	v_sub_f32_e32 v72, v191, v214
	v_add_f32_e32 v104, v123, v104
	v_exp_f32_e32 v124, v72
	v_sub_f32_e32 v72, v188, v214
	v_add_f32_e32 v104, v118, v104
	v_exp_f32_e32 v129, v72
	v_sub_f32_e32 v72, v205, v214
	v_add_f32_e32 v104, v125, v104
	v_exp_f32_e32 v72, v72
	v_add_f32_e32 v104, v120, v104
	v_exp_f32_e32 v115, v73
	v_sub_f32_e32 v73, v207, v214
	v_add_f32_e32 v104, v127, v104
	v_exp_f32_e32 v73, v73
	v_sub_f32_e32 v74, v206, v214
	v_add_f32_e32 v104, v124, v104
	v_exp_f32_e32 v117, v74
	v_sub_f32_e32 v74, v209, v214
	v_add_f32_e32 v104, v129, v104
	v_exp_f32_e32 v74, v74
	v_add_f32_e32 v104, v72, v104
	v_add_f32_e32 v104, v115, v104
	v_add_f32_e32 v104, v73, v104
	v_add_f32_e32 v104, v117, v104
	v_add_f32_e32 v104, v74, v104
	v_add_f32_e32 v104, v119, v104
	v_add_f32_e32 v104, v116, v104
	v_add_f32_e32 v104, v121, v104
	ds_bpermute_b32 v149, v212, v104
	v_lshlrev_b32_e32 v153, 2, v77
	v_and_b32_e32 v153, 12, v153
	s_waitcnt lgkmcnt(0)
; #define LAS __attribute__((address_space(3)))
; __device__ __forceinline__ unsigned pk2(float lo, float hi) { return f2bf(lo) | (f2bf(hi) << 16); }
; template <int L>
; __device__ __forceinline__ void layer_body(const Args& args, LAS unsigned char* lds, const int wave, const int G, const int gw, const int NGW, const int lo, const int hi,
;                                            unsigned char* const ws_kernel, const XcdBarrier& bar, int& pid) {
;     ...
;                     sum += __shfl_xor(sum, 16); sum += __shfl_xor(sum, 32);
;                     bf16x8 pbf[8];
; #pragma unroll
;                     for (int s = 0; s < 8; ++s) { const f32x4 p0 = sc[2 * s], p1 = sc[2 * s + 1]; v4u w; w.x = pk2(p0[0], p0[1]); w.y = pk2(p0[2], p0[3]); w.z = pk2(p1[0], p1[1]); w.w = pk2(p1[2], p1[3]); pbf[s] = __builtin_bit_cast(bf16x8, w); }
;                     __syncthreads();
; #pragma unroll
;                     for (int i = 0; i < 14; ++i) { const int kid = skey + 32 * i; *(LAS v4u*)(size_t)(IMG + vimg_off(kid, sch)) = rst[i]; }
;                     __syncthreads();
;                     if (unit + GH < UEND) { NA_LOADROWS(unit + GH, rst, D); NA_LOADQ(unit + GH); }
	v_add_f32_e32 v149, v104, v149
	v_lshlrev_b32_e32 v104, 8, v77
	v_bfe_u32 v77, v77, 2, 2
	v_bitop3_b32 v77, v153, v112, v77 bitop3:0x36
	v_lshlrev_b32_e32 v77, 4, v77
	v_add3_u32 v77, v104, 0, v77
	ds_bpermute_b32 v151, v213, v149
	v_add_u32_e32 v104, 0x10000, v77
	s_waitcnt vmcnt(13)
	ds_write_b128 v77, v[0:3]
	s_waitcnt vmcnt(12)
	ds_write_b128 v77, v[4:7] offset:8192
	s_waitcnt vmcnt(11)
	ds_write_b128 v77, v[8:11] offset:16384
	s_waitcnt vmcnt(10)
	ds_write_b128 v77, v[12:15] offset:24576
	s_waitcnt vmcnt(9)
	ds_write_b128 v77, v[16:19] offset:32768
	s_waitcnt vmcnt(8)
	ds_write_b128 v77, v[20:23] offset:40960
	s_waitcnt vmcnt(7)
	ds_write_b128 v77, v[40:43] offset:49152
	s_waitcnt vmcnt(6)
	ds_write_b128 v77, v[44:47] offset:57344
	s_waitcnt vmcnt(5)
	ds_write_b128 v104, v[48:51]
	v_add_u32_e32 v104, 0x12000, v77
	s_waitcnt vmcnt(4)
	ds_write_b128 v104, v[52:55]
	v_add_u32_e32 v104, 0x14000, v77
	s_waitcnt vmcnt(3)
	ds_write_b128 v104, v[56:59]
	v_add_u32_e32 v104, 0x16000, v77
	s_waitcnt vmcnt(2)
	ds_write_b128 v104, v[60:63]
	v_add_u32_e32 v104, 0x18000, v77
	v_add_u32_e32 v77, 0x1a000, v77
	s_waitcnt vmcnt(1)
	ds_write_b128 v104, v[64:67]
	s_waitcnt vmcnt(0)
	ds_write_b128 v77, v[68:71]
	s_waitcnt lgkmcnt(0)
	s_barrier
	s_cbranch_vccnz .LBB0_843
	s_add_i32 s42, s83, s84
	s_and_b32 s45, s42, 28
	s_add_i32 s47, s91, s96
	v_sub_u32_e64 v1, s45, 1 clamp
	s_and_b32 s42, s47, 0x780
	v_lshlrev_b32_e32 v0, 3, v112
	s_and_b32 s44, s21, 1
	s_max_u32 s46, s45, 4
	v_min_u32_e32 v1, 24, v1
	s_lshl_b32 s48, s42, 1
	s_add_u32 s42, s59, s48
	v_lshlrev_b32_e32 v104, 1, v0
	v_subrev_u32_e32 v0, s46, v1
	s_addc_u32 s43, s80, 0
	v_add_u32_e32 v31, 11, v0
	v_sub_u32_e64 v30, s45, 4 clamp
	v_lshl_add_u64 v[24:25], s[42:43], 0, v[104:105]
	s_and_b32 s46, s47, 0xfffff800
	s_mul_i32 s42, s44, 24
	v_min_i32_e32 v0, v78, v31
	v_min_i32_e32 v2, v80, v31
	v_min_i32_e32 v8, v82, v31
	v_min_i32_e32 v10, v84, v31
	v_min_i32_e32 v16, v86, v31
	v_min_i32_e32 v18, v88, v31
	v_min_i32_e32 v26, v90, v31
	v_min_i32_e32 v28, v92, v31
	s_or_b32 s47, s46, s42
	v_add_lshl_u32 v0, v0, v30, 6
	v_add_lshl_u32 v2, v2, v30, 6
	v_add_lshl_u32 v8, v8, v30, 6
	v_add_lshl_u32 v10, v10, v30, 6
	v_add_lshl_u32 v16, v16, v30, 6
	v_add_lshl_u32 v18, v18, v30, 6
	v_add_lshl_u32 v26, v26, v30, 6
	v_add_lshl_u32 v28, v28, v30, 6
	v_add3_u32 v0, v79, s47, v0
	v_add3_u32 v2, v81, s47, v2
	v_add3_u32 v8, v83, s47, v8
	v_add3_u32 v10, v85, s47, v10
	v_add3_u32 v16, v87, s47, v16
	v_add3_u32 v18, v89, s47, v18
	v_add3_u32 v26, v91, s47, v26
	v_add3_u32 v28, v93, s47, v28
	v_mad_i64_i32 v[0:1], s[42:43], v0, s22, v[24:25]
	v_mad_i64_i32 v[4:5], s[42:43], v2, s22, v[24:25]
	v_mad_i64_i32 v[8:9], s[42:43], v8, s22, v[24:25]
	v_mad_i64_i32 v[12:13], s[42:43], v10, s22, v[24:25]
	v_mad_i64_i32 v[16:17], s[42:43], v16, s22, v[24:25]
	v_mad_i64_i32 v[20:21], s[42:43], v18, s22, v[24:25]
	v_mad_i64_i32 v[26:27], s[42:43], v26, s22, v[24:25]
	v_mad_i64_i32 v[28:29], s[42:43], v28, s22, v[24:25]
	global_load_dwordx4 v[0:3], v[0:1], off
	s_nop 0
	global_load_dwordx4 v[4:7], v[4:5], off
	s_nop 0
	global_load_dwordx4 v[8:11], v[8:9], off
	s_nop 0
	global_load_dwordx4 v[12:15], v[12:13], off
	s_nop 0
	global_load_dwordx4 v[16:19], v[16:17], off
	s_nop 0
	global_load_dwordx4 v[20:23], v[20:21], off
	s_nop 0
	global_load_dwordx4 v[40:43], v[26:27], off
	global_load_dwordx4 v[44:47], v[28:29], off
	v_min_i32_e32 v26, v94, v31
	v_min_i32_e32 v28, v96, v31
	v_add_lshl_u32 v26, v26, v30, 6
	v_add_lshl_u32 v28, v28, v30, 6
	v_add3_u32 v26, v95, s47, v26
	v_add3_u32 v28, v97, s47, v28
	v_mad_i64_i32 v[26:27], s[42:43], v26, s22, v[24:25]
	v_mad_i64_i32 v[28:29], s[42:43], v28, s22, v[24:25]
	global_load_dwordx4 v[48:51], v[26:27], off
	global_load_dwordx4 v[52:55], v[28:29], off
	v_min_i32_e32 v26, v98, v31
	v_min_i32_e32 v28, v100, v31
	v_add_lshl_u32 v26, v26, v30, 6
	v_add_lshl_u32 v28, v28, v30, 6
	v_add3_u32 v26, v99, s47, v26
	v_add3_u32 v28, v101, s47, v28
	v_mad_i64_i32 v[26:27], s[42:43], v26, s22, v[24:25]
	v_mad_i64_i32 v[28:29], s[42:43], v28, s22, v[24:25]
	global_load_dwordx4 v[56:59], v[26:27], off
	global_load_dwordx4 v[60:63], v[28:29], off
	v_min_i32_e32 v26, v102, v31
	v_min_i32_e32 v28, v113, v31
	v_add_lshl_u32 v26, v26, v30, 6
	v_add_lshl_u32 v28, v28, v30, 6
	v_add3_u32 v26, v103, s47, v26
	v_add3_u32 v28, v114, s47, v28
	v_mad_i64_i32 v[26:27], s[42:43], v26, s22, v[24:25]
	v_mad_i64_i32 v[24:25], s[42:43], v28, s22, v[24:25]
	s_add_u32 s42, s55, s48
	s_addc_u32 s43, s56, 0
	s_add_i32 s45, s45, s53
	s_lshl_b32 s45, s45, 6
	s_add_i32 s45, s45, s46
	s_lshl_b32 s44, s44, 5
	s_or_b32 s44, s45, s44
	s_or_b32 s44, s44, s54
	global_load_dwordx4 v[64:67], v[26:27], off
	global_load_dwordx4 v[68:71], v[24:25], off
	v_or_b32_e32 v26, s44, v112
	v_mov_b64_e32 v[24:25], s[42:43]
	v_mad_i64_i32 v[24:25], s[42:43], v26, s22, v[24:25]
	v_lshlrev_b32_e32 v104, 4, v76
	v_lshl_add_u64 v[36:37], v[24:25], 0, v[104:105]
	global_load_dwordx4 v[24:27], v[36:37], off
	global_load_dwordx4 v[28:31], v[36:37], off offset:64
	global_load_dwordx4 v[32:35], v[36:37], off offset:128
	s_nop 0
	global_load_dwordx4 v[36:39], v[36:37], off offset:192
	s_branch .LBB0_843

; #define LAS __attribute__((address_space(3)))
; template <int L>
; __device__ __forceinline__ void layer_body(const Args& args, LAS unsigned char* lds, const int wave, const int G, const int gw, const int NGW, const int lo, const int hi,
;                                            unsigned char* const ws_kernel, const XcdBarrier& bar, int& pid) {
;     ...
;                     bf16x8 pbf[8];
; #pragma unroll
;                     for (int s = 0; s < 8; ++s) { const f32x4 p0 = sc[2 * s], p1 = sc[2 * s + 1]; v4u w; w.x = pk2(p0[0], p0[1]); w.y = pk2(p0[2], p0[3]); w.z = pk2(p1[0], p1[1]); w.w = pk2(p1[2], p1[3]); pbf[s] = __builtin_bit_cast(bf16x8, w); }
;                     __syncthreads();
; #pragma unroll
;                     for (int i = 0; i < 14; ++i) { const int kid = skey + 32 * i; *(LAS v4u*)(size_t)(IMG + vimg_off(kid, sch)) = rst[i]; }
;                     __syncthreads();
;                     if (unit + GH < UEND) { NA_LOADROWS(unit + GH, rst, D); NA_LOADQ(unit + GH); }
;                     f32x4 acc[8];
; #pragma unroll
;                     for (int mt = 0; mt < 8; ++mt) acc[mt] = (f32x4){0.f, 0.f, 0.f, 0.f};
;                     const int trq = (lane & 15) >> 2, trp = lane & 3;
; #pragma unroll
;                     for (int s = 0; s < 8; ++s) {
;                         const int ir0 = (r0w - krlo + s) * 40 + coloff;
; #pragma unroll
;                         for (int mh = 0; mh < 2; ++mh) {
;                             s16x4 lo[4], hi[4];
; #pragma unroll
;                             for (int m4 = 0; m4 < 4; ++m4) { const int mt = mh * 4 + m4, r0_ = ir0 + 4 * kg + trq, r1_ = ir0 + 16 + 4 * kg + trq, ch_ = 2 * mt + (trp >> 1);
;                                 lo[m4] = tr_read_b64(IMG + vimg_off(r0_, ch_) + 8u * (trp & 1)); hi[m4] = tr_read_b64(IMG + vimg_off(r1_, ch_) + 8u * (trp & 1)); }
;                             asm volatile("s_waitcnt lgkmcnt(0)" ::: "memory"); __builtin_amdgcn_sched_barrier(0);
; #pragma unroll
;                             for (int m4 = 0; m4 < 4; ++m4) { const int mt = mh * 4 + m4; const bf16x8 va = (bf16x8){lo[m4][0], lo[m4][1], lo[m4][2], lo[m4][3], hi[m4][0], hi[m4][1], hi[m4][2], hi[m4][3]};
;                                 acc[mt] = __builtin_amdgcn_mfma_f32_16x16x32_bf16(va, pbf[s], acc[mt], 0, 0, 0); }
;                         }
.LBB0_3408:
	v_cvt_pk_bf16_f32 v101, v194, v200
	v_cvt_pk_bf16_f32 v100, v190, v198
	v_cvt_pk_bf16_f32 v103, v199, v202
	v_cvt_pk_bf16_f32 v102, v196, v201
	v_cvt_pk_bf16_f32 v97, v186, v193
	v_cvt_pk_bf16_f32 v96, v180, v191
	v_cvt_pk_bf16_f32 v99, v192, v197
	v_cvt_pk_bf16_f32 v98, v188, v195
	v_cvt_pk_bf16_f32 v93, v178, v185
	v_cvt_pk_bf16_f32 v92, v177, v182
	v_cvt_pk_bf16_f32 v95, v184, v189
	v_cvt_pk_bf16_f32 v94, v179, v187
	v_cvt_pk_bf16_f32 v89, v142, v148
	v_cvt_pk_bf16_f32 v88, v138, v146
	v_cvt_pk_bf16_f32 v91, v147, v152
	v_cvt_pk_bf16_f32 v90, v144, v150
	v_cvt_pk_bf16_f32 v85, v134, v141
	v_cvt_pk_bf16_f32 v84, v130, v139
	v_cvt_pk_bf16_f32 v87, v140, v145
	v_cvt_pk_bf16_f32 v86, v136, v143
	v_cvt_pk_bf16_f32 v81, v126, v133
	v_cvt_pk_bf16_f32 v80, v122, v131
	v_bfe_u32 v78, v125, 16, 1
	v_add3_u32 v113, v125, v78, s64
	v_bfe_u32 v79, v118, 16, 1
	v_cvt_pk_bf16_f32 v83, v132, v137
	v_add3_u32 v79, v118, v79, s64
	v_cvt_pk_bf16_f32 v82, v128, v135
	v_lshrrev_b32_e32 v118, 16, v79
	v_cvt_pk_bf16_f32 v79, v124, v129
	v_cvt_pk_bf16_f32 v76, v75, v123
	v_cvt_pk_bf16_f32 v78, v120, v127
	v_and_or_b32 v77, v113, s65, v118
	v_bfe_u32 v114, v115, 16, 1
	v_add3_u32 v114, v115, v114, s64
	v_bfe_u32 v115, v72, 16, 1
	v_add3_u32 v72, v72, v115, s64
	v_lshrrev_b32_e32 v112, 2, v112
	v_lshrrev_b32_e32 v72, 16, v72
	v_cvt_pk_bf16_f32 v75, v116, v121
	v_or_b32_e32 v115, v109, v112
	s_add_i32 s68, s68, s67
	v_cvt_pk_bf16_f32 v73, v73, v117
	v_and_or_b32 v72, v114, s65, v72
	v_or_b32_e32 v113, 16, v115
	v_bfe_u32 v112, v111, 1, 1
	v_lshlrev_b32_e32 v111, 3, v111
	v_add_u32_e32 v114, s68, v115
	v_and_or_b32 v111, v111, 8, 0
	v_add_u32_e32 v116, s68, v113
	v_lshlrev_b32_e32 v117, 2, v114
	v_and_b32_e32 v152, 12, v117
	v_bfe_u32 v153, v114, 2, 2
	v_lshl_add_u32 v154, v114, 8, v111
	v_lshlrev_b32_e32 v114, 2, v116
	v_and_b32_e32 v155, 12, v114
	v_bitop3_b32 v114, v152, v112, v153 bitop3:0x36
	v_bfe_u32 v156, v116, 2, 2
	v_lshl_add_u32 v253, v114, 4, v154
	v_lshl_add_u32 v157, v116, 8, v111
	ds_read_b64_tr_b16 v[120:121], v253
	v_bitop3_b32 v114, v155, v112, v156 bitop3:0x36
	v_lshl_add_u32 v252, v114, 4, v157
	ds_read_b64_tr_b16 v[122:123], v252
	v_or_b32_e32 v114, 2, v112
	v_xor_b32_e32 v116, 0x20, v253
	ds_read_b64_tr_b16 v[124:125], v116
	v_xor_b32_e32 v116, 0x20, v252
	ds_read_b64_tr_b16 v[126:127], v116
	v_or_b32_e32 v116, 4, v112
	v_xor_b32_e32 v117, 0x40, v253
	ds_read_b64_tr_b16 v[128:129], v117
	v_xor_b32_e32 v117, 0x40, v252
	ds_read_b64_tr_b16 v[130:131], v117
	v_xor_b32_e32 v118, 0x60, v253
	ds_read_b64_tr_b16 v[132:133], v118
	v_xor_b32_e32 v118, 0x60, v252
	ds_read_b64_tr_b16 v[134:135], v118
	s_waitcnt lgkmcnt(0)
	v_cvt_pk_bf16_f32 v74, v74, v119
	v_add_f32_e32 v104, v149, v151
	v_xor_b32_e32 v119, 0x80, v253
	v_mfma_f32_16x16x32_bf16 v[136:139], v[120:123], v[100:103], 0
	ds_read_b64_tr_b16 v[122:123], v119
	v_xor_b32_e32 v119, 0x80, v252
	v_mfma_f32_16x16x32_bf16 v[140:143], v[124:127], v[100:103], 0
	ds_read_b64_tr_b16 v[124:125], v119
	v_xor_b32_e32 v120, 0xa0, v253
	v_mfma_f32_16x16x32_bf16 v[126:129], v[128:131], v[100:103], 0
	ds_read_b64_tr_b16 v[130:131], v120
	v_xor_b32_e32 v120, 0xa0, v252
	v_mfma_f32_16x16x32_bf16 v[144:147], v[132:135], v[100:103], 0
	ds_read_b64_tr_b16 v[132:133], v120
	v_xor_b32_e32 v121, 0xc0, v253
	ds_read_b64_tr_b16 v[148:149], v121
	v_xor_b32_e32 v121, 0xc0, v252
	ds_read_b64_tr_b16 v[150:151], v121
	v_or_b32_e32 v121, 14, v112
	v_xor_b32_e32 v134, 0xe0, v253
	ds_read_b64_tr_b16 v[152:153], v134
	v_xor_b32_e32 v134, 0xe0, v252
	ds_read_b64_tr_b16 v[154:155], v134
	s_waitcnt lgkmcnt(0)
	s_add_i32 s69, s69, s67
	v_add_u32_e32 v134, s69, v115
	v_add_u32_e32 v135, s69, v113
	v_lshlrev_b32_e32 v156, 2, v134
	v_and_b32_e32 v168, 12, v156
	v_bfe_u32 v169, v134, 2, 2
	v_lshl_add_u32 v170, v134, 8, v111
	v_lshlrev_b32_e32 v134, 2, v135
	v_and_b32_e32 v171, 12, v134
	v_bitop3_b32 v134, v168, v112, v169 bitop3:0x36
	v_bfe_u32 v172, v135, 2, 2
	v_lshl_add_u32 v253, v134, 4, v170
	v_mfma_f32_16x16x32_bf16 v[122:125], v[122:125], v[100:103], 0
	v_lshl_add_u32 v173, v135, 8, v111
	v_mfma_f32_16x16x32_bf16 v[130:133], v[130:133], v[100:103], 0
	v_mfma_f32_16x16x32_bf16 v[148:151], v[148:151], v[100:103], 0
	v_mfma_f32_16x16x32_bf16 v[100:103], v[152:155], v[100:103], 0
	ds_read_b64_tr_b16 v[152:153], v253
	v_bitop3_b32 v134, v171, v112, v172 bitop3:0x36
	v_lshl_add_u32 v252, v134, 4, v173
	ds_read_b64_tr_b16 v[154:155], v252
	v_xor_b32_e32 v134, 0x20, v253
	ds_read_b64_tr_b16 v[156:157], v134
	v_xor_b32_e32 v134, 0x20, v252
	ds_read_b64_tr_b16 v[158:159], v134
	v_xor_b32_e32 v134, 0x40, v253
	ds_read_b64_tr_b16 v[160:161], v134
	v_xor_b32_e32 v134, 0x40, v252
	ds_read_b64_tr_b16 v[162:163], v134
	v_xor_b32_e32 v134, 0x60, v253
	ds_read_b64_tr_b16 v[164:165], v134
	v_xor_b32_e32 v134, 0x60, v252
	ds_read_b64_tr_b16 v[166:167], v134
	s_waitcnt lgkmcnt(0)
	v_xor_b32_e32 v174, 0x80, v253
	v_mfma_f32_16x16x32_bf16 v[134:137], v[152:155], v[96:99], v[136:139]
	ds_read_b64_tr_b16 v[138:139], v174
	v_xor_b32_e32 v174, 0x80, v252
	v_mfma_f32_16x16x32_bf16 v[152:155], v[156:159], v[96:99], v[140:143]
	ds_read_b64_tr_b16 v[140:141], v174
	v_mfma_f32_16x16x32_bf16 v[126:129], v[160:163], v[96:99], v[126:129]
	s_nop 0
	v_xor_b32_e32 v142, 0xa0, v253
	ds_read_b64_tr_b16 v[142:143], v142
	v_xor_b32_e32 v160, 0xa0, v252
	v_mfma_f32_16x16x32_bf16 v[156:159], v[164:167], v[96:99], v[144:147]
	ds_read_b64_tr_b16 v[144:145], v160
	s_nop 2
	v_xor_b32_e32 v146, 0xc0, v253
	ds_read_b64_tr_b16 v[160:161], v146
	v_xor_b32_e32 v146, 0xc0, v252
	ds_read_b64_tr_b16 v[162:163], v146
	v_xor_b32_e32 v146, 0xe0, v253
	ds_read_b64_tr_b16 v[164:165], v146
	v_xor_b32_e32 v146, 0xe0, v252
	ds_read_b64_tr_b16 v[166:167], v146
	s_waitcnt lgkmcnt(0)
; __device__ __forceinline__ s16x4 tr_read_b64(unsigned addr) { s16x4 r; asm volatile("ds_read_b64_tr_b16 %0, %1" : "=v"(r) : "v"(addr) : "memory"); return r; }
; template <int L>
; __device__ __forceinline__ void layer_body(const Args& args, LAS unsigned char* lds, const int wave, const int G, const int gw, const int NGW, const int lo, const int hi,
;                                            unsigned char* const ws_kernel, const XcdBarrier& bar, int& pid) {
;     ...
;                     for (int s = 0; s < 8; ++s) {
;                         const int ir0 = (r0w - krlo + s) * 40 + coloff;
; #pragma unroll
;                         for (int mh = 0; mh < 2; ++mh) {
;                             s16x4 lo[4], hi[4];
; #pragma unroll
;                             for (int m4 = 0; m4 < 4; ++m4) { const int mt = mh * 4 + m4, r0_ = ir0 + 4 * kg + trq, r1_ = ir0 + 16 + 4 * kg + trq, ch_ = 2 * mt + (trp >> 1);
;                                 lo[m4] = tr_read_b64(IMG + vimg_off(r0_, ch_) + 8u * (trp & 1)); hi[m4] = tr_read_b64(IMG + vimg_off(r1_, ch_) + 8u * (trp & 1)); }
;                             asm volatile("s_waitcnt lgkmcnt(0)" ::: "memory"); __builtin_amdgcn_sched_barrier(0);
; #pragma unroll
;                             for (int m4 = 0; m4 < 4; ++m4) { const int mt = mh * 4 + m4; const bf16x8 va = (bf16x8){lo[m4][0], lo[m4][1], lo[m4][2], lo[m4][3], hi[m4][0], hi[m4][1], hi[m4][2], hi[m4][3]};
;                                 acc[mt] = __builtin_amdgcn_mfma_f32_16x16x32_bf16(va, pbf[s], acc[mt], 0, 0, 0); }
;                         }
	s_add_i32 s70, s70, s67
	v_add_u32_e32 v146, s70, v115
	v_mfma_f32_16x16x32_bf16 v[122:125], v[138:141], v[96:99], v[122:125]
	v_add_u32_e32 v147, s70, v113
	v_lshlrev_b32_e32 v138, 2, v146
	v_and_b32_e32 v168, 12, v138
	v_mfma_f32_16x16x32_bf16 v[130:133], v[142:145], v[96:99], v[130:133]
	v_bfe_u32 v169, v146, 2, 2
	v_lshlrev_b32_e32 v142, 2, v147
	v_lshl_add_u32 v170, v146, 8, v111
	v_mfma_f32_16x16x32_bf16 v[138:141], v[160:163], v[96:99], v[148:151]
	v_and_b32_e32 v171, 12, v142
	v_bfe_u32 v172, v147, 2, 2
	v_lshl_add_u32 v173, v147, 8, v111
	v_mfma_f32_16x16x32_bf16 v[96:99], v[164:167], v[96:99], v[100:103]
	v_bitop3_b32 v142, v168, v114, v169 bitop3:0x36
	v_lshl_add_u32 v142, v142, 4, v170
	v_bitop3_b32 v144, v171, v114, v172 bitop3:0x36
	v_bitop3_b32 v100, v168, v112, v169 bitop3:0x36
	v_lshl_add_u32 v253, v100, 4, v170
	v_bitop3_b32 v102, v171, v112, v172 bitop3:0x36
	ds_read_b64_tr_b16 v[100:101], v253
	v_lshl_add_u32 v252, v102, 4, v173
	ds_read_b64_tr_b16 v[102:103], v252
	ds_read_b64_tr_b16 v[142:143], v142
	v_lshl_add_u32 v144, v144, 4, v173
	ds_read_b64_tr_b16 v[144:145], v144
	v_xor_b32_e32 v146, 0x40, v253
	ds_read_b64_tr_b16 v[146:147], v146
	v_xor_b32_e32 v148, 0x40, v252
	ds_read_b64_tr_b16 v[148:149], v148
	v_xor_b32_e32 v150, 0x60, v253
	ds_read_b64_tr_b16 v[160:161], v150
	v_xor_b32_e32 v150, 0x60, v252
	ds_read_b64_tr_b16 v[162:163], v150
	s_waitcnt lgkmcnt(0)
	v_mfma_f32_16x16x32_bf16 v[100:103], v[100:103], v[92:95], v[134:137]
	v_xor_b32_e32 v150, 0x80, v253
	ds_read_b64_tr_b16 v[134:135], v150
	v_mfma_f32_16x16x32_bf16 v[126:129], v[146:149], v[92:95], v[126:129]
	v_xor_b32_e32 v136, 0x80, v252
	ds_read_b64_tr_b16 v[136:137], v136
	v_mfma_f32_16x16x32_bf16 v[142:145], v[142:145], v[92:95], v[152:155]
	v_xor_b32_e32 v150, 0xa0, v253
	ds_read_b64_tr_b16 v[146:147], v150
	v_xor_b32_e32 v148, 0xa0, v252
	v_mfma_f32_16x16x32_bf16 v[150:153], v[160:163], v[92:95], v[156:159]
	ds_read_b64_tr_b16 v[148:149], v148
	v_xor_b32_e32 v154, 0xc0, v253
	ds_read_b64_tr_b16 v[154:155], v154
	v_xor_b32_e32 v156, 0xc0, v252
	ds_read_b64_tr_b16 v[156:157], v156
	v_xor_b32_e32 v158, 0xe0, v253
	ds_read_b64_tr_b16 v[158:159], v158
	v_xor_b32_e32 v160, 0xe0, v252
	ds_read_b64_tr_b16 v[160:161], v160
	s_waitcnt lgkmcnt(0)
	s_add_i32 s71, s71, s67
	v_add_u32_e32 v162, s71, v115
	v_mfma_f32_16x16x32_bf16 v[122:125], v[134:137], v[92:95], v[122:125]
	v_add_u32_e32 v163, s71, v113
	v_lshlrev_b32_e32 v134, 2, v162
	v_and_b32_e32 v164, 12, v134
	v_mfma_f32_16x16x32_bf16 v[130:133], v[146:149], v[92:95], v[130:133]
	v_bfe_u32 v165, v162, 2, 2
	v_lshlrev_b32_e32 v146, 2, v163
	v_lshl_add_u32 v162, v162, 8, v111
	v_mfma_f32_16x16x32_bf16 v[134:137], v[154:157], v[92:95], v[138:141]
	v_and_b32_e32 v166, 12, v146
	v_bfe_u32 v167, v163, 2, 2
	v_lshl_add_u32 v163, v163, 8, v111
	v_mfma_f32_16x16x32_bf16 v[92:95], v[158:161], v[92:95], v[96:99]
	v_bitop3_b32 v138, v164, v114, v165 bitop3:0x36
	v_lshl_add_u32 v138, v138, 4, v162
	v_bitop3_b32 v140, v166, v114, v167 bitop3:0x36
	v_bitop3_b32 v96, v164, v112, v165 bitop3:0x36
	v_lshl_add_u32 v253, v96, 4, v162
	v_bitop3_b32 v98, v166, v112, v167 bitop3:0x36
	ds_read_b64_tr_b16 v[96:97], v253
	v_lshl_add_u32 v252, v98, 4, v163
	ds_read_b64_tr_b16 v[98:99], v252
	ds_read_b64_tr_b16 v[138:139], v138
	v_lshl_add_u32 v140, v140, 4, v163
	ds_read_b64_tr_b16 v[140:141], v140
	v_xor_b32_e32 v146, 0x40, v253
	ds_read_b64_tr_b16 v[146:147], v146
	v_xor_b32_e32 v148, 0x40, v252
	ds_read_b64_tr_b16 v[148:149], v148
	v_xor_b32_e32 v154, 0x60, v253
	ds_read_b64_tr_b16 v[154:155], v154
	v_xor_b32_e32 v156, 0x60, v252
	ds_read_b64_tr_b16 v[156:157], v156
	s_waitcnt lgkmcnt(0)
	v_mfma_f32_16x16x32_bf16 v[96:99], v[96:99], v[88:91], v[100:103]
	v_xor_b32_e32 v158, 0x80, v253
	ds_read_b64_tr_b16 v[100:101], v158
	v_mfma_f32_16x16x32_bf16 v[138:141], v[138:141], v[88:91], v[142:145]
	s_nop 0
	v_xor_b32_e32 v102, 0x80, v252
	ds_read_b64_tr_b16 v[102:103], v102
	v_mfma_f32_16x16x32_bf16 v[126:129], v[146:149], v[88:91], v[126:129]
	v_xor_b32_e32 v142, 0xa0, v253
	ds_read_b64_tr_b16 v[142:143], v142
	v_xor_b32_e32 v144, 0xa0, v252
	v_mfma_f32_16x16x32_bf16 v[146:149], v[154:157], v[88:91], v[150:153]
	ds_read_b64_tr_b16 v[144:145], v144
	v_xor_b32_e32 v154, 0xe0, v253
	v_xor_b32_e32 v150, 0xc0, v253
	ds_read_b64_tr_b16 v[150:151], v150
	v_xor_b32_e32 v152, 0xc0, v252
	ds_read_b64_tr_b16 v[152:153], v152
	ds_read_b64_tr_b16 v[154:155], v154
	v_xor_b32_e32 v156, 0xe0, v252
	ds_read_b64_tr_b16 v[156:157], v156
	s_waitcnt lgkmcnt(0)
	s_add_i32 s72, s72, s67
	v_add_u32_e32 v158, s72, v115
	v_mfma_f32_16x16x32_bf16 v[100:103], v[100:103], v[88:91], v[122:125]
	v_add_u32_e32 v159, s72, v113
	v_bfe_u32 v161, v158, 2, 2
	v_bfe_u32 v163, v159, 2, 2
	v_lshlrev_b32_e32 v122, 2, v158
	v_and_b32_e32 v160, 12, v122
	v_mfma_f32_16x16x32_bf16 v[122:125], v[142:145], v[88:91], v[130:133]
	v_lshlrev_b32_e32 v142, 2, v159
	v_lshl_add_u32 v158, v158, 8, v111
	v_and_b32_e32 v162, 12, v142
	v_mfma_f32_16x16x32_bf16 v[130:133], v[150:153], v[88:91], v[134:137]
	v_lshl_add_u32 v159, v159, 8, v111
	v_bitop3_b32 v142, v160, v116, v161 bitop3:0x36
	v_lshl_add_u32 v142, v142, 4, v158
	v_mfma_f32_16x16x32_bf16 v[88:91], v[154:157], v[88:91], v[92:95]
	v_bitop3_b32 v134, v160, v114, v161 bitop3:0x36
	v_lshl_add_u32 v134, v134, 4, v158
	v_bitop3_b32 v136, v162, v114, v163 bitop3:0x36
	v_bitop3_b32 v92, v160, v112, v161 bitop3:0x36
	v_lshl_add_u32 v253, v92, 4, v158
	v_bitop3_b32 v94, v162, v112, v163 bitop3:0x36
	ds_read_b64_tr_b16 v[92:93], v253
	v_lshl_add_u32 v252, v94, 4, v159
	ds_read_b64_tr_b16 v[94:95], v252
	ds_read_b64_tr_b16 v[134:135], v134
	v_lshl_add_u32 v136, v136, 4, v159
	ds_read_b64_tr_b16 v[136:137], v136
	ds_read_b64_tr_b16 v[142:143], v142
	v_xor_b32_e32 v144, 0x40, v252
	ds_read_b64_tr_b16 v[144:145], v144
	v_xor_b32_e32 v150, 0x60, v253
	ds_read_b64_tr_b16 v[150:151], v150
	v_xor_b32_e32 v152, 0x60, v252
	ds_read_b64_tr_b16 v[152:153], v152
	s_waitcnt lgkmcnt(0)
; __device__ __forceinline__ s16x4 tr_read_b64(unsigned addr) { s16x4 r; asm volatile("ds_read_b64_tr_b16 %0, %1" : "=v"(r) : "v"(addr) : "memory"); return r; }
; template <int L>
; __device__ __forceinline__ void layer_body(const Args& args, LAS unsigned char* lds, const int wave, const int G, const int gw, const int NGW, const int lo, const int hi,
;                                            unsigned char* const ws_kernel, const XcdBarrier& bar, int& pid) {
;     ...
;                     for (int s = 0; s < 8; ++s) {
;                         const int ir0 = (r0w - krlo + s) * 40 + coloff;
; #pragma unroll
;                         for (int mh = 0; mh < 2; ++mh) {
;                             s16x4 lo[4], hi[4];
; #pragma unroll
;                             for (int m4 = 0; m4 < 4; ++m4) { const int mt = mh * 4 + m4, r0_ = ir0 + 4 * kg + trq, r1_ = ir0 + 16 + 4 * kg + trq, ch_ = 2 * mt + (trp >> 1);
;                                 lo[m4] = tr_read_b64(IMG + vimg_off(r0_, ch_) + 8u * (trp & 1)); hi[m4] = tr_read_b64(IMG + vimg_off(r1_, ch_) + 8u * (trp & 1)); }
;                             asm volatile("s_waitcnt lgkmcnt(0)" ::: "memory"); __builtin_amdgcn_sched_barrier(0);
; #pragma unroll
;                             for (int m4 = 0; m4 < 4; ++m4) { const int mt = mh * 4 + m4; const bf16x8 va = (bf16x8){lo[m4][0], lo[m4][1], lo[m4][2], lo[m4][3], hi[m4][0], hi[m4][1], hi[m4][2], hi[m4][3]};
;                                 acc[mt] = __builtin_amdgcn_mfma_f32_16x16x32_bf16(va, pbf[s], acc[mt], 0, 0, 0); }
;                         }
	v_mfma_f32_16x16x32_bf16 v[92:95], v[92:95], v[84:87], v[96:99]
	v_xor_b32_e32 v154, 0x80, v253
	ds_read_b64_tr_b16 v[96:97], v154
	v_mfma_f32_16x16x32_bf16 v[134:137], v[134:137], v[84:87], v[138:141]
	s_nop 0
	v_xor_b32_e32 v98, 0x80, v252
	ds_read_b64_tr_b16 v[98:99], v98
	v_mfma_f32_16x16x32_bf16 v[126:129], v[142:145], v[84:87], v[126:129]
	v_xor_b32_e32 v138, 0xa0, v253
	ds_read_b64_tr_b16 v[138:139], v138
	v_xor_b32_e32 v140, 0xa0, v252
	v_mfma_f32_16x16x32_bf16 v[142:145], v[150:153], v[84:87], v[146:149]
	ds_read_b64_tr_b16 v[140:141], v140
	v_xor_b32_e32 v150, 0xe0, v253
	v_xor_b32_e32 v146, 0xc0, v253
	ds_read_b64_tr_b16 v[146:147], v146
	v_xor_b32_e32 v148, 0xc0, v252
	ds_read_b64_tr_b16 v[148:149], v148
	ds_read_b64_tr_b16 v[150:151], v150
	v_xor_b32_e32 v152, 0xe0, v252
	ds_read_b64_tr_b16 v[152:153], v152
	s_waitcnt lgkmcnt(0)
	s_add_i32 s74, s74, s67
	v_add_u32_e32 v154, s74, v115
	v_mfma_f32_16x16x32_bf16 v[96:99], v[96:99], v[84:87], v[100:103]
	v_add_u32_e32 v155, s74, v113
	v_bfe_u32 v157, v154, 2, 2
	v_bfe_u32 v159, v155, 2, 2
	v_lshlrev_b32_e32 v100, 2, v154
	v_and_b32_e32 v156, 12, v100
	v_mfma_f32_16x16x32_bf16 v[100:103], v[138:141], v[84:87], v[122:125]
	v_lshlrev_b32_e32 v138, 2, v155
	v_lshl_add_u32 v154, v154, 8, v111
	v_and_b32_e32 v158, 12, v138
	v_mfma_f32_16x16x32_bf16 v[122:125], v[146:149], v[84:87], v[130:133]
	v_lshl_add_u32 v155, v155, 8, v111
	v_bitop3_b32 v138, v156, v116, v157 bitop3:0x36
	v_lshl_add_u32 v138, v138, 4, v154
	v_mfma_f32_16x16x32_bf16 v[84:87], v[150:153], v[84:87], v[88:91]
	v_bitop3_b32 v130, v156, v114, v157 bitop3:0x36
	v_lshl_add_u32 v130, v130, 4, v154
	v_bitop3_b32 v132, v158, v114, v159 bitop3:0x36
	v_bitop3_b32 v88, v156, v112, v157 bitop3:0x36
	v_lshl_add_u32 v253, v88, 4, v154
	v_bitop3_b32 v90, v158, v112, v159 bitop3:0x36
	ds_read_b64_tr_b16 v[88:89], v253
	v_lshl_add_u32 v252, v90, 4, v155
	ds_read_b64_tr_b16 v[90:91], v252
	ds_read_b64_tr_b16 v[130:131], v130
	v_lshl_add_u32 v132, v132, 4, v155
	ds_read_b64_tr_b16 v[132:133], v132
	ds_read_b64_tr_b16 v[138:139], v138
	v_xor_b32_e32 v140, 0x40, v252
	ds_read_b64_tr_b16 v[140:141], v140
	v_xor_b32_e32 v146, 0x60, v253
	ds_read_b64_tr_b16 v[146:147], v146
	v_xor_b32_e32 v148, 0x60, v252
	ds_read_b64_tr_b16 v[148:149], v148
	s_waitcnt lgkmcnt(0)
	v_mfma_f32_16x16x32_bf16 v[88:91], v[88:91], v[80:83], v[92:95]
	v_xor_b32_e32 v150, 0x80, v253
	ds_read_b64_tr_b16 v[92:93], v150
	v_mfma_f32_16x16x32_bf16 v[130:133], v[130:133], v[80:83], v[134:137]
	s_nop 0
	v_xor_b32_e32 v94, 0x80, v252
	ds_read_b64_tr_b16 v[94:95], v94
	v_mfma_f32_16x16x32_bf16 v[126:129], v[138:141], v[80:83], v[126:129]
	v_xor_b32_e32 v134, 0xa0, v253
	ds_read_b64_tr_b16 v[134:135], v134
	v_xor_b32_e32 v136, 0xa0, v252
	v_mfma_f32_16x16x32_bf16 v[138:141], v[146:149], v[80:83], v[142:145]
	ds_read_b64_tr_b16 v[136:137], v136
	v_xor_b32_e32 v146, 0xe0, v253
	v_xor_b32_e32 v142, 0xc0, v253
	ds_read_b64_tr_b16 v[142:143], v142
	v_xor_b32_e32 v144, 0xc0, v252
	ds_read_b64_tr_b16 v[144:145], v144
	ds_read_b64_tr_b16 v[146:147], v146
	v_xor_b32_e32 v148, 0xe0, v252
	ds_read_b64_tr_b16 v[148:149], v148
	s_waitcnt lgkmcnt(0)
	s_add_i32 s75, s75, s67
	v_add_u32_e32 v150, s75, v115
	v_mfma_f32_16x16x32_bf16 v[92:95], v[92:95], v[80:83], v[96:99]
	v_add_u32_e32 v151, s75, v113
	v_bfe_u32 v153, v150, 2, 2
	v_bfe_u32 v155, v151, 2, 2
	v_lshlrev_b32_e32 v96, 2, v150
	v_and_b32_e32 v152, 12, v96
	v_mfma_f32_16x16x32_bf16 v[96:99], v[134:137], v[80:83], v[100:103]
	v_lshlrev_b32_e32 v134, 2, v151
	v_lshl_add_u32 v150, v150, 8, v111
	v_and_b32_e32 v154, 12, v134
	v_mfma_f32_16x16x32_bf16 v[100:103], v[142:145], v[80:83], v[122:125]
	v_lshl_add_u32 v151, v151, 8, v111
	v_bitop3_b32 v134, v152, v116, v153 bitop3:0x36
	v_lshl_add_u32 v134, v134, 4, v150
	v_mfma_f32_16x16x32_bf16 v[80:83], v[146:149], v[80:83], v[84:87]
	v_bitop3_b32 v122, v152, v114, v153 bitop3:0x36
	v_lshl_add_u32 v122, v122, 4, v150
	v_bitop3_b32 v124, v154, v114, v155 bitop3:0x36
	v_bitop3_b32 v84, v152, v112, v153 bitop3:0x36
	v_lshl_add_u32 v253, v84, 4, v150
	v_bitop3_b32 v86, v154, v112, v155 bitop3:0x36
	ds_read_b64_tr_b16 v[84:85], v253
	v_lshl_add_u32 v252, v86, 4, v151
	ds_read_b64_tr_b16 v[86:87], v252
	ds_read_b64_tr_b16 v[122:123], v122
	v_lshl_add_u32 v124, v124, 4, v151
	ds_read_b64_tr_b16 v[124:125], v124
	ds_read_b64_tr_b16 v[134:135], v134
	v_xor_b32_e32 v136, 0x40, v252
	ds_read_b64_tr_b16 v[136:137], v136
	v_xor_b32_e32 v142, 0x60, v253
	ds_read_b64_tr_b16 v[142:143], v142
	v_xor_b32_e32 v144, 0x60, v252
	ds_read_b64_tr_b16 v[144:145], v144
	s_waitcnt lgkmcnt(0)
	v_mfma_f32_16x16x32_bf16 v[84:87], v[84:87], v[76:79], v[88:91]
	v_xor_b32_e32 v146, 0x80, v253
	ds_read_b64_tr_b16 v[88:89], v146
	v_mfma_f32_16x16x32_bf16 v[122:125], v[122:125], v[76:79], v[130:133]
	s_nop 0
	v_xor_b32_e32 v90, 0x80, v252
	ds_read_b64_tr_b16 v[90:91], v90
	v_mfma_f32_16x16x32_bf16 v[126:129], v[134:137], v[76:79], v[126:129]
	v_xor_b32_e32 v130, 0xa0, v253
	ds_read_b64_tr_b16 v[130:131], v130
	v_xor_b32_e32 v132, 0xa0, v252
	v_mfma_f32_16x16x32_bf16 v[134:137], v[142:145], v[76:79], v[138:141]
	ds_read_b64_tr_b16 v[132:133], v132
	v_xor_b32_e32 v142, 0xe0, v253
	v_xor_b32_e32 v138, 0xc0, v253
	ds_read_b64_tr_b16 v[138:139], v138
	v_xor_b32_e32 v140, 0xc0, v252
	ds_read_b64_tr_b16 v[140:141], v140
	ds_read_b64_tr_b16 v[142:143], v142
	v_xor_b32_e32 v144, 0xe0, v252
	ds_read_b64_tr_b16 v[144:145], v144
	s_waitcnt lgkmcnt(0)
; #define GAS __attribute__((address_space(1)))
; __device__ __forceinline__ unsigned pk2(float lo, float hi) { return f2bf(lo) | (f2bf(hi) << 16); }
; __device__ __forceinline__ s16x4 tr_read_b64(unsigned addr) { s16x4 r; asm volatile("ds_read_b64_tr_b16 %0, %1" : "=v"(r) : "v"(addr) : "memory"); return r; }
; template <int L>
; __device__ __forceinline__ void layer_body(const Args& args, LAS unsigned char* lds, const int wave, const int G, const int gw, const int NGW, const int lo, const int hi,
;                                            unsigned char* const ws_kernel, const XcdBarrier& bar, int& pid) {
;     ...
;                     for (int s = 0; s < 8; ++s) {
;                         const int ir0 = (r0w - krlo + s) * 40 + coloff;
; #pragma unroll
;                         for (int mh = 0; mh < 2; ++mh) {
;                             s16x4 lo[4], hi[4];
; #pragma unroll
;                             for (int m4 = 0; m4 < 4; ++m4) { const int mt = mh * 4 + m4, r0_ = ir0 + 4 * kg + trq, r1_ = ir0 + 16 + 4 * kg + trq, ch_ = 2 * mt + (trp >> 1);
;                                 lo[m4] = tr_read_b64(IMG + vimg_off(r0_, ch_) + 8u * (trp & 1)); hi[m4] = tr_read_b64(IMG + vimg_off(r1_, ch_) + 8u * (trp & 1)); }
;                             asm volatile("s_waitcnt lgkmcnt(0)" ::: "memory"); __builtin_amdgcn_sched_barrier(0);
; #pragma unroll
;                             for (int m4 = 0; m4 < 4; ++m4) { const int mt = mh * 4 + m4; const bf16x8 va = (bf16x8){lo[m4][0], lo[m4][1], lo[m4][2], lo[m4][3], hi[m4][0], hi[m4][1], hi[m4][2], hi[m4][3]};
;                                 acc[mt] = __builtin_amdgcn_mfma_f32_16x16x32_bf16(va, pbf[s], acc[mt], 0, 0, 0); }
;                         }
;                     }
;                     const float inv = 1.0f / sum;
;                     GAS bf16* op = (GAS bf16*)(obuf + (size_t)(b * SEQ + r * 64 + c) * D + h * HD + 4 * kg);
; #pragma unroll
;                     for (int mt = 0; mt < 8; ++mt) { v2u w; w.x = pk2(acc[mt][0] * inv, acc[mt][1] * inv); w.y = pk2(acc[mt][2] * inv, acc[mt][3] * inv); *(GAS v2u*)(op + 16 * mt) = w; }
	s_add_i32 s76, s76, s67
	v_add_u32_e32 v115, s76, v115
	v_mfma_f32_16x16x32_bf16 v[88:91], v[88:91], v[76:79], v[92:95]
	v_add_u32_e32 v113, s76, v113
	v_bfe_u32 v147, v115, 2, 2
	v_lshl_add_u32 v148, v115, 8, v111
	v_lshlrev_b32_e32 v92, 2, v115
	v_and_b32_e32 v146, 12, v92
	v_lshlrev_b32_e32 v115, 2, v113
	v_mfma_f32_16x16x32_bf16 v[92:95], v[130:133], v[76:79], v[96:99]
	v_lshl_add_u32 v111, v113, 8, v111
	v_mfma_f32_16x16x32_bf16 v[96:99], v[138:141], v[76:79], v[100:103]
	v_and_b32_e32 v138, 12, v115
	v_bfe_u32 v139, v113, 2, 2
	v_mfma_f32_16x16x32_bf16 v[76:79], v[142:145], v[76:79], v[80:83]
	v_bitop3_b32 v100, v146, v114, v147 bitop3:0x36
	v_lshl_add_u32 v100, v100, 4, v148
	v_bitop3_b32 v102, v138, v114, v139 bitop3:0x36
	v_bitop3_b32 v80, v146, v112, v147 bitop3:0x36
	v_lshl_add_u32 v253, v80, 4, v148
	v_bitop3_b32 v82, v138, v112, v139 bitop3:0x36
	ds_read_b64_tr_b16 v[80:81], v253
	v_lshl_add_u32 v252, v82, 4, v111
	ds_read_b64_tr_b16 v[82:83], v252
	ds_read_b64_tr_b16 v[100:101], v100
	v_lshl_add_u32 v102, v102, 4, v111
	ds_read_b64_tr_b16 v[102:103], v102
	v_xor_b32_e32 v112, 0x40, v253
	ds_read_b64_tr_b16 v[112:113], v112
	v_xor_b32_e32 v114, 0x40, v252
	ds_read_b64_tr_b16 v[114:115], v114
	v_xor_b32_e32 v116, 0x60, v253
	ds_read_b64_tr_b16 v[130:131], v116
	v_xor_b32_e32 v116, 0x60, v252
	ds_read_b64_tr_b16 v[132:133], v116
	s_waitcnt lgkmcnt(0)
	v_xor_b32_e32 v116, 0x80, v253
	v_mfma_f32_16x16x32_bf16 v[80:83], v[80:83], v[72:75], v[84:87]
	ds_read_b64_tr_b16 v[84:85], v116
	v_xor_b32_e32 v116, 0xa0, v253
	v_mfma_f32_16x16x32_bf16 v[112:115], v[112:115], v[72:75], v[126:129]
	v_xor_b32_e32 v86, 0x80, v252
	ds_read_b64_tr_b16 v[86:87], v86
	ds_read_b64_tr_b16 v[116:117], v116
	v_xor_b32_e32 v118, 0xa0, v252
	ds_read_b64_tr_b16 v[118:119], v118
	v_xor_b32_e32 v126, 0xc0, v253
	ds_read_b64_tr_b16 v[126:127], v126
	v_xor_b32_e32 v120, 0xc0, v252
	ds_read_b64_tr_b16 v[128:129], v120
	v_xor_b32_e32 v120, 0xe0, v253
	v_mfma_f32_16x16x32_bf16 v[100:103], v[100:103], v[72:75], v[122:125]
	v_mfma_f32_16x16x32_bf16 v[122:125], v[130:133], v[72:75], v[134:137]
	ds_read_b64_tr_b16 v[130:131], v120
	v_xor_b32_e32 v111, 0xe0, v252
	ds_read_b64_tr_b16 v[132:133], v111
	s_waitcnt lgkmcnt(0)
	v_div_scale_f32 v111, s[16:17], v104, v104, 1.0
	v_rcp_f32_e32 v120, v111
	v_mfma_f32_16x16x32_bf16 v[84:87], v[84:87], v[72:75], v[88:91]
	s_lshl_b32 s15, s66, 6
	s_add_i32 s15, s15, s8
	s_lshl_b32 s8, s14, 1
	v_fma_f32 v88, -v111, v120, 1.0
	v_fmac_f32_e32 v120, v88, v120
	v_mfma_f32_16x16x32_bf16 v[88:91], v[116:119], v[72:75], v[92:95]
	v_div_scale_f32 v116, vcc, 1.0, v104, 1.0
	v_mul_f32_e32 v117, v116, v120
	v_mfma_f32_16x16x32_bf16 v[92:95], v[126:129], v[72:75], v[96:99]
	s_add_i32 s53, s53, s51
	s_add_i32 s57, s57, s55
	s_nop 0
	v_fma_f32 v96, -v111, v117, v116
	v_fmac_f32_e32 v117, v96, v120
	v_fma_f32 v96, -v111, v117, v116
	v_mfma_f32_16x16x32_bf16 v[72:75], v[130:133], v[72:75], v[76:79]
	v_mov_b32_e32 v97, v82
	v_mov_b32_e32 v82, v81
	s_nop 0
	v_div_fmas_f32 v76, v96, v120, v117
	v_div_fixup_f32 v76, v76, v104, 1.0
	v_mov_b32_e32 v96, v80
	v_or_b32_e32 v78, s15, v110
	v_pk_mul_f32 v[96:97], v[76:77], v[96:97] op_sel_hi:[0,1]
	v_ashrrev_i32_e32 v79, 31, v78
	v_pk_mul_f32 v[80:81], v[76:77], v[82:83] op_sel_hi:[0,1]
	v_lshlrev_b64 v[78:79], 12, v[78:79]
	v_and_b32_sdwa v83, v81, v108 dst_sel:DWORD dst_unused:UNUSED_PAD src0_sel:WORD_1 src1_sel:DWORD
	v_lshl_add_u64 v[78:79], s[6:7], 0, v[78:79]
	v_and_b32_sdwa v77, v97, v108 dst_sel:DWORD dst_unused:UNUSED_PAD src0_sel:WORD_1 src1_sel:DWORD
	v_add3_u32 v81, v81, v83, s64
	v_lshl_add_u64 v[78:79], v[78:79], 0, s[8:9]
	v_lshlrev_b32_e32 v104, 1, v109
	v_add3_u32 v77, v97, v77, s64
	v_and_b32_e32 v81, 0xffff0000, v81
	v_lshl_add_u64 v[78:79], v[78:79], 0, v[104:105]
	v_or_b32_sdwa v81, v81, v77 dst_sel:DWORD dst_unused:UNUSED_PAD src0_sel:DWORD src1_sel:WORD_1
	v_cvt_pk_bf16_f32 v80, v96, v80
	global_store_dwordx2 v[78:79], v[80:81], off
	v_mov_b32_e32 v80, v100
	v_mov_b32_e32 v81, v102
	v_pk_mul_f32 v[80:81], v[76:77], v[80:81] op_sel_hi:[0,1]
	v_mov_b32_e32 v102, v101
	v_pk_mul_f32 v[82:83], v[76:77], v[102:103] op_sel_hi:[0,1]
	v_and_b32_sdwa v77, v81, v108 dst_sel:DWORD dst_unused:UNUSED_PAD src0_sel:WORD_1 src1_sel:DWORD
	v_add3_u32 v77, v81, v77, s64
	v_and_b32_sdwa v81, v83, v108 dst_sel:DWORD dst_unused:UNUSED_PAD src0_sel:WORD_1 src1_sel:DWORD
	v_add3_u32 v81, v83, v81, s64
	v_and_b32_e32 v81, 0xffff0000, v81
	v_or_b32_sdwa v81, v81, v77 dst_sel:DWORD dst_unused:UNUSED_PAD src0_sel:DWORD src1_sel:WORD_1
	v_cvt_pk_bf16_f32 v80, v80, v82
	global_store_dwordx2 v[78:79], v[80:81], off offset:32
	v_mov_b32_e32 v80, v112
	v_mov_b32_e32 v81, v114
	v_pk_mul_f32 v[80:81], v[76:77], v[80:81] op_sel_hi:[0,1]
	v_mov_b32_e32 v114, v113
	v_pk_mul_f32 v[82:83], v[76:77], v[114:115] op_sel_hi:[0,1]
	v_and_b32_sdwa v77, v81, v108 dst_sel:DWORD dst_unused:UNUSED_PAD src0_sel:WORD_1 src1_sel:DWORD
	v_add3_u32 v77, v81, v77, s64
	v_and_b32_sdwa v81, v83, v108 dst_sel:DWORD dst_unused:UNUSED_PAD src0_sel:WORD_1 src1_sel:DWORD
	v_add3_u32 v81, v83, v81, s64
	v_and_b32_e32 v81, 0xffff0000, v81
	v_or_b32_sdwa v81, v81, v77 dst_sel:DWORD dst_unused:UNUSED_PAD src0_sel:DWORD src1_sel:WORD_1
	v_cvt_pk_bf16_f32 v80, v80, v82
	global_store_dwordx2 v[78:79], v[80:81], off offset:64
	v_mov_b32_e32 v80, v122
	v_mov_b32_e32 v81, v124
	v_pk_mul_f32 v[80:81], v[76:77], v[80:81] op_sel_hi:[0,1]
	v_mov_b32_e32 v124, v123
	v_pk_mul_f32 v[82:83], v[76:77], v[124:125] op_sel_hi:[0,1]
	v_and_b32_sdwa v77, v81, v108 dst_sel:DWORD dst_unused:UNUSED_PAD src0_sel:WORD_1 src1_sel:DWORD
	v_add3_u32 v77, v81, v77, s64
; #define GAS __attribute__((address_space(1)))
; #define LAS __attribute__((address_space(3)))
; __device__ __forceinline__ unsigned pk2(float lo, float hi) { return f2bf(lo) | (f2bf(hi) << 16); }
; #define NA_DECODE(u_, b, h, rbase, hc, krlo, nkr) do { hc = (u_) & 1; const int rg_ = ((u_) >> 1) & 7; h = ((u_) >> 4) & 15; b = (u_) >> 8; rbase = 4 * rg_; \
;                     krlo = min(max(rbase - 4, 0), 24); nkr = min(max(rbase - 1, 0), 24) + 8 - krlo; } while (0)
; template <int L>
; __device__ __forceinline__ void layer_body(const Args& args, LAS unsigned char* lds, const int wave, const int G, const int gw, const int NGW, const int lo, const int hi,
;                                            unsigned char* const ws_kernel, const XcdBarrier& bar, int& pid) {
;     ...
;                 for (; unit < UEND; unit += GH) {
;                     int b, h, rbase, hc, krlo, nkr; NA_DECODE(unit, b, h, rbase, hc, krlo, nkr);
;                     int tl_ = tid; asm volatile("" : "+v"(tl_));
;                     const int lane = tl_ & 63, qi = lane & 15, kg = lane >> 4, sch = tl_ & 15, skey = tl_ >> 4;
; #pragma unroll
;                     for (int i = 0; i < 14; ++i) { const int kid = skey + 32 * i; *(LAS v4u*)(size_t)(IMG + kid * KPITCH + 16 * sch) = rst[i]; }
;                     if (tl_ < 15 * 31) rl[tl_] = rpb[h * 15 * 31 + tl_];
;                     __syncthreads();
;                     NA_LOADROWS(unit, rst, 2 * D);
;     ...
;                     const float inv = 1.0f / sum;
;                     GAS bf16* op = (GAS bf16*)(obuf + (size_t)(b * SEQ + r * 64 + c) * D + h * HD + 4 * kg);
; #pragma unroll
;                     for (int mt = 0; mt < 8; ++mt) { v2u w; w.x = pk2(acc[mt][0] * inv, acc[mt][1] * inv); w.y = pk2(acc[mt][2] * inv, acc[mt][3] * inv); *(GAS v2u*)(op + 16 * mt) = w; }
;                     __syncthreads();
	v_and_b32_sdwa v81, v83, v108 dst_sel:DWORD dst_unused:UNUSED_PAD src0_sel:WORD_1 src1_sel:DWORD
	v_add3_u32 v81, v83, v81, s64
	v_and_b32_e32 v81, 0xffff0000, v81
	v_or_b32_sdwa v81, v81, v77 dst_sel:DWORD dst_unused:UNUSED_PAD src0_sel:DWORD src1_sel:WORD_1
	v_cvt_pk_bf16_f32 v80, v80, v82
	global_store_dwordx2 v[78:79], v[80:81], off offset:96
	v_mov_b32_e32 v80, v84
	v_mov_b32_e32 v81, v86
	v_pk_mul_f32 v[80:81], v[76:77], v[80:81] op_sel_hi:[0,1]
	v_mov_b32_e32 v86, v85
	v_pk_mul_f32 v[82:83], v[76:77], v[86:87] op_sel_hi:[0,1]
	v_and_b32_sdwa v77, v81, v108 dst_sel:DWORD dst_unused:UNUSED_PAD src0_sel:WORD_1 src1_sel:DWORD
	v_add3_u32 v77, v81, v77, s64
	v_and_b32_sdwa v81, v83, v108 dst_sel:DWORD dst_unused:UNUSED_PAD src0_sel:WORD_1 src1_sel:DWORD
	v_add3_u32 v81, v83, v81, s64
	v_and_b32_e32 v81, 0xffff0000, v81
	v_or_b32_sdwa v81, v81, v77 dst_sel:DWORD dst_unused:UNUSED_PAD src0_sel:DWORD src1_sel:WORD_1
	v_cvt_pk_bf16_f32 v80, v80, v82
	global_store_dwordx2 v[78:79], v[80:81], off offset:128
	v_mov_b32_e32 v80, v88
	v_mov_b32_e32 v81, v90
	v_pk_mul_f32 v[80:81], v[76:77], v[80:81] op_sel_hi:[0,1]
	v_mov_b32_e32 v90, v89
	v_pk_mul_f32 v[82:83], v[76:77], v[90:91] op_sel_hi:[0,1]
	v_and_b32_sdwa v77, v81, v108 dst_sel:DWORD dst_unused:UNUSED_PAD src0_sel:WORD_1 src1_sel:DWORD
	v_add3_u32 v77, v81, v77, s64
	v_and_b32_sdwa v81, v83, v108 dst_sel:DWORD dst_unused:UNUSED_PAD src0_sel:WORD_1 src1_sel:DWORD
	v_add3_u32 v81, v83, v81, s64
	v_and_b32_e32 v81, 0xffff0000, v81
	v_or_b32_sdwa v81, v81, v77 dst_sel:DWORD dst_unused:UNUSED_PAD src0_sel:DWORD src1_sel:WORD_1
	v_cvt_pk_bf16_f32 v80, v80, v82
	global_store_dwordx2 v[78:79], v[80:81], off offset:160
	v_mov_b32_e32 v80, v92
	v_mov_b32_e32 v81, v94
	v_pk_mul_f32 v[80:81], v[76:77], v[80:81] op_sel_hi:[0,1]
	v_mov_b32_e32 v94, v93
	v_pk_mul_f32 v[82:83], v[76:77], v[94:95] op_sel_hi:[0,1]
	v_and_b32_sdwa v77, v81, v108 dst_sel:DWORD dst_unused:UNUSED_PAD src0_sel:WORD_1 src1_sel:DWORD
	v_add3_u32 v77, v81, v77, s64
	v_and_b32_sdwa v81, v83, v108 dst_sel:DWORD dst_unused:UNUSED_PAD src0_sel:WORD_1 src1_sel:DWORD
	v_add3_u32 v81, v83, v81, s64
	v_and_b32_e32 v81, 0xffff0000, v81
	v_or_b32_sdwa v81, v81, v77 dst_sel:DWORD dst_unused:UNUSED_PAD src0_sel:DWORD src1_sel:WORD_1
	v_cvt_pk_bf16_f32 v80, v80, v82
	global_store_dwordx2 v[78:79], v[80:81], off offset:192
	v_mov_b32_e32 v81, v74
	v_mov_b32_e32 v74, v73
	v_mov_b32_e32 v80, v72
	v_pk_mul_f32 v[72:73], v[76:77], v[74:75] op_sel_hi:[0,1]
	v_pk_mul_f32 v[80:81], v[76:77], v[80:81] op_sel_hi:[0,1]
	v_cvt_pk_bf16_f32 v73, v81, v73
	v_cvt_pk_bf16_f32 v72, v80, v72
	s_andn2_b64 vcc, exec, s[0:1]
	global_store_dwordx2 v[78:79], v[72:73], off offset:224
	s_barrier
	s_cbranch_vccz .LBB0_3541
.LBB0_3409:
	v_mov_b32_e32 v111, v106
	s_bfe_u32 s73, s40, 0x40004
	v_and_b32_e32 v112, 15, v111
	v_ashrrev_i32_e32 v76, 4, v111
	v_lshlrev_b32_e32 v104, 4, v112
	v_mul_lo_u32 v72, v76, s58
	v_add3_u32 v72, v104, 0, v72
	v_cmp_gt_i32_e32 vcc, s59, v111
	s_waitcnt vmcnt(0)
	ds_write_b128 v72, v[4:7]
	v_add_u32_e32 v4, 0x2200, v72
	ds_write_b128 v72, v[0:3] offset:8704
	v_add_u32_e32 v0, 0x4400, v72
	ds_write_b128 v72, v[12:15] offset:17408
	v_add_u32_e32 v1, 0x6600, v72
	ds_write_b128 v72, v[8:11] offset:26112
	v_add_u32_e32 v2, 0x8800, v72
	ds_write_b128 v72, v[20:23] offset:34816
	v_add_u32_e32 v3, 0xaa00, v72
	ds_write_b128 v72, v[16:19] offset:43520
	v_add_u32_e32 v5, 0xcc00, v72
	ds_write_b128 v72, v[32:35] offset:52224
	ds_write_b128 v72, v[44:47] offset:60928
	ds_write_b128 v4, v[48:51] offset:60928
	ds_write_b128 v0, v[52:55] offset:60928
	ds_write_b128 v1, v[56:59] offset:60928
	ds_write_b128 v2, v[60:63] offset:60928
	ds_write_b128 v3, v[64:67] offset:60928
	ds_write_b128 v5, v[68:71] offset:60928
	s_and_saveexec_b64 s[0:1], vcc
	s_cbranch_execz .LBB0_3411
	s_mul_i32 s8, s73, 0x1d1
	v_add_u32_e32 v0, s8, v111
	v_ashrrev_i32_e32 v1, 31, v0
	v_lshl_add_u64 v[0:1], v[0:1], 2, s[4:5]
	global_load_dword v0, v[0:1], off
	v_lshl_add_u32 v1, v111, 2, 0
	v_add_u32_e32 v1, 0x1dc00, v1
	s_waitcnt vmcnt(0)
	v_mul_f32_e32 v0, s13, v0
	ds_write_b32 v1, v0
.LBB0_3411:
	s_or_b64 exec, exec, s[0:1]
	s_add_i32 s0, s50, s53
	s_and_b32 s66, s0, 28
	v_add_u32_e32 v8, 64, v76
	v_add_u32_e32 v16, 0x80, v76
	v_add_u32_e32 v32, 0xc0, v76
	v_add_u32_e32 v48, 0x100, v76
	v_add_u32_e32 v56, 0x140, v76
	v_add_u32_e32 v66, 0x180, v76
	s_max_u32 s14, s66, 4
	v_med3_u32 v0, s66, 1, 25
	v_mul_hi_i32 v9, v8, s60
	v_mul_hi_i32 v17, v16, s60
	v_mul_hi_i32 v33, v32, s60
	v_mul_hi_i32 v49, v48, s60
	v_mul_hi_i32 v57, v56, s60
	v_mul_hi_i32 v67, v66, s60
	v_add_u32_e32 v2, 32, v76
	v_add_u32_e32 v10, 0x60, v76
	v_add_u32_e32 v18, 0xa0, v76
	v_add_u32_e32 v34, 0xe0, v76
	v_add_u32_e32 v50, 0x120, v76
	v_add_u32_e32 v58, 0x160, v76
	v_add_u32_e32 v68, 0x1a0, v76
	s_and_b32 s15, s40, 1
	s_lshl_b32 s0, s73, 8
	v_subrev_u32_e32 v0, s14, v0
	v_lshrrev_b32_e32 v11, 31, v9
	v_ashrrev_i32_e32 v9, 4, v9
	v_lshrrev_b32_e32 v19, 31, v17
	v_ashrrev_i32_e32 v17, 4, v17
	v_lshrrev_b32_e32 v35, 31, v33
	v_ashrrev_i32_e32 v33, 4, v33
	v_lshrrev_b32_e32 v51, 31, v49
	v_ashrrev_i32_e32 v49, 4, v49
	v_lshrrev_b32_e32 v59, 31, v57
	v_ashrrev_i32_e32 v57, 4, v57
	v_lshrrev_b32_e32 v71, 31, v67
	v_ashrrev_i32_e32 v67, 4, v67
	s_add_u32 s0, s46, s0
	v_add_u32_e32 v70, 10, v0
	v_mul_hi_i32 v0, v76, s60
	v_mul_hi_i32 v3, v2, s60
	v_add_u32_e32 v81, v9, v11
	v_mul_hi_i32 v11, v10, s60
	v_add_u32_e32 v85, v17, v19
	v_mul_hi_i32 v19, v18, s60
	v_add_u32_e32 v89, v33, v35
	v_mul_hi_i32 v35, v34, s60
	v_add_u32_e32 v93, v49, v51
	v_mul_hi_i32 v51, v50, s60
	v_add_u32_e32 v97, v57, v59
	v_mul_hi_i32 v59, v58, s60
; #define LAS __attribute__((address_space(3)))
; #define NA_DECODE(u_, b, h, rbase, hc, krlo, nkr) do { hc = (u_) & 1; const int rg_ = ((u_) >> 1) & 7; h = ((u_) >> 4) & 15; b = (u_) >> 8; rbase = 4 * rg_; \
;                     krlo = min(max(rbase - 4, 0), 24); nkr = min(max(rbase - 1, 0), 24) + 8 - krlo; } while (0)
; template <int L>
; __device__ __forceinline__ void layer_body(const Args& args, LAS unsigned char* lds, const int wave, const int G, const int gw, const int NGW, const int lo, const int hi,
;                                            unsigned char* const ws_kernel, const XcdBarrier& bar, int& pid) {
;     ...
;                 int unit = vcu;
;                 { const int qi = lane & 15, kg = lane >> 4, sch = tid & 15, skey = tid >> 4; if (unit < UEND) { NA_LOADROWS(unit, rst, D); NA_LOADQ(unit); } }
;                 for (; unit < UEND; unit += GH) {
;                     int b, h, rbase, hc, krlo, nkr; NA_DECODE(unit, b, h, rbase, hc, krlo, nkr);
;                     int tl_ = tid; asm volatile("" : "+v"(tl_));
;                     const int lane = tl_ & 63, qi = lane & 15, kg = lane >> 4, sch = tl_ & 15, skey = tl_ >> 4;
; #pragma unroll
;                     for (int i = 0; i < 14; ++i) { const int kid = skey + 32 * i; *(LAS v4u*)(size_t)(IMG + kid * KPITCH + 16 * sch) = rst[i]; }
;                     if (tl_ < 15 * 31) rl[tl_] = rpb[h * 15 * 31 + tl_];
;                     __syncthreads();
;                     NA_LOADROWS(unit, rst, 2 * D);
;                     const int rr = wave >> 1, cb = 2 * hc + (wave & 1), r = rbase + rr, r0w = min(max(r - 4, 0), 24), cs = min(max(16 * cb - 8, 0), 32), coloff = cs - 24 * hc;
;                     const int c = 16 * cb + qi, wsq = min(max(c - 8, 0), 48);
;                     f32x4 sc[16];
; #pragma unroll
;                     for (int t = 0; t < 16; ++t) {
;                         const int irow = (r0w - krlo + (t >> 1)) * 40 + coloff + 16 * (t & 1);
;                         const unsigned ka = IMG + (unsigned)((irow + qi) * KPITCH + 16 * kg);
;                         f32x4 a = (f32x4){0.f, 0.f, 0.f, 0.f};
; #pragma unroll
;                         for (int ks = 0; ks < 4; ++ks) a = __builtin_amdgcn_mfma_f32_16x16x32_bf16(*(const LAS bf16x8*)(size_t)(ka + 64 * ks), qfn[ks], a, 0, 0, 0);
	v_add_u32_e32 v102, v67, v71
	v_mul_hi_i32 v71, v68, s60
	s_addc_u32 s1, s47, 0
	v_lshrrev_b32_e32 v1, 31, v0
	v_ashrrev_i32_e32 v0, 4, v0
	v_lshrrev_b32_e32 v4, 31, v3
	v_ashrrev_i32_e32 v3, 4, v3
	v_lshrrev_b32_e32 v12, 31, v11
	v_ashrrev_i32_e32 v11, 4, v11
	v_lshrrev_b32_e32 v20, 31, v19
	v_ashrrev_i32_e32 v19, 4, v19
	v_lshrrev_b32_e32 v44, 31, v35
	v_ashrrev_i32_e32 v35, 4, v35
	v_lshrrev_b32_e32 v52, 31, v51
	v_ashrrev_i32_e32 v51, 4, v51
	v_lshrrev_b32_e32 v60, 31, v59
	v_ashrrev_i32_e32 v59, 4, v59
	v_lshrrev_b32_e32 v72, 31, v71
	v_ashrrev_i32_e32 v71, 4, v71
	v_lshl_add_u64 v[64:65], s[0:1], 0, v[104:105]
	s_add_i32 s0, s54, s57
	v_add_u32_e32 v77, v0, v1
	v_add_u32_e32 v79, v3, v4
	v_add_u32_e32 v83, v11, v12
	v_add_u32_e32 v87, v19, v20
	v_add_u32_e32 v91, v35, v44
	v_add_u32_e32 v95, v51, v52
	v_add_u32_e32 v100, v59, v60
	v_add_u32_e32 v113, v71, v72
	v_sub_u32_e64 v69, s66, 4 clamp
	s_and_b32 s8, s0, 0xfffff800
	s_mul_i32 s0, s15, 24
	v_min_i32_e32 v0, v77, v70
	v_min_i32_e32 v3, v79, v70
	v_min_i32_e32 v9, v81, v70
	v_min_i32_e32 v11, v83, v70
	v_min_i32_e32 v17, v85, v70
	v_min_i32_e32 v19, v87, v70
	v_min_i32_e32 v33, v89, v70
	v_min_i32_e32 v35, v91, v70
	v_min_i32_e32 v49, v93, v70
	v_min_i32_e32 v51, v95, v70
	v_min_i32_e32 v57, v97, v70
	v_min_i32_e32 v59, v100, v70
	v_min_i32_e32 v67, v102, v70
	v_min_i32_e32 v70, v113, v70
	s_or_b32 s16, s8, s0
	v_add_lshl_u32 v0, v0, v69, 6
	v_mad_i32_i24 v78, v77, s61, v76
	v_add_lshl_u32 v3, v3, v69, 6
	v_mad_i32_i24 v80, v79, s61, v2
	v_add_lshl_u32 v9, v9, v69, 6
	v_mad_i32_i24 v82, v81, s61, v8
	v_add_lshl_u32 v11, v11, v69, 6
	v_mad_i32_i24 v84, v83, s61, v10
	v_add_lshl_u32 v17, v17, v69, 6
	v_mad_i32_i24 v86, v85, s61, v16
	v_add_lshl_u32 v19, v19, v69, 6
	v_mad_i32_i24 v88, v87, s61, v18
	v_add_lshl_u32 v33, v33, v69, 6
	v_mad_i32_i24 v90, v89, s61, v32
	v_add_lshl_u32 v35, v35, v69, 6
	v_mad_i32_i24 v92, v91, s61, v34
	v_add_lshl_u32 v49, v49, v69, 6
	v_mad_i32_i24 v94, v93, s61, v48
	v_add_lshl_u32 v51, v51, v69, 6
	v_mad_i32_i24 v96, v95, s61, v50
	v_add_lshl_u32 v57, v57, v69, 6
	v_mad_i32_i24 v98, v97, s61, v56
	v_add_lshl_u32 v59, v59, v69, 6
	v_mad_i32_i24 v101, v100, s61, v58
	v_add_lshl_u32 v67, v67, v69, 6
	v_mad_i32_i24 v103, v102, s61, v66
	v_add_lshl_u32 v69, v70, v69, 6
	v_mad_i32_i24 v114, v113, s61, v68
	v_add3_u32 v0, v78, s16, v0
	v_add3_u32 v2, v80, s16, v3
	v_add3_u32 v8, v82, s16, v9
	v_add3_u32 v10, v84, s16, v11
	v_add3_u32 v16, v86, s16, v17
	v_add3_u32 v18, v88, s16, v19
	v_add3_u32 v32, v90, s16, v33
	v_add3_u32 v34, v92, s16, v35
	v_add3_u32 v48, v94, s16, v49
	v_add3_u32 v50, v96, s16, v51
	v_add3_u32 v56, v98, s16, v57
	v_add3_u32 v58, v101, s16, v59
	v_add3_u32 v66, v103, s16, v67
	v_add3_u32 v68, v114, s16, v69
	v_mad_i64_i32 v[0:1], s[0:1], v0, s62, v[64:65]
	v_mad_i64_i32 v[2:3], s[0:1], v2, s62, v[64:65]
	v_mad_i64_i32 v[8:9], s[0:1], v8, s62, v[64:65]
	v_mad_i64_i32 v[10:11], s[0:1], v10, s62, v[64:65]
	v_mad_i64_i32 v[16:17], s[0:1], v16, s62, v[64:65]
	v_mad_i64_i32 v[18:19], s[0:1], v18, s62, v[64:65]
	v_mad_i64_i32 v[32:33], s[0:1], v32, s62, v[64:65]
	v_mad_i64_i32 v[44:45], s[0:1], v34, s62, v[64:65]
	v_mad_i64_i32 v[48:49], s[0:1], v48, s62, v[64:65]
	v_mad_i64_i32 v[52:53], s[0:1], v50, s62, v[64:65]
	v_mad_i64_i32 v[56:57], s[0:1], v56, s62, v[64:65]
	v_mad_i64_i32 v[60:61], s[0:1], v58, s62, v[64:65]
	v_mad_i64_i32 v[66:67], s[0:1], v66, s62, v[64:65]
	v_mad_i64_i32 v[68:69], s[0:1], v68, s62, v[64:65]
	s_waitcnt lgkmcnt(0)
	s_barrier
	global_load_dwordx4 v[4:7], v[0:1], off
	s_nop 0
	global_load_dwordx4 v[0:3], v[2:3], off
	s_nop 0
	global_load_dwordx4 v[12:15], v[8:9], off
	s_nop 0
	global_load_dwordx4 v[8:11], v[10:11], off
	s_nop 0
	global_load_dwordx4 v[20:23], v[16:17], off
	s_nop 0
	global_load_dwordx4 v[16:19], v[18:19], off
	s_nop 0
	global_load_dwordx4 v[32:35], v[32:33], off
	s_nop 0
	global_load_dwordx4 v[44:47], v[44:45], off
	s_nop 0
	global_load_dwordx4 v[48:51], v[48:49], off
	s_nop 0
	global_load_dwordx4 v[52:55], v[52:53], off
	s_nop 0
	global_load_dwordx4 v[56:59], v[56:57], off
	s_nop 0
	global_load_dwordx4 v[60:63], v[60:61], off
	s_nop 0
	global_load_dwordx4 v[64:67], v[66:67], off
	s_nop 0
	global_load_dwordx4 v[68:71], v[68:69], off
	s_add_i32 s66, s66, s42
	s_lshl_b32 s1, s15, 5
	s_max_i32 s0, s66, 4
	s_or_b32 s1, s1, s43
	s_add_i32 s0, s0, -4
	s_max_i32 s16, s1, 8
	s_min_u32 s0, s0, 24
	s_add_i32 s16, s16, -8
	s_min_u32 s16, s16, 32
	s_mulk_i32 s15, 0xffe8
	s_sub_i32 s76, s0, s14
	s_add_i32 s67, s16, s15
	s_mul_i32 s76, s76, 40
	v_bfe_u32 v99, v111, 4, 2
	v_add_u32_e32 v123, s67, v112
	s_add_i32 s68, s76, 0xa0
	v_lshl_add_u32 v118, v99, 4, 0
	v_add_u32_e32 v72, s68, v123
	v_mad_i32_i24 v104, v72, s58, v118
	ds_read_b128 v[72:75], v104
	ds_read_b128 v[124:127], v104 offset:64
	ds_read_b128 v[128:131], v104 offset:128
	s_waitcnt lgkmcnt(2)
	v_mfma_f32_16x16x32_bf16 v[72:75], v[72:75], v[24:27], 0
	ds_read_b128 v[136:139], v104 offset:192
	v_or_b32_e32 v110, s1, v112
	v_max_i32_e32 v109, 8, v110
	s_waitcnt lgkmcnt(2)
	v_mfma_f32_16x16x32_bf16 v[72:75], v[124:127], v[28:31], v[72:75]
	v_add_u32_e32 v104, -8, v109
	v_min_u32_e32 v126, 48, v104
	s_sub_i32 s0, s0, s66
	s_waitcnt lgkmcnt(1)
	v_mfma_f32_16x16x32_bf16 v[72:75], v[128:131], v[36:39], v[72:75]
	v_lshlrev_b32_e32 v109, 2, v99
	v_add_u32_e32 v134, s16, v109
	v_add_u32_e32 v128, 16, v126
	s_waitcnt lgkmcnt(0)
; #define LAS __attribute__((address_space(3)))
; template <int L>
; __device__ __forceinline__ void layer_body(const Args& args, LAS unsigned char* lds, const int wave, const int G, const int gw, const int NGW, const int lo, const int hi,
;                                            unsigned char* const ws_kernel, const XcdBarrier& bar, int& pid) {
;     ...
; #pragma unroll
;                     for (int t = 0; t < 16; ++t) {
;                         const int irow = (r0w - krlo + (t >> 1)) * 40 + coloff + 16 * (t & 1);
;                         const unsigned ka = IMG + (unsigned)((irow + qi) * KPITCH + 16 * kg);
;                         f32x4 a = (f32x4){0.f, 0.f, 0.f, 0.f};
; #pragma unroll
;                         for (int ks = 0; ks < 4; ++ks) a = __builtin_amdgcn_mfma_f32_16x16x32_bf16(*(const LAS bf16x8*)(size_t)(ka + 64 * ks), qfn[ks], a, 0, 0, 0);
;                         const int dr = r0w + (t >> 1) - r + 7;
; #pragma unroll
;                         for (int j = 0; j < 4; ++j) { const int kc = cs + 16 * (t & 1) + 4 * kg + j; const bool valid = (kc >= wsq) && (kc < wsq + 16); const int dc = min(max(kc - c + 15, 0), 30);
;                             sc[t][j] = valid ? a[j] * scale_log2 + rl[dr * 31 + dc] * LOG2E : -1e30f; }
;                         __builtin_amdgcn_sched_barrier(0);
;                     }
	v_mfma_f32_16x16x32_bf16 v[72:75], v[136:139], v[40:43], v[72:75]
	s_mulk_i32 s0, 0x7c
	s_add_i32 s77, s0, 0
	v_cmp_ge_u32_e32 vcc, v134, v126
	v_cmp_lt_u32_e64 s[0:1], v134, v128
	v_sub_u32_e32 v115, v134, v110
	s_add_i32 s77, s77, 0x1dc00
	s_and_b64 s[14:15], vcc, s[0:1]
	v_mov_b32_e32 v104, 0xf149f2ca
	v_max_i32_e32 v124, -15, v115
	v_mov_b32_e32 v115, 0xf149f2ca
	v_mov_b32_e32 v202, 0xf149f2ca
	s_nop 1
	v_add_u32_e32 v201, 15, v124
	v_min_u32_e32 v201, 30, v201
	v_lshl_add_u32 v213, v201, 2, s77
	ds_read_b32 v201, v213 offset:868
	s_nop 0
	s_waitcnt lgkmcnt(0)
	v_fma_f32 v200, v72, s12, v201
	v_cndmask_b32_e64 v115, v202, v200, s[14:15]
	v_or_b32_e32 v72, 1, v134
	v_cmp_ge_u32_e32 vcc, v72, v126
	v_cmp_lt_u32_e64 s[0:1], v72, v128
	v_sub_u32_e32 v72, v72, v110
	s_and_b64 s[16:17], vcc, s[0:1]
	v_max_i32_e32 v125, -15, v72
	s_nop 1
	v_add_u32_e32 v215, 15, v125
	v_min_u32_e32 v215, 30, v215
	v_lshl_add_u32 v220, v215, 2, s77
	ds_read_b32 v215, v220 offset:868
	s_nop 0
	s_waitcnt lgkmcnt(0)
	v_fma_f32 v214, v73, s12, v215
	v_cndmask_b32_e64 v104, v202, v214, s[16:17]
	v_or_b32_e32 v72, 2, v134
	v_cmp_ge_u32_e32 vcc, v72, v126
	v_cmp_lt_u32_e64 s[0:1], v72, v128
	v_sub_u32_e32 v72, v72, v110
	s_and_b64 s[20:21], vcc, s[0:1]
	v_mov_b32_e32 v116, 0xf149f2ca
	v_max_i32_e32 v127, -15, v72
	v_mov_b32_e32 v117, 0xf149f2ca
	s_nop 1
	v_add_u32_e32 v217, 15, v127
	v_min_u32_e32 v217, 30, v217
	v_lshl_add_u32 v221, v217, 2, s77
	ds_read_b32 v217, v221 offset:868
	s_nop 0
	s_waitcnt lgkmcnt(0)
	v_fma_f32 v216, v74, s12, v217
	v_cndmask_b32_e64 v117, v202, v216, s[20:21]
	v_or_b32_e32 v72, 3, v134
	v_cmp_ge_u32_e32 vcc, v72, v126
	v_cmp_lt_u32_e64 s[0:1], v72, v128
	v_sub_u32_e32 v72, v72, v110
	s_and_b64 s[22:23], vcc, s[0:1]
	v_max_i32_e32 v129, -15, v72
	s_nop 1
	v_add_u32_e32 v219, 15, v129
	v_min_u32_e32 v219, 30, v219
	v_lshl_add_u32 v222, v219, 2, s77
	ds_read_b32 v219, v222 offset:868
	s_nop 0
	s_waitcnt lgkmcnt(0)
	v_fma_f32 v218, v75, s12, v219
	v_cndmask_b32_e64 v116, v202, v218, s[22:23]
	v_add_u32_e32 v130, 16, v123
	v_add_u32_e32 v72, s68, v130
	v_mad_i32_i24 v119, v72, s58, v118
	ds_read_b128 v[72:75], v119
	ds_read_b128 v[136:139], v119 offset:64
	ds_read_b128 v[140:143], v119 offset:128
	v_add_u32_e32 v120, 16, v134
	v_cmp_lt_u32_e32 vcc, v134, v126
	s_waitcnt lgkmcnt(2)
	v_mfma_f32_16x16x32_bf16 v[72:75], v[72:75], v[24:27], 0
	v_cmp_ge_u32_e64 s[0:1], v120, v126
	v_sub_u32_e32 v120, v120, v110
	s_and_b64 s[24:25], s[0:1], vcc
	s_waitcnt lgkmcnt(1)
	v_mfma_f32_16x16x32_bf16 v[72:75], v[136:139], v[28:31], v[72:75]
	ds_read_b128 v[136:139], v119 offset:192
	v_mov_b32_e32 v119, 0xf149f2ca
	v_max_i32_e32 v131, -15, v120
	s_waitcnt lgkmcnt(1)
	v_mfma_f32_16x16x32_bf16 v[72:75], v[140:143], v[36:39], v[72:75]
	v_mov_b32_e32 v120, 0xf149f2ca
	s_waitcnt lgkmcnt(0)
	v_mfma_f32_16x16x32_bf16 v[72:75], v[136:139], v[40:43], v[72:75]
	s_nop 1
	v_add_u32_e32 v201, 15, v131
	v_min_u32_e32 v201, 30, v201
	v_lshl_add_u32 v223, v201, 2, s77
	ds_read_b32 v201, v223 offset:868
	s_nop 1
	s_nop 0
	s_waitcnt lgkmcnt(0)
	v_fma_f32 v200, v72, s12, v201
	v_cndmask_b32_e64 v120, v202, v200, s[24:25]
	s_nop 4
	v_add_u32_e32 v72, 17, v134
	v_cmp_ge_u32_e32 vcc, v72, v126
	v_cmp_lt_u32_e64 s[0:1], v72, v128
	v_sub_u32_e32 v72, v72, v110
	s_and_b64 s[26:27], vcc, s[0:1]
	v_max_i32_e32 v132, -15, v72
	s_nop 1
	v_add_u32_e32 v215, 15, v132
	v_min_u32_e32 v215, 30, v215
	v_lshl_add_u32 v224, v215, 2, s77
	ds_read_b32 v215, v224 offset:868
	s_nop 0
	s_waitcnt lgkmcnt(0)
	v_fma_f32 v214, v73, s12, v215
	v_cndmask_b32_e64 v119, v202, v214, s[26:27]
	v_add_u32_e32 v72, 18, v134
	v_cmp_ge_u32_e32 vcc, v72, v126
	v_cmp_lt_u32_e64 s[0:1], v72, v128
	v_sub_u32_e32 v72, v72, v110
	s_and_b64 s[36:37], vcc, s[0:1]
	v_mov_b32_e32 v121, 0xf149f2ca
	v_max_i32_e32 v133, -15, v72
	v_mov_b32_e32 v122, 0xf149f2ca
	s_nop 1
	v_add_u32_e32 v217, 15, v133
	v_min_u32_e32 v217, 30, v217
	v_lshl_add_u32 v225, v217, 2, s77
	ds_read_b32 v217, v225 offset:868
	s_nop 0
	s_waitcnt lgkmcnt(0)
	v_fma_f32 v216, v74, s12, v217
	v_cndmask_b32_e64 v122, v202, v216, s[36:37]
	v_add_u32_e32 v72, 19, v134
	v_cmp_ge_u32_e32 vcc, v72, v126
	v_cmp_lt_u32_e64 s[0:1], v72, v128
	v_sub_u32_e32 v72, v72, v110
	s_and_b64 s[0:1], vcc, s[0:1]
	v_max_i32_e32 v134, -15, v72
	s_nop 1
	v_add_u32_e32 v219, 15, v134
	v_min_u32_e32 v219, 30, v219
	v_lshl_add_u32 v226, v219, 2, s77
	ds_read_b32 v219, v226 offset:868
	s_nop 0
	s_waitcnt lgkmcnt(0)
	v_fma_f32 v218, v75, s12, v219
	v_cndmask_b32_e64 v121, v202, v218, s[0:1]
	s_add_i32 s69, s76, 0xc8
	v_add_u32_e32 v72, s69, v123
	v_mad_i32_i24 v126, v72, s58, v118
	ds_read_b128 v[72:75], v126
	ds_read_b128 v[136:139], v126 offset:64
	ds_read_b128 v[140:143], v126 offset:128
	v_mov_b32_e32 v128, 0xf149f2ca
	s_waitcnt lgkmcnt(2)
	v_mfma_f32_16x16x32_bf16 v[72:75], v[72:75], v[24:27], 0
	s_waitcnt lgkmcnt(1)
	v_mfma_f32_16x16x32_bf16 v[72:75], v[136:139], v[28:31], v[72:75]
	ds_read_b128 v[136:139], v126 offset:192
	v_mov_b32_e32 v126, 0xf149f2ca
	s_waitcnt lgkmcnt(1)
	v_mfma_f32_16x16x32_bf16 v[72:75], v[140:143], v[36:39], v[72:75]
	s_waitcnt lgkmcnt(0)
	v_mfma_f32_16x16x32_bf16 v[72:75], v[136:139], v[40:43], v[72:75]
	ds_read_b32 v201, v213 offset:992
	ds_read_b32 v215, v220 offset:992
	ds_read_b32 v217, v221 offset:992
	ds_read_b32 v219, v222 offset:992
	s_nop 4
	s_waitcnt lgkmcnt(0)
	v_fma_f32 v200, v72, s12, v201
	v_fma_f32 v214, v73, s12, v215
	v_fma_f32 v216, v74, s12, v217
	v_fma_f32 v218, v75, s12, v219
	v_cndmask_b32_e64 v128, v202, v200, s[14:15]
	v_cndmask_b32_e64 v126, v202, v214, s[16:17]
	v_cndmask_b32_e64 v136, v202, v216, s[20:21]
	v_cndmask_b32_e64 v135, v202, v218, s[22:23]
	v_add_u32_e32 v72, s69, v130
	v_mad_i32_i24 v137, v72, s58, v118
	ds_read_b128 v[72:75], v137
	ds_read_b128 v[138:141], v137 offset:64
	ds_read_b128 v[142:145], v137 offset:128
	s_waitcnt lgkmcnt(2)
; #define LAS __attribute__((address_space(3)))
; template <int L>
; __device__ __forceinline__ void layer_body(const Args& args, LAS unsigned char* lds, const int wave, const int G, const int gw, const int NGW, const int lo, const int hi,
;                                            unsigned char* const ws_kernel, const XcdBarrier& bar, int& pid) {
;     ...
; #pragma unroll
;                     for (int t = 0; t < 16; ++t) {
;                         const int irow = (r0w - krlo + (t >> 1)) * 40 + coloff + 16 * (t & 1);
;                         const unsigned ka = IMG + (unsigned)((irow + qi) * KPITCH + 16 * kg);
;                         f32x4 a = (f32x4){0.f, 0.f, 0.f, 0.f};
; #pragma unroll
;                         for (int ks = 0; ks < 4; ++ks) a = __builtin_amdgcn_mfma_f32_16x16x32_bf16(*(const LAS bf16x8*)(size_t)(ka + 64 * ks), qfn[ks], a, 0, 0, 0);
;                         const int dr = r0w + (t >> 1) - r + 7;
; #pragma unroll
;                         for (int j = 0; j < 4; ++j) { const int kc = cs + 16 * (t & 1) + 4 * kg + j; const bool valid = (kc >= wsq) && (kc < wsq + 16); const int dc = min(max(kc - c + 15, 0), 30);
;                             sc[t][j] = valid ? a[j] * scale_log2 + rl[dr * 31 + dc] * LOG2E : -1e30f; }
;                         __builtin_amdgcn_sched_barrier(0);
;                     }
	v_mfma_f32_16x16x32_bf16 v[72:75], v[72:75], v[24:27], 0
	s_waitcnt lgkmcnt(1)
	v_mfma_f32_16x16x32_bf16 v[72:75], v[138:141], v[28:31], v[72:75]
	ds_read_b128 v[138:141], v137 offset:192
	v_mov_b32_e32 v137, 0xf149f2ca
	s_waitcnt lgkmcnt(1)
	v_mfma_f32_16x16x32_bf16 v[72:75], v[142:145], v[36:39], v[72:75]
	s_waitcnt lgkmcnt(0)
	v_mfma_f32_16x16x32_bf16 v[72:75], v[138:141], v[40:43], v[72:75]
	v_mov_b32_e32 v138, 0xf149f2ca
	ds_read_b32 v201, v223 offset:992
	ds_read_b32 v215, v224 offset:992
	ds_read_b32 v217, v225 offset:992
	ds_read_b32 v219, v226 offset:992
	s_nop 4
	s_waitcnt lgkmcnt(0)
	v_fma_f32 v200, v72, s12, v201
	v_fma_f32 v214, v73, s12, v215
	v_fma_f32 v216, v74, s12, v217
	v_fma_f32 v218, v75, s12, v219
	v_cndmask_b32_e64 v138, v202, v200, s[24:25]
	v_cndmask_b32_e64 v137, v202, v214, s[26:27]
	v_cndmask_b32_e64 v140, v202, v216, s[36:37]
	v_cndmask_b32_e64 v139, v202, v218, s[0:1]
	s_add_i32 s70, s76, 0xf0
	v_add_u32_e32 v72, s70, v123
	v_mad_i32_i24 v141, v72, s58, v118
	ds_read_b128 v[72:75], v141
	ds_read_b128 v[142:145], v141 offset:64
	ds_read_b128 v[146:149], v141 offset:128
	s_waitcnt lgkmcnt(2)
	v_mfma_f32_16x16x32_bf16 v[72:75], v[72:75], v[24:27], 0
	s_waitcnt lgkmcnt(1)
	v_mfma_f32_16x16x32_bf16 v[72:75], v[142:145], v[28:31], v[72:75]
	ds_read_b128 v[142:145], v141 offset:192
	v_mov_b32_e32 v141, 0xf149f2ca
	s_waitcnt lgkmcnt(1)
	v_mfma_f32_16x16x32_bf16 v[72:75], v[146:149], v[36:39], v[72:75]
	s_waitcnt lgkmcnt(0)
	v_mfma_f32_16x16x32_bf16 v[72:75], v[142:145], v[40:43], v[72:75]
	v_mov_b32_e32 v142, 0xf149f2ca
	ds_read_b32 v201, v213 offset:1116
	ds_read_b32 v215, v220 offset:1116
	ds_read_b32 v217, v221 offset:1116
	ds_read_b32 v219, v222 offset:1116
	s_nop 4
	s_waitcnt lgkmcnt(0)
	v_fma_f32 v200, v72, s12, v201
	v_fma_f32 v214, v73, s12, v215
	v_fma_f32 v216, v74, s12, v217
	v_fma_f32 v218, v75, s12, v219
	v_cndmask_b32_e64 v142, v202, v200, s[14:15]
	v_cndmask_b32_e64 v141, v202, v214, s[16:17]
	v_cndmask_b32_e64 v144, v202, v216, s[20:21]
	v_cndmask_b32_e64 v143, v202, v218, s[22:23]
	v_add_u32_e32 v72, s70, v130
	v_mad_i32_i24 v145, v72, s58, v118
	ds_read_b128 v[72:75], v145
	ds_read_b128 v[146:149], v145 offset:64
	ds_read_b128 v[150:153], v145 offset:128
	s_waitcnt lgkmcnt(2)
	v_mfma_f32_16x16x32_bf16 v[72:75], v[72:75], v[24:27], 0
	s_waitcnt lgkmcnt(1)
	v_mfma_f32_16x16x32_bf16 v[72:75], v[146:149], v[28:31], v[72:75]
	ds_read_b128 v[146:149], v145 offset:192
	v_mov_b32_e32 v145, 0xf149f2ca
	s_waitcnt lgkmcnt(1)
	v_mfma_f32_16x16x32_bf16 v[72:75], v[150:153], v[36:39], v[72:75]
	s_waitcnt lgkmcnt(0)
	v_mfma_f32_16x16x32_bf16 v[72:75], v[146:149], v[40:43], v[72:75]
	v_mov_b32_e32 v146, 0xf149f2ca
	ds_read_b32 v201, v223 offset:1116
	ds_read_b32 v215, v224 offset:1116
	ds_read_b32 v217, v225 offset:1116
	ds_read_b32 v219, v226 offset:1116
	s_nop 4
	s_waitcnt lgkmcnt(0)
	v_fma_f32 v200, v72, s12, v201
	v_fma_f32 v214, v73, s12, v215
	v_fma_f32 v216, v74, s12, v217
	v_fma_f32 v218, v75, s12, v219
	v_cndmask_b32_e64 v146, v202, v200, s[24:25]
	v_cndmask_b32_e64 v145, v202, v214, s[26:27]
	v_cndmask_b32_e64 v148, v202, v216, s[36:37]
	v_cndmask_b32_e64 v147, v202, v218, s[0:1]
	s_add_i32 s71, s76, 0x118
	v_add_u32_e32 v72, s71, v123
	v_mad_i32_i24 v149, v72, s58, v118
	ds_read_b128 v[72:75], v149
	ds_read_b128 v[150:153], v149 offset:64
	ds_read_b128 v[154:157], v149 offset:128
	s_waitcnt lgkmcnt(2)
	v_mfma_f32_16x16x32_bf16 v[72:75], v[72:75], v[24:27], 0
	s_waitcnt lgkmcnt(1)
	v_mfma_f32_16x16x32_bf16 v[72:75], v[150:153], v[28:31], v[72:75]
	ds_read_b128 v[150:153], v149 offset:192
	v_mov_b32_e32 v149, 0xf149f2ca
	s_waitcnt lgkmcnt(1)
	v_mfma_f32_16x16x32_bf16 v[72:75], v[154:157], v[36:39], v[72:75]
	s_waitcnt lgkmcnt(0)
	v_mfma_f32_16x16x32_bf16 v[72:75], v[150:153], v[40:43], v[72:75]
	v_mov_b32_e32 v150, 0xf149f2ca
	ds_read_b32 v201, v213 offset:1240
	ds_read_b32 v215, v220 offset:1240
	ds_read_b32 v217, v221 offset:1240
	ds_read_b32 v219, v222 offset:1240
	s_nop 4
	s_waitcnt lgkmcnt(0)
	v_fma_f32 v200, v72, s12, v201
	v_fma_f32 v214, v73, s12, v215
	v_fma_f32 v216, v74, s12, v217
	v_fma_f32 v218, v75, s12, v219
	v_cndmask_b32_e64 v150, v202, v200, s[14:15]
	v_cndmask_b32_e64 v149, v202, v214, s[16:17]
	v_cndmask_b32_e64 v152, v202, v216, s[20:21]
	v_cndmask_b32_e64 v151, v202, v218, s[22:23]
	v_add_u32_e32 v72, s71, v130
	v_mad_i32_i24 v153, v72, s58, v118
	ds_read_b128 v[72:75], v153
	ds_read_b128 v[154:157], v153 offset:64
	ds_read_b128 v[158:161], v153 offset:128
	s_waitcnt lgkmcnt(2)
	v_mfma_f32_16x16x32_bf16 v[72:75], v[72:75], v[24:27], 0
	s_waitcnt lgkmcnt(1)
	v_mfma_f32_16x16x32_bf16 v[72:75], v[154:157], v[28:31], v[72:75]
	ds_read_b128 v[154:157], v153 offset:192
	v_mov_b32_e32 v153, 0xf149f2ca
	s_waitcnt lgkmcnt(1)
	v_mfma_f32_16x16x32_bf16 v[72:75], v[158:161], v[36:39], v[72:75]
	s_waitcnt lgkmcnt(0)
	v_mfma_f32_16x16x32_bf16 v[72:75], v[154:157], v[40:43], v[72:75]
	v_mov_b32_e32 v154, 0xf149f2ca
	ds_read_b32 v201, v223 offset:1240
	ds_read_b32 v215, v224 offset:1240
	ds_read_b32 v217, v225 offset:1240
	ds_read_b32 v219, v226 offset:1240
	s_nop 4
	s_waitcnt lgkmcnt(0)
	v_fma_f32 v200, v72, s12, v201
	v_fma_f32 v214, v73, s12, v215
	v_fma_f32 v216, v74, s12, v217
	v_fma_f32 v218, v75, s12, v219
	v_cndmask_b32_e64 v154, v202, v200, s[24:25]
	v_cndmask_b32_e64 v153, v202, v214, s[26:27]
	v_cndmask_b32_e64 v156, v202, v216, s[36:37]
	v_cndmask_b32_e64 v155, v202, v218, s[0:1]
	s_add_i32 s72, s76, 0x140
	v_add_u32_e32 v72, s72, v123
	v_mad_i32_i24 v157, v72, s58, v118
	ds_read_b128 v[72:75], v157
	ds_read_b128 v[158:161], v157 offset:64
	ds_read_b128 v[162:165], v157 offset:128
	s_waitcnt lgkmcnt(2)
; #define LAS __attribute__((address_space(3)))
; template <int L>
; __device__ __forceinline__ void layer_body(const Args& args, LAS unsigned char* lds, const int wave, const int G, const int gw, const int NGW, const int lo, const int hi,
;                                            unsigned char* const ws_kernel, const XcdBarrier& bar, int& pid) {
;     ...
; #pragma unroll
;                     for (int t = 0; t < 16; ++t) {
;                         const int irow = (r0w - krlo + (t >> 1)) * 40 + coloff + 16 * (t & 1);
;                         const unsigned ka = IMG + (unsigned)((irow + qi) * KPITCH + 16 * kg);
;                         f32x4 a = (f32x4){0.f, 0.f, 0.f, 0.f};
; #pragma unroll
;                         for (int ks = 0; ks < 4; ++ks) a = __builtin_amdgcn_mfma_f32_16x16x32_bf16(*(const LAS bf16x8*)(size_t)(ka + 64 * ks), qfn[ks], a, 0, 0, 0);
;                         const int dr = r0w + (t >> 1) - r + 7;
; #pragma unroll
;                         for (int j = 0; j < 4; ++j) { const int kc = cs + 16 * (t & 1) + 4 * kg + j; const bool valid = (kc >= wsq) && (kc < wsq + 16); const int dc = min(max(kc - c + 15, 0), 30);
;                             sc[t][j] = valid ? a[j] * scale_log2 + rl[dr * 31 + dc] * LOG2E : -1e30f; }
;                         __builtin_amdgcn_sched_barrier(0);
;                     }
	v_mfma_f32_16x16x32_bf16 v[72:75], v[72:75], v[24:27], 0
	s_waitcnt lgkmcnt(1)
	v_mfma_f32_16x16x32_bf16 v[72:75], v[158:161], v[28:31], v[72:75]
	ds_read_b128 v[158:161], v157 offset:192
	v_mov_b32_e32 v157, 0xf149f2ca
	s_waitcnt lgkmcnt(1)
	v_mfma_f32_16x16x32_bf16 v[72:75], v[162:165], v[36:39], v[72:75]
	s_waitcnt lgkmcnt(0)
	v_mfma_f32_16x16x32_bf16 v[72:75], v[158:161], v[40:43], v[72:75]
	v_mov_b32_e32 v158, 0xf149f2ca
	ds_read_b32 v201, v213 offset:1364
	ds_read_b32 v215, v220 offset:1364
	ds_read_b32 v217, v221 offset:1364
	ds_read_b32 v219, v222 offset:1364
	s_nop 4
	s_waitcnt lgkmcnt(0)
	v_fma_f32 v200, v72, s12, v201
	v_fma_f32 v214, v73, s12, v215
	v_fma_f32 v216, v74, s12, v217
	v_fma_f32 v218, v75, s12, v219
	v_cndmask_b32_e64 v158, v202, v200, s[14:15]
	v_cndmask_b32_e64 v157, v202, v214, s[16:17]
	v_cndmask_b32_e64 v160, v202, v216, s[20:21]
	v_cndmask_b32_e64 v159, v202, v218, s[22:23]
	v_add_u32_e32 v72, s72, v130
	v_mad_i32_i24 v161, v72, s58, v118
	ds_read_b128 v[72:75], v161
	ds_read_b128 v[162:165], v161 offset:64
	ds_read_b128 v[166:169], v161 offset:128
	s_waitcnt lgkmcnt(2)
	v_mfma_f32_16x16x32_bf16 v[72:75], v[72:75], v[24:27], 0
	s_waitcnt lgkmcnt(1)
	v_mfma_f32_16x16x32_bf16 v[72:75], v[162:165], v[28:31], v[72:75]
	ds_read_b128 v[162:165], v161 offset:192
	v_mov_b32_e32 v161, 0xf149f2ca
	s_waitcnt lgkmcnt(1)
	v_mfma_f32_16x16x32_bf16 v[72:75], v[166:169], v[36:39], v[72:75]
	s_waitcnt lgkmcnt(0)
	v_mfma_f32_16x16x32_bf16 v[72:75], v[162:165], v[40:43], v[72:75]
	v_mov_b32_e32 v162, 0xf149f2ca
	ds_read_b32 v201, v223 offset:1364
	ds_read_b32 v215, v224 offset:1364
	ds_read_b32 v217, v225 offset:1364
	ds_read_b32 v219, v226 offset:1364
	s_nop 4
	s_waitcnt lgkmcnt(0)
	v_fma_f32 v200, v72, s12, v201
	v_fma_f32 v214, v73, s12, v215
	v_fma_f32 v216, v74, s12, v217
	v_fma_f32 v218, v75, s12, v219
	v_cndmask_b32_e64 v162, v202, v200, s[24:25]
	v_cndmask_b32_e64 v161, v202, v214, s[26:27]
	v_cndmask_b32_e64 v164, v202, v216, s[36:37]
	v_cndmask_b32_e64 v163, v202, v218, s[0:1]
	s_add_i32 s74, s76, 0x168
	v_add_u32_e32 v72, s74, v123
	v_mad_i32_i24 v165, v72, s58, v118
	ds_read_b128 v[72:75], v165
	ds_read_b128 v[166:169], v165 offset:64
	ds_read_b128 v[170:173], v165 offset:128
	s_waitcnt lgkmcnt(2)
	v_mfma_f32_16x16x32_bf16 v[72:75], v[72:75], v[24:27], 0
	s_waitcnt lgkmcnt(1)
	v_mfma_f32_16x16x32_bf16 v[72:75], v[166:169], v[28:31], v[72:75]
	ds_read_b128 v[166:169], v165 offset:192
	v_mov_b32_e32 v165, 0xf149f2ca
	s_waitcnt lgkmcnt(1)
	v_mfma_f32_16x16x32_bf16 v[72:75], v[170:173], v[36:39], v[72:75]
	s_waitcnt lgkmcnt(0)
	v_mfma_f32_16x16x32_bf16 v[72:75], v[166:169], v[40:43], v[72:75]
	v_mov_b32_e32 v166, 0xf149f2ca
	ds_read_b32 v201, v213 offset:1488
	ds_read_b32 v215, v220 offset:1488
	ds_read_b32 v217, v221 offset:1488
	ds_read_b32 v219, v222 offset:1488
	s_nop 4
	s_waitcnt lgkmcnt(0)
	v_fma_f32 v200, v72, s12, v201
	v_fma_f32 v214, v73, s12, v215
	v_fma_f32 v216, v74, s12, v217
	v_fma_f32 v218, v75, s12, v219
	v_cndmask_b32_e64 v166, v202, v200, s[14:15]
	v_cndmask_b32_e64 v165, v202, v214, s[16:17]
	v_cndmask_b32_e64 v168, v202, v216, s[20:21]
	v_cndmask_b32_e64 v167, v202, v218, s[22:23]
	v_add_u32_e32 v72, s74, v130
	v_mad_i32_i24 v169, v72, s58, v118
	ds_read_b128 v[72:75], v169
	ds_read_b128 v[170:173], v169 offset:64
	ds_read_b128 v[174:177], v169 offset:128
	s_waitcnt lgkmcnt(2)
	v_mfma_f32_16x16x32_bf16 v[72:75], v[72:75], v[24:27], 0
	s_waitcnt lgkmcnt(1)
	v_mfma_f32_16x16x32_bf16 v[72:75], v[170:173], v[28:31], v[72:75]
	ds_read_b128 v[170:173], v169 offset:192
	v_mov_b32_e32 v169, 0xf149f2ca
	s_waitcnt lgkmcnt(1)
	v_mfma_f32_16x16x32_bf16 v[72:75], v[174:177], v[36:39], v[72:75]
	s_waitcnt lgkmcnt(0)
	v_mfma_f32_16x16x32_bf16 v[72:75], v[170:173], v[40:43], v[72:75]
	v_mov_b32_e32 v170, 0xf149f2ca
	ds_read_b32 v201, v223 offset:1488
	ds_read_b32 v215, v224 offset:1488
	ds_read_b32 v217, v225 offset:1488
	ds_read_b32 v219, v226 offset:1488
	s_nop 4
	s_waitcnt lgkmcnt(0)
	v_fma_f32 v200, v72, s12, v201
	v_fma_f32 v214, v73, s12, v215
	v_fma_f32 v216, v74, s12, v217
	v_fma_f32 v218, v75, s12, v219
	v_cndmask_b32_e64 v170, v202, v200, s[24:25]
	v_cndmask_b32_e64 v169, v202, v214, s[26:27]
	v_cndmask_b32_e64 v172, v202, v216, s[36:37]
	v_cndmask_b32_e64 v171, v202, v218, s[0:1]
	s_add_i32 s75, s76, 0x190
	v_add_u32_e32 v72, s75, v123
	v_mad_i32_i24 v173, v72, s58, v118
	ds_read_b128 v[72:75], v173
	ds_read_b128 v[174:177], v173 offset:64
	ds_read_b128 v[178:181], v173 offset:128
	s_waitcnt lgkmcnt(2)
	v_mfma_f32_16x16x32_bf16 v[72:75], v[72:75], v[24:27], 0
	s_waitcnt lgkmcnt(1)
	v_mfma_f32_16x16x32_bf16 v[72:75], v[174:177], v[28:31], v[72:75]
	ds_read_b128 v[174:177], v173 offset:192
	v_mov_b32_e32 v173, 0xf149f2ca
	s_waitcnt lgkmcnt(1)
	v_mfma_f32_16x16x32_bf16 v[72:75], v[178:181], v[36:39], v[72:75]
	s_waitcnt lgkmcnt(0)
	v_mfma_f32_16x16x32_bf16 v[72:75], v[174:177], v[40:43], v[72:75]
	v_mov_b32_e32 v174, 0xf149f2ca
	ds_read_b32 v201, v213 offset:1612
	ds_read_b32 v215, v220 offset:1612
	ds_read_b32 v217, v221 offset:1612
	ds_read_b32 v219, v222 offset:1612
	s_nop 4
	s_waitcnt lgkmcnt(0)
	v_fma_f32 v200, v72, s12, v201
	v_fma_f32 v214, v73, s12, v215
	v_fma_f32 v216, v74, s12, v217
	v_fma_f32 v218, v75, s12, v219
	v_cndmask_b32_e64 v174, v202, v200, s[14:15]
	v_cndmask_b32_e64 v173, v202, v214, s[16:17]
	v_cndmask_b32_e64 v176, v202, v216, s[20:21]
	v_cndmask_b32_e64 v175, v202, v218, s[22:23]
	v_add_u32_e32 v72, s75, v130
	v_mad_i32_i24 v177, v72, s58, v118
	ds_read_b128 v[72:75], v177
	ds_read_b128 v[178:181], v177 offset:64
	ds_read_b128 v[182:185], v177 offset:128
	s_waitcnt lgkmcnt(2)
; #define LAS __attribute__((address_space(3)))
; template <int L>
; __device__ __forceinline__ void layer_body(const Args& args, LAS unsigned char* lds, const int wave, const int G, const int gw, const int NGW, const int lo, const int hi,
;                                            unsigned char* const ws_kernel, const XcdBarrier& bar, int& pid) {
;     ...
; #pragma unroll
;                     for (int t = 0; t < 16; ++t) {
;                         const int irow = (r0w - krlo + (t >> 1)) * 40 + coloff + 16 * (t & 1);
;                         const unsigned ka = IMG + (unsigned)((irow + qi) * KPITCH + 16 * kg);
;                         f32x4 a = (f32x4){0.f, 0.f, 0.f, 0.f};
; #pragma unroll
;                         for (int ks = 0; ks < 4; ++ks) a = __builtin_amdgcn_mfma_f32_16x16x32_bf16(*(const LAS bf16x8*)(size_t)(ka + 64 * ks), qfn[ks], a, 0, 0, 0);
;                         const int dr = r0w + (t >> 1) - r + 7;
; #pragma unroll
;                         for (int j = 0; j < 4; ++j) { const int kc = cs + 16 * (t & 1) + 4 * kg + j; const bool valid = (kc >= wsq) && (kc < wsq + 16); const int dc = min(max(kc - c + 15, 0), 30);
;                             sc[t][j] = valid ? a[j] * scale_log2 + rl[dr * 31 + dc] * LOG2E : -1e30f; }
;                         __builtin_amdgcn_sched_barrier(0);
;                     }
;                     float mx = -1e30f;
; #pragma unroll
;                     for (int t = 0; t < 16; ++t)
; #pragma unroll
;                         for (int j = 0; j < 4; ++j) mx = fmaxf(mx, sc[t][j]);
;                     mx = fmaxf(mx, __shfl_xor(mx, 16)); mx = fmaxf(mx, __shfl_xor(mx, 32));
	v_mfma_f32_16x16x32_bf16 v[72:75], v[72:75], v[24:27], 0
	s_waitcnt lgkmcnt(1)
	v_mfma_f32_16x16x32_bf16 v[72:75], v[178:181], v[28:31], v[72:75]
	ds_read_b128 v[178:181], v177 offset:192
	s_waitcnt lgkmcnt(1)
	v_mfma_f32_16x16x32_bf16 v[72:75], v[182:185], v[36:39], v[72:75]
	v_mov_b32_e32 v183, 0xf149f2ca
	s_waitcnt lgkmcnt(0)
	v_mfma_f32_16x16x32_bf16 v[72:75], v[178:181], v[40:43], v[72:75]
	v_mov_b32_e32 v181, 0xf149f2ca
	ds_read_b32 v201, v223 offset:1612
	ds_read_b32 v215, v224 offset:1612
	ds_read_b32 v217, v225 offset:1612
	ds_read_b32 v219, v226 offset:1612
	s_nop 4
	s_waitcnt lgkmcnt(0)
	v_fma_f32 v200, v72, s12, v201
	v_fma_f32 v214, v73, s12, v215
	v_fma_f32 v216, v74, s12, v217
	v_fma_f32 v218, v75, s12, v219
	v_cndmask_b32_e64 v183, v202, v200, s[24:25]
	v_cndmask_b32_e64 v181, v202, v214, s[26:27]
	v_cndmask_b32_e64 v204, v202, v216, s[36:37]
	v_cndmask_b32_e64 v203, v202, v218, s[0:1]
	s_addk_i32 s76, 0x1b8
	v_add_u32_e32 v72, s76, v123
	v_mad_i32_i24 v123, v72, s58, v118
	ds_read_b128 v[72:75], v123
	ds_read_b128 v[184:187], v123 offset:64
	ds_read_b128 v[188:191], v123 offset:128
	v_mov_b32_e32 v205, 0xf149f2ca
	v_mov_b32_e32 v206, 0xf149f2ca
	s_waitcnt lgkmcnt(2)
	v_mfma_f32_16x16x32_bf16 v[72:75], v[72:75], v[24:27], 0
	s_waitcnt lgkmcnt(1)
	v_mfma_f32_16x16x32_bf16 v[72:75], v[184:187], v[28:31], v[72:75]
	ds_read_b128 v[184:187], v123 offset:192
	s_waitcnt lgkmcnt(1)
	v_mfma_f32_16x16x32_bf16 v[72:75], v[188:191], v[36:39], v[72:75]
	s_waitcnt lgkmcnt(0)
	v_mfma_f32_16x16x32_bf16 v[72:75], v[184:187], v[40:43], v[72:75]
	ds_read_b32 v201, v213 offset:1736
	ds_read_b32 v215, v220 offset:1736
	ds_read_b32 v217, v221 offset:1736
	ds_read_b32 v219, v222 offset:1736
	s_nop 4
	s_waitcnt lgkmcnt(0)
	v_fma_f32 v200, v72, s12, v201
	v_fma_f32 v214, v73, s12, v215
	v_fma_f32 v216, v74, s12, v217
	v_fma_f32 v218, v75, s12, v219
	v_cndmask_b32_e64 v206, v202, v200, s[14:15]
	v_cndmask_b32_e64 v205, v202, v214, s[16:17]
	v_cndmask_b32_e64 v208, v202, v216, s[20:21]
	v_cndmask_b32_e64 v207, v202, v218, s[22:23]
	v_add_u32_e32 v72, s76, v130
	v_mad_i32_i24 v118, v72, s58, v118
	ds_read_b128 v[72:75], v118
	ds_read_b128 v[184:187], v118 offset:64
	ds_read_b128 v[188:191], v118 offset:128
	v_mov_b32_e32 v209, 0xf149f2ca
	v_mov_b32_e32 v210, 0xf149f2ca
	s_waitcnt lgkmcnt(2)
	v_mfma_f32_16x16x32_bf16 v[72:75], v[72:75], v[24:27], 0
	s_waitcnt lgkmcnt(1)
	v_mfma_f32_16x16x32_bf16 v[72:75], v[184:187], v[28:31], v[72:75]
	ds_read_b128 v[184:187], v118 offset:192
	s_waitcnt lgkmcnt(1)
	v_mfma_f32_16x16x32_bf16 v[72:75], v[188:191], v[36:39], v[72:75]
	s_waitcnt lgkmcnt(0)
	v_mfma_f32_16x16x32_bf16 v[72:75], v[184:187], v[40:43], v[72:75]
	ds_read_b32 v201, v223 offset:1736
	ds_read_b32 v215, v224 offset:1736
	ds_read_b32 v217, v225 offset:1736
	ds_read_b32 v219, v226 offset:1736
	s_nop 4
	s_waitcnt lgkmcnt(0)
	v_fma_f32 v200, v72, s12, v201
	v_fma_f32 v214, v73, s12, v215
	v_fma_f32 v216, v74, s12, v217
	v_fma_f32 v218, v75, s12, v219
	v_cndmask_b32_e64 v210, v202, v200, s[24:25]
	v_cndmask_b32_e64 v209, v202, v214, s[26:27]
	v_cndmask_b32_e64 v212, v202, v216, s[36:37]
	v_cndmask_b32_e64 v211, v202, v218, s[0:1]
	s_lshl_b32 s14, s73, 7
	v_max3_f32 v72, v115, s63, v104
	v_max3_f32 v72, v72, v117, v116
	v_max3_f32 v72, v72, v120, v119
	v_max3_f32 v72, v72, v122, v121
	v_max3_f32 v72, v72, v128, v126
	v_max3_f32 v72, v72, v136, v135
	v_max3_f32 v72, v72, v138, v137
	v_max3_f32 v72, v72, v140, v139
	v_max3_f32 v72, v72, v142, v141
	v_max3_f32 v72, v72, v144, v143
	v_max3_f32 v72, v72, v146, v145
	v_max3_f32 v72, v72, v148, v147
	v_max3_f32 v72, v72, v150, v149
	v_max3_f32 v72, v72, v152, v151
	v_max3_f32 v72, v72, v154, v153
	v_max3_f32 v72, v72, v156, v155
	v_max3_f32 v72, v72, v158, v157
	v_max3_f32 v72, v72, v160, v159
	v_max3_f32 v72, v72, v162, v161
	v_max3_f32 v72, v72, v164, v163
	v_max3_f32 v72, v72, v166, v165
	v_max3_f32 v72, v72, v168, v167
	v_max3_f32 v72, v72, v170, v169
	v_max3_f32 v72, v72, v172, v171
	v_max3_f32 v72, v72, v174, v173
	v_max3_f32 v72, v72, v176, v175
	v_max3_f32 v72, v72, v183, v181
	v_max3_f32 v72, v72, v204, v203
	v_and_b32_e32 v74, 64, v107
	v_max3_f32 v72, v72, v206, v205
	v_xor_b32_e32 v73, 16, v107
	v_add_u32_e32 v74, 64, v74
	v_max3_f32 v72, v72, v208, v207
	v_cmp_lt_i32_e32 vcc, v73, v74
	v_max3_f32 v72, v72, v210, v209
	v_max3_f32 v72, v72, v212, v211
	v_cndmask_b32_e32 v73, v107, v73, vcc
	v_lshlrev_b32_e32 v213, 2, v73
	ds_bpermute_b32 v73, v213, v72
	s_waitcnt lgkmcnt(0)
	s_barrier
; template <int L>
; __device__ __forceinline__ void layer_body(const Args& args, LAS unsigned char* lds, const int wave, const int G, const int gw, const int NGW, const int lo, const int hi,
;                                            unsigned char* const ws_kernel, const XcdBarrier& bar, int& pid) {
;     ...
;                     mx = fmaxf(mx, __shfl_xor(mx, 16)); mx = fmaxf(mx, __shfl_xor(mx, 32));
;                     float sum = 0.f;
; #pragma unroll
;                     for (int t = 0; t < 16; ++t)
; #pragma unroll
;                         for (int j = 0; j < 4; ++j) { sc[t][j] = __builtin_amdgcn_exp2f(sc[t][j] - mx); sum += sc[t][j]; }
;                     sum += __shfl_xor(sum, 16); sum += __shfl_xor(sum, 32);
	s_add_i32 s40, s40, s86
	v_max_f32_e32 v73, v73, v73
	v_max_f32_e32 v72, v72, v73
	v_xor_b32_e32 v73, 32, v107
	v_cmp_lt_i32_e32 vcc, v73, v74
	s_cmp_ge_i32 s40, s41
	s_cselect_b64 s[0:1], -1, 0
	v_cndmask_b32_e32 v73, v107, v73, vcc
	v_lshlrev_b32_e32 v214, 2, v73
	ds_bpermute_b32 v73, v214, v72
	s_and_b64 vcc, exec, s[0:1]
	s_waitcnt lgkmcnt(0)
	v_max_f32_e32 v73, v73, v73
	v_max_f32_e32 v215, v72, v73
	v_sub_f32_e32 v72, v115, v215
	v_exp_f32_e32 v190, v72
	v_sub_f32_e32 v72, v104, v215
	v_exp_f32_e32 v198, v72
	v_sub_f32_e32 v72, v117, v215
	v_exp_f32_e32 v194, v72
	v_sub_f32_e32 v72, v116, v215
	v_exp_f32_e32 v200, v72
	v_sub_f32_e32 v72, v120, v215
	v_sub_f32_e32 v104, v209, v215
	v_exp_f32_e32 v196, v72
	v_sub_f32_e32 v72, v119, v215
	v_exp_f32_e32 v119, v104
	v_sub_f32_e32 v104, v212, v215
	v_exp_f32_e32 v201, v72
	v_sub_f32_e32 v72, v122, v215
	v_exp_f32_e32 v116, v104
	v_sub_f32_e32 v104, v211, v215
	v_exp_f32_e32 v199, v72
	v_sub_f32_e32 v72, v121, v215
	v_exp_f32_e32 v121, v104
	v_add_f32_e32 v104, 0, v190
	v_add_f32_e32 v104, v198, v104
	v_add_f32_e32 v104, v194, v104
	v_exp_f32_e32 v202, v72
	v_sub_f32_e32 v72, v128, v215
	v_add_f32_e32 v104, v200, v104
	v_exp_f32_e32 v180, v72
	v_sub_f32_e32 v72, v126, v215
	v_add_f32_e32 v104, v196, v104
	v_exp_f32_e32 v191, v72
	v_sub_f32_e32 v72, v136, v215
	v_add_f32_e32 v104, v201, v104
	v_exp_f32_e32 v186, v72
	v_sub_f32_e32 v72, v135, v215
	v_add_f32_e32 v104, v199, v104
	v_exp_f32_e32 v193, v72
	v_sub_f32_e32 v72, v138, v215
	v_add_f32_e32 v104, v202, v104
	v_exp_f32_e32 v188, v72
	v_sub_f32_e32 v72, v137, v215
	v_add_f32_e32 v104, v180, v104
	v_exp_f32_e32 v195, v72
	v_sub_f32_e32 v72, v140, v215
	v_add_f32_e32 v104, v191, v104
	v_exp_f32_e32 v192, v72
	v_sub_f32_e32 v72, v139, v215
	v_add_f32_e32 v104, v186, v104
	v_exp_f32_e32 v197, v72
	v_sub_f32_e32 v72, v142, v215
	v_add_f32_e32 v104, v193, v104
	v_exp_f32_e32 v177, v72
	v_sub_f32_e32 v72, v141, v215
	v_add_f32_e32 v104, v188, v104
	v_exp_f32_e32 v182, v72
	v_sub_f32_e32 v72, v144, v215
	v_add_f32_e32 v104, v195, v104
	v_exp_f32_e32 v178, v72
	v_sub_f32_e32 v72, v143, v215
	v_add_f32_e32 v104, v192, v104
	v_exp_f32_e32 v185, v72
	v_sub_f32_e32 v72, v146, v215
	v_add_f32_e32 v104, v197, v104
	v_exp_f32_e32 v179, v72
	v_sub_f32_e32 v72, v145, v215
	v_add_f32_e32 v104, v177, v104
	v_exp_f32_e32 v187, v72
	v_sub_f32_e32 v72, v148, v215
	v_add_f32_e32 v104, v182, v104
	v_exp_f32_e32 v184, v72
	v_sub_f32_e32 v72, v147, v215
	v_add_f32_e32 v104, v178, v104
	v_exp_f32_e32 v189, v72
	v_sub_f32_e32 v72, v150, v215
	v_add_f32_e32 v104, v185, v104
	v_exp_f32_e32 v138, v72
	v_sub_f32_e32 v72, v149, v215
	v_add_f32_e32 v104, v179, v104
	v_exp_f32_e32 v146, v72
	v_sub_f32_e32 v72, v152, v215
	v_add_f32_e32 v104, v187, v104
	v_exp_f32_e32 v142, v72
	v_sub_f32_e32 v72, v151, v215
	v_add_f32_e32 v104, v184, v104
	v_exp_f32_e32 v148, v72
	v_sub_f32_e32 v72, v154, v215
	v_add_f32_e32 v104, v189, v104
	v_exp_f32_e32 v144, v72
	v_sub_f32_e32 v72, v153, v215
	v_add_f32_e32 v104, v138, v104
	v_exp_f32_e32 v150, v72
	v_sub_f32_e32 v72, v156, v215
	v_add_f32_e32 v104, v146, v104
	v_exp_f32_e32 v147, v72
	v_sub_f32_e32 v72, v155, v215
	v_add_f32_e32 v104, v142, v104
	v_exp_f32_e32 v152, v72
	v_sub_f32_e32 v72, v158, v215
	v_add_f32_e32 v104, v148, v104
	v_exp_f32_e32 v130, v72
	v_sub_f32_e32 v72, v157, v215
	v_add_f32_e32 v104, v144, v104
	v_exp_f32_e32 v139, v72
	v_sub_f32_e32 v72, v160, v215
	v_add_f32_e32 v104, v150, v104
	v_exp_f32_e32 v134, v72
	v_sub_f32_e32 v72, v159, v215
	v_add_f32_e32 v104, v147, v104
	v_exp_f32_e32 v141, v72
	v_sub_f32_e32 v72, v162, v215
	v_add_f32_e32 v104, v152, v104
	v_exp_f32_e32 v136, v72
	v_sub_f32_e32 v72, v161, v215
	v_add_f32_e32 v104, v130, v104
	v_exp_f32_e32 v143, v72
	v_sub_f32_e32 v72, v164, v215
	v_add_f32_e32 v104, v139, v104
	v_exp_f32_e32 v140, v72
	v_sub_f32_e32 v72, v163, v215
	v_add_f32_e32 v104, v134, v104
	v_exp_f32_e32 v145, v72
	v_sub_f32_e32 v72, v166, v215
	v_add_f32_e32 v104, v141, v104
	v_exp_f32_e32 v122, v72
	v_sub_f32_e32 v72, v165, v215
	v_add_f32_e32 v104, v136, v104
	v_exp_f32_e32 v131, v72
	v_sub_f32_e32 v72, v168, v215
	v_add_f32_e32 v104, v143, v104
	v_exp_f32_e32 v126, v72
	v_sub_f32_e32 v72, v167, v215
	v_add_f32_e32 v104, v140, v104
	v_exp_f32_e32 v133, v72
	v_sub_f32_e32 v72, v170, v215
	v_add_f32_e32 v104, v145, v104
	v_exp_f32_e32 v128, v72
	v_sub_f32_e32 v72, v169, v215
	v_add_f32_e32 v104, v122, v104
	v_exp_f32_e32 v135, v72
	v_sub_f32_e32 v72, v172, v215
	v_add_f32_e32 v104, v131, v104
	v_exp_f32_e32 v132, v72
	v_sub_f32_e32 v72, v171, v215
	v_add_f32_e32 v104, v126, v104
	v_exp_f32_e32 v137, v72
	v_sub_f32_e32 v72, v174, v215
	v_add_f32_e32 v104, v133, v104
	v_exp_f32_e32 v75, v72
	v_sub_f32_e32 v72, v173, v215
	v_add_f32_e32 v104, v128, v104
	v_exp_f32_e32 v123, v72
	v_sub_f32_e32 v72, v176, v215
	v_add_f32_e32 v104, v135, v104
	v_exp_f32_e32 v118, v72
	v_sub_f32_e32 v72, v175, v215
	v_add_f32_e32 v104, v132, v104
	v_exp_f32_e32 v125, v72
	v_sub_f32_e32 v72, v183, v215
	v_add_f32_e32 v104, v137, v104
	v_exp_f32_e32 v120, v72
	v_sub_f32_e32 v72, v181, v215
	v_add_f32_e32 v104, v75, v104
	v_exp_f32_e32 v127, v72
	v_sub_f32_e32 v72, v204, v215
	v_add_f32_e32 v104, v123, v104
	v_exp_f32_e32 v124, v72
	v_sub_f32_e32 v72, v203, v215
	v_add_f32_e32 v104, v118, v104
	v_exp_f32_e32 v129, v72
	v_sub_f32_e32 v72, v206, v215
	v_add_f32_e32 v104, v125, v104
	v_exp_f32_e32 v72, v72
	v_sub_f32_e32 v73, v205, v215
	v_add_f32_e32 v104, v120, v104
	v_exp_f32_e32 v115, v73
	v_sub_f32_e32 v73, v208, v215
	v_add_f32_e32 v104, v127, v104
	v_exp_f32_e32 v73, v73
	v_sub_f32_e32 v74, v207, v215
	v_add_f32_e32 v104, v124, v104
	v_exp_f32_e32 v117, v74
	v_sub_f32_e32 v74, v210, v215
	v_add_f32_e32 v104, v129, v104
	v_exp_f32_e32 v74, v74
	v_add_f32_e32 v104, v72, v104
	v_add_f32_e32 v104, v115, v104
	v_add_f32_e32 v104, v73, v104
	v_add_f32_e32 v104, v117, v104
	v_add_f32_e32 v104, v74, v104
	v_add_f32_e32 v104, v119, v104
	v_add_f32_e32 v104, v116, v104
	v_add_f32_e32 v104, v121, v104
	ds_bpermute_b32 v149, v213, v104
	v_lshlrev_b32_e32 v153, 2, v76
	v_and_b32_e32 v153, 12, v153
	s_waitcnt lgkmcnt(0)
; #define LAS __attribute__((address_space(3)))
; template <int L>
; __device__ __forceinline__ void layer_body(const Args& args, LAS unsigned char* lds, const int wave, const int G, const int gw, const int NGW, const int lo, const int hi,
;                                            unsigned char* const ws_kernel, const XcdBarrier& bar, int& pid) {
;     ...
;                     __syncthreads();
; #pragma unroll
;                     for (int i = 0; i < 14; ++i) { const int kid = skey + 32 * i; *(LAS v4u*)(size_t)(IMG + vimg_off(kid, sch)) = rst[i]; }
;                     __syncthreads();
;                     if (unit + GH < UEND) { NA_LOADROWS(unit + GH, rst, D); NA_LOADQ(unit + GH); }
	v_add_f32_e32 v149, v104, v149
	v_lshlrev_b32_e32 v104, 8, v76
	v_bfe_u32 v76, v76, 2, 2
	v_bitop3_b32 v76, v153, v112, v76 bitop3:0x36
	v_lshlrev_b32_e32 v76, 4, v76
	v_add3_u32 v76, v104, 0, v76
	ds_bpermute_b32 v151, v214, v149
	v_add_u32_e32 v104, 0x10000, v76
	s_waitcnt vmcnt(13)
	ds_write_b128 v76, v[4:7]
	s_waitcnt vmcnt(12)
	ds_write_b128 v76, v[0:3] offset:8192
	s_waitcnt vmcnt(11)
	ds_write_b128 v76, v[12:15] offset:16384
	s_waitcnt vmcnt(10)
	ds_write_b128 v76, v[8:11] offset:24576
	s_waitcnt vmcnt(9)
	ds_write_b128 v76, v[20:23] offset:32768
	s_waitcnt vmcnt(8)
	ds_write_b128 v76, v[16:19] offset:40960
	s_waitcnt vmcnt(7)
	ds_write_b128 v76, v[32:35] offset:49152
	s_waitcnt vmcnt(6)
	ds_write_b128 v76, v[44:47] offset:57344
	s_waitcnt vmcnt(5)
	ds_write_b128 v104, v[48:51]
	v_add_u32_e32 v104, 0x12000, v76
	s_waitcnt vmcnt(4)
	ds_write_b128 v104, v[52:55]
	v_add_u32_e32 v104, 0x14000, v76
	s_waitcnt vmcnt(3)
	ds_write_b128 v104, v[56:59]
	v_add_u32_e32 v104, 0x16000, v76
	s_waitcnt vmcnt(2)
	ds_write_b128 v104, v[60:63]
	v_add_u32_e32 v104, 0x18000, v76
	v_add_u32_e32 v76, 0x1a000, v76
	s_waitcnt vmcnt(1)
	ds_write_b128 v104, v[64:67]
	s_waitcnt vmcnt(0)
	ds_write_b128 v76, v[68:71]
	s_waitcnt lgkmcnt(0)
	s_barrier
	s_cbranch_vccnz .LBB0_3408
	s_add_i32 s16, s52, s53
	s_and_b32 s20, s16, 28
	s_add_i32 s22, s56, s57
	v_sub_u32_e64 v1, s20, 1 clamp
	s_and_b32 s16, s22, 0x780
	v_lshlrev_b32_e32 v0, 3, v112
	s_and_b32 s15, s40, 1
	s_max_u32 s21, s20, 4
	v_min_u32_e32 v1, 24, v1
	s_lshl_b32 s23, s16, 1
	s_add_u32 s16, s48, s23
	v_lshlrev_b32_e32 v104, 1, v0
	v_subrev_u32_e32 v0, s21, v1
	s_addc_u32 s17, s49, 0
	v_add_u32_e32 v31, 11, v0
	v_sub_u32_e64 v30, s20, 4 clamp
	v_lshl_add_u64 v[24:25], s[16:17], 0, v[104:105]
	s_and_b32 s21, s22, 0xfffff800
	s_mul_i32 s16, s15, 24
	v_min_i32_e32 v0, v77, v31
	v_min_i32_e32 v2, v79, v31
	v_min_i32_e32 v8, v81, v31
	v_min_i32_e32 v10, v83, v31
	v_min_i32_e32 v16, v85, v31
	v_min_i32_e32 v18, v87, v31
	v_min_i32_e32 v26, v89, v31
	v_min_i32_e32 v28, v91, v31
	s_or_b32 s22, s21, s16
	v_add_lshl_u32 v0, v0, v30, 6
	v_add_lshl_u32 v2, v2, v30, 6
	v_add_lshl_u32 v8, v8, v30, 6
	v_add_lshl_u32 v10, v10, v30, 6
	v_add_lshl_u32 v16, v16, v30, 6
	v_add_lshl_u32 v18, v18, v30, 6
	v_add_lshl_u32 v26, v26, v30, 6
	v_add_lshl_u32 v28, v28, v30, 6
	v_add3_u32 v0, v78, s22, v0
	v_add3_u32 v2, v80, s22, v2
	v_add3_u32 v8, v82, s22, v8
	v_add3_u32 v10, v84, s22, v10
	v_add3_u32 v16, v86, s22, v16
	v_add3_u32 v18, v88, s22, v18
	v_add3_u32 v26, v90, s22, v26
	v_add3_u32 v28, v92, s22, v28
	v_mad_i64_i32 v[0:1], s[16:17], v0, s62, v[24:25]
	v_mad_i64_i32 v[2:3], s[16:17], v2, s62, v[24:25]
	v_mad_i64_i32 v[8:9], s[16:17], v8, s62, v[24:25]
	v_mad_i64_i32 v[10:11], s[16:17], v10, s62, v[24:25]
	v_mad_i64_i32 v[16:17], s[16:17], v16, s62, v[24:25]
	v_mad_i64_i32 v[18:19], s[16:17], v18, s62, v[24:25]
	v_mad_i64_i32 v[26:27], s[16:17], v26, s62, v[24:25]
	v_mad_i64_i32 v[28:29], s[16:17], v28, s62, v[24:25]
	global_load_dwordx4 v[4:7], v[0:1], off
	s_nop 0
	global_load_dwordx4 v[0:3], v[2:3], off
	s_nop 0
	global_load_dwordx4 v[12:15], v[8:9], off
	s_nop 0
	global_load_dwordx4 v[8:11], v[10:11], off
	s_nop 0
	global_load_dwordx4 v[20:23], v[16:17], off
	s_nop 0
	global_load_dwordx4 v[16:19], v[18:19], off
	s_nop 0
	global_load_dwordx4 v[32:35], v[26:27], off
	global_load_dwordx4 v[44:47], v[28:29], off
	v_min_i32_e32 v26, v93, v31
	v_min_i32_e32 v28, v95, v31
	v_add_lshl_u32 v26, v26, v30, 6
	v_add_lshl_u32 v28, v28, v30, 6
	v_add3_u32 v26, v94, s22, v26
	v_add3_u32 v28, v96, s22, v28
	v_mad_i64_i32 v[26:27], s[16:17], v26, s62, v[24:25]
	v_mad_i64_i32 v[28:29], s[16:17], v28, s62, v[24:25]
	global_load_dwordx4 v[48:51], v[26:27], off
	global_load_dwordx4 v[52:55], v[28:29], off
	v_min_i32_e32 v26, v97, v31
	v_min_i32_e32 v28, v100, v31
	v_add_lshl_u32 v26, v26, v30, 6
	v_add_lshl_u32 v28, v28, v30, 6
	v_add3_u32 v26, v98, s22, v26
	v_add3_u32 v28, v101, s22, v28
	v_mad_i64_i32 v[26:27], s[16:17], v26, s62, v[24:25]
	v_mad_i64_i32 v[28:29], s[16:17], v28, s62, v[24:25]
	global_load_dwordx4 v[56:59], v[26:27], off
	global_load_dwordx4 v[60:63], v[28:29], off
	v_min_i32_e32 v26, v102, v31
	v_min_i32_e32 v28, v113, v31
	v_add_lshl_u32 v26, v26, v30, 6
	v_add_lshl_u32 v28, v28, v30, 6
	v_add3_u32 v26, v103, s22, v26
	v_add3_u32 v28, v114, s22, v28
	v_mad_i64_i32 v[26:27], s[16:17], v26, s62, v[24:25]
	v_mad_i64_i32 v[24:25], s[16:17], v28, s62, v[24:25]
	s_add_u32 s16, s44, s23
	s_addc_u32 s17, s45, 0
	s_add_i32 s20, s20, s42
	s_lshl_b32 s20, s20, 6
	s_add_i32 s20, s20, s21
	s_lshl_b32 s15, s15, 5
	s_or_b32 s15, s20, s15
	s_or_b32 s15, s15, s43
	global_load_dwordx4 v[64:67], v[26:27], off
	global_load_dwordx4 v[68:71], v[24:25], off
	v_or_b32_e32 v26, s15, v112
	v_mov_b64_e32 v[24:25], s[16:17]
	v_mad_i64_i32 v[24:25], s[16:17], v26, s62, v[24:25]
	v_lshlrev_b32_e32 v104, 4, v99
	v_lshl_add_u64 v[40:41], v[24:25], 0, v[104:105]
	global_load_dwordx4 v[24:27], v[40:41], off
	global_load_dwordx4 v[28:31], v[40:41], off offset:64
	global_load_dwordx4 v[36:39], v[40:41], off offset:128
	s_nop 0
	global_load_dwordx4 v[40:43], v[40:41], off offset:192
	s_branch .LBB0_3408
